# phase-1 sample-row up-GEMM: 40 loads in flight, lane-split row scale; + Resid epilogue prefetch of xb tile loads
# speedup vs baseline: 1.0327x; 1.0110x over previous
; #define SK_LOAD(AR, BR, k0) do { _Pragma("unroll") for (int i = 0; i < UNR; ++i) { AR[i] = *(const bf16x8*)(ap + (k0) + 32 * i); \
;             _Pragma("unroll") for (int g = 0; g < NG; ++g) BR[g][i] = *(const bf16x8*)(bp[g] + (k0) + 32 * i); } } while (0)
; #define SK_MMA(AR, BR) do { _Pragma("unroll") for (int i = 0; i < UNR; ++i) _Pragma("unroll") for (int g = 0; g < NG; ++g) acc[g] = __builtin_amdgcn_mfma_f32_16x16x32_bf16(BR[g][i], AR[i], acc[g], 0, 0, 0); } while (0)
;     ...
;         const bf16_t* ap = A + (size_t)srow * K + kh * KL + 8 * kq;
;         const bf16_t* bp[NG]; f32x4 acc[NG];
; #pragma unroll
;         for (int g = 0; g < NG; ++g) { bp[g] = Bt + (size_t)(Epi::brow(cg, g) + rr) * K + kh * KL + 8 * kq; acc[g] = (f32x4){0.f, 0.f, 0.f, 0.f}; }
;         bf16x8 a0[UNR], a1[UNR], b0[NG][UNR], b1[NG][UNR];
;     ...
;         SK_LOAD(a0, b0, 0);
;         for (int k = 0; k < KL; k += 64 * UNR) {
;             SK_LOAD(a1, b1, k + 32 * UNR);
;             SK_MMA(a0, b0);
;             if (k + 64 * UNR < KL) SK_LOAD(a0, b0, k + 64 * UNR);
;             SK_MMA(a1, b1);
; __device__ __forceinline__ float rs_sample(const float* ssps, int srow) { return rs_from(ssps + (size_t)srow * 64, 16, 1.0f / 1024.0f); }
.Lsku_beg:
	v_lshl_add_u64 v[72:73], v[62:63], 0, v[10:11]
	v_lshl_add_u64 v[70:71], v[62:63], 0, v[12:13]
	v_lshlrev_b64 v[24:25], 11, v[14:15]
	v_lshl_add_u64 v[74:75], v[62:63], 0, v[24:25]
	s_ashr_i32 s1, s0, 31
	s_add_i32 s3, s3, s6
	s_add_i32 s2, s2, s94
	s_cmpk_lt_i32 s2, 0xb0
	v_lshlrev_b64 v[34:35], 8, v[32:33]
	v_lshl_add_u64 v[34:35], s[92:93], 0, v[34:35]
	v_lshl_add_u64 v[34:35], v[60:61], 3, v[34:35]
	global_load_dwordx4 v[16:19], v[34:35], off
	global_load_dwordx4 v[20:23], v[34:35], off offset:16
	global_load_dwordx4 v[24:27], v[34:35], off offset:32
	global_load_dwordx4 v[28:31], v[34:35], off offset:48
	global_load_dwordx4 v[84:87], v[76:77], off
	global_load_dwordx4 v[88:91], v[68:69], off
	global_load_dwordx4 v[92:95], v[72:73], off
	global_load_dwordx4 v[96:99], v[70:71], off
	global_load_dwordx4 v[100:103], v[74:75], off
	global_load_dwordx4 v[104:107], v[76:77], off offset:64
	global_load_dwordx4 v[108:111], v[68:69], off offset:64
	global_load_dwordx4 v[112:115], v[72:73], off offset:64
	global_load_dwordx4 v[116:119], v[70:71], off offset:64
	global_load_dwordx4 v[120:123], v[74:75], off offset:64
	global_load_dwordx4 v[124:127], v[76:77], off offset:128
	global_load_dwordx4 v[128:131], v[68:69], off offset:128
	global_load_dwordx4 v[132:135], v[72:73], off offset:128
	global_load_dwordx4 v[136:139], v[70:71], off offset:128
	global_load_dwordx4 v[140:143], v[74:75], off offset:128
	global_load_dwordx4 v[144:147], v[76:77], off offset:192
	global_load_dwordx4 v[148:151], v[68:69], off offset:192
	global_load_dwordx4 v[152:155], v[72:73], off offset:192
	global_load_dwordx4 v[156:159], v[70:71], off offset:192
	global_load_dwordx4 v[160:163], v[74:75], off offset:192
	global_load_dwordx4 v[164:167], v[76:77], off offset:256
	global_load_dwordx4 v[168:171], v[68:69], off offset:256
	global_load_dwordx4 v[172:175], v[72:73], off offset:256
	global_load_dwordx4 v[176:179], v[70:71], off offset:256
	global_load_dwordx4 v[180:183], v[74:75], off offset:256
	global_load_dwordx4 v[184:187], v[76:77], off offset:320
	global_load_dwordx4 v[188:191], v[68:69], off offset:320
	global_load_dwordx4 v[192:195], v[72:73], off offset:320
	global_load_dwordx4 v[196:199], v[70:71], off offset:320
	global_load_dwordx4 v[200:203], v[74:75], off offset:320
	global_load_dwordx4 v[204:207], v[76:77], off offset:384
	global_load_dwordx4 v[208:211], v[68:69], off offset:384
	global_load_dwordx4 v[212:215], v[72:73], off offset:384
	global_load_dwordx4 v[216:219], v[70:71], off offset:384
	global_load_dwordx4 v[220:223], v[74:75], off offset:384
	global_load_dwordx4 v[224:227], v[76:77], off offset:448
	global_load_dwordx4 v[228:231], v[68:69], off offset:448
	global_load_dwordx4 v[232:235], v[72:73], off offset:448
	global_load_dwordx4 v[236:239], v[70:71], off offset:448
	global_load_dwordx4 v[240:243], v[74:75], off offset:448
	v_add_u32_e32 v36, 0x8000, v32
	v_mad_i64_i32 v[38:39], s[10:11], v36, s8, v[66:67]
	v_lshl_add_u64 v[38:39], s[0:1], 1, v[38:39]
	v_lshl_add_u64 v[38:39], v[38:39], 0, v[60:61]
	v_mbcnt_lo_u32_b32 v40, -1, 0
	v_mbcnt_hi_u32_b32 v40, -1, v40
	v_xor_b32_e32 v41, 16, v40
	v_xor_b32_e32 v42, 32, v40
	v_lshlrev_b32_e32 v41, 2, v41
	v_lshlrev_b32_e32 v42, 2, v42
	s_waitcnt vmcnt(35)
	v_mfma_f32_16x16x32_bf16 v[0:3], v[88:91], v[84:87], 0
	v_mfma_f32_16x16x32_bf16 v[4:7], v[92:95], v[84:87], 0
	v_mfma_f32_16x16x32_bf16 v[8:11], v[96:99], v[84:87], 0
	v_mfma_f32_16x16x32_bf16 v[12:15], v[100:103], v[84:87], 0
	global_load_dwordx4 v[84:87], v[76:77], off offset:512
	global_load_dwordx4 v[88:91], v[68:69], off offset:512
	global_load_dwordx4 v[92:95], v[72:73], off offset:512
	global_load_dwordx4 v[96:99], v[70:71], off offset:512
	global_load_dwordx4 v[100:103], v[74:75], off offset:512
	s_waitcnt vmcnt(35)
	v_mfma_f32_16x16x32_bf16 v[0:3], v[108:111], v[104:107], v[0:3]
	v_mfma_f32_16x16x32_bf16 v[4:7], v[112:115], v[104:107], v[4:7]
	v_mfma_f32_16x16x32_bf16 v[8:11], v[116:119], v[104:107], v[8:11]
	v_mfma_f32_16x16x32_bf16 v[12:15], v[120:123], v[104:107], v[12:15]
	global_load_dwordx4 v[104:107], v[76:77], off offset:576
	global_load_dwordx4 v[108:111], v[68:69], off offset:576
	global_load_dwordx4 v[112:115], v[72:73], off offset:576
	global_load_dwordx4 v[116:119], v[70:71], off offset:576
	global_load_dwordx4 v[120:123], v[74:75], off offset:576
	s_waitcnt vmcnt(35)
	v_mfma_f32_16x16x32_bf16 v[0:3], v[128:131], v[124:127], v[0:3]
	v_mfma_f32_16x16x32_bf16 v[4:7], v[132:135], v[124:127], v[4:7]
	v_mfma_f32_16x16x32_bf16 v[8:11], v[136:139], v[124:127], v[8:11]
	v_mfma_f32_16x16x32_bf16 v[12:15], v[140:143], v[124:127], v[12:15]
	global_load_dwordx4 v[124:127], v[76:77], off offset:640
	global_load_dwordx4 v[128:131], v[68:69], off offset:640
	global_load_dwordx4 v[132:135], v[72:73], off offset:640
	global_load_dwordx4 v[136:139], v[70:71], off offset:640
	global_load_dwordx4 v[140:143], v[74:75], off offset:640
	s_waitcnt vmcnt(35)
	v_mfma_f32_16x16x32_bf16 v[0:3], v[148:151], v[144:147], v[0:3]
	v_mfma_f32_16x16x32_bf16 v[4:7], v[152:155], v[144:147], v[4:7]
	v_mfma_f32_16x16x32_bf16 v[8:11], v[156:159], v[144:147], v[8:11]
	v_mfma_f32_16x16x32_bf16 v[12:15], v[160:163], v[144:147], v[12:15]
	global_load_dwordx4 v[144:147], v[76:77], off offset:704
	global_load_dwordx4 v[148:151], v[68:69], off offset:704
	global_load_dwordx4 v[152:155], v[72:73], off offset:704
	global_load_dwordx4 v[156:159], v[70:71], off offset:704
	global_load_dwordx4 v[160:163], v[74:75], off offset:704
	s_waitcnt vmcnt(35)
; #define SK_LOAD(AR, BR, k0) do { _Pragma("unroll") for (int i = 0; i < UNR; ++i) { AR[i] = *(const bf16x8*)(ap + (k0) + 32 * i); \
;             _Pragma("unroll") for (int g = 0; g < NG; ++g) BR[g][i] = *(const bf16x8*)(bp[g] + (k0) + 32 * i); } } while (0)
; #define SK_MMA(AR, BR) do { _Pragma("unroll") for (int i = 0; i < UNR; ++i) _Pragma("unroll") for (int g = 0; g < NG; ++g) acc[g] = __builtin_amdgcn_mfma_f32_16x16x32_bf16(BR[g][i], AR[i], acc[g], 0, 0, 0); } while (0)
;     ...
;         for (int k = 0; k < KL; k += 64 * UNR) {
;             SK_LOAD(a1, b1, k + 32 * UNR);
;             SK_MMA(a0, b0);
;             if (k + 64 * UNR < KL) SK_LOAD(a0, b0, k + 64 * UNR);
;             SK_MMA(a1, b1);
	v_mfma_f32_16x16x32_bf16 v[0:3], v[168:171], v[164:167], v[0:3]
	v_mfma_f32_16x16x32_bf16 v[4:7], v[172:175], v[164:167], v[4:7]
	v_mfma_f32_16x16x32_bf16 v[8:11], v[176:179], v[164:167], v[8:11]
	v_mfma_f32_16x16x32_bf16 v[12:15], v[180:183], v[164:167], v[12:15]
	global_load_dwordx4 v[164:167], v[76:77], off offset:768
	global_load_dwordx4 v[168:171], v[68:69], off offset:768
	global_load_dwordx4 v[172:175], v[72:73], off offset:768
	global_load_dwordx4 v[176:179], v[70:71], off offset:768
	global_load_dwordx4 v[180:183], v[74:75], off offset:768
	s_waitcnt vmcnt(35)
	v_mfma_f32_16x16x32_bf16 v[0:3], v[188:191], v[184:187], v[0:3]
	v_mfma_f32_16x16x32_bf16 v[4:7], v[192:195], v[184:187], v[4:7]
	v_mfma_f32_16x16x32_bf16 v[8:11], v[196:199], v[184:187], v[8:11]
	v_mfma_f32_16x16x32_bf16 v[12:15], v[200:203], v[184:187], v[12:15]
	global_load_dwordx4 v[184:187], v[76:77], off offset:832
	global_load_dwordx4 v[188:191], v[68:69], off offset:832
	global_load_dwordx4 v[192:195], v[72:73], off offset:832
	global_load_dwordx4 v[196:199], v[70:71], off offset:832
	global_load_dwordx4 v[200:203], v[74:75], off offset:832
	s_waitcnt vmcnt(35)
	v_mfma_f32_16x16x32_bf16 v[0:3], v[208:211], v[204:207], v[0:3]
	v_mfma_f32_16x16x32_bf16 v[4:7], v[212:215], v[204:207], v[4:7]
	v_mfma_f32_16x16x32_bf16 v[8:11], v[216:219], v[204:207], v[8:11]
	v_mfma_f32_16x16x32_bf16 v[12:15], v[220:223], v[204:207], v[12:15]
	global_load_dwordx4 v[204:207], v[76:77], off offset:896
	global_load_dwordx4 v[208:211], v[68:69], off offset:896
	global_load_dwordx4 v[212:215], v[72:73], off offset:896
	global_load_dwordx4 v[216:219], v[70:71], off offset:896
	global_load_dwordx4 v[220:223], v[74:75], off offset:896
	s_waitcnt vmcnt(35)
	v_mfma_f32_16x16x32_bf16 v[0:3], v[228:231], v[224:227], v[0:3]
	v_mfma_f32_16x16x32_bf16 v[4:7], v[232:235], v[224:227], v[4:7]
	v_mfma_f32_16x16x32_bf16 v[8:11], v[236:239], v[224:227], v[8:11]
	v_mfma_f32_16x16x32_bf16 v[12:15], v[240:243], v[224:227], v[12:15]
	global_load_dwordx4 v[224:227], v[76:77], off offset:960
	global_load_dwordx4 v[228:231], v[68:69], off offset:960
	global_load_dwordx4 v[232:235], v[72:73], off offset:960
	global_load_dwordx4 v[236:239], v[70:71], off offset:960
	global_load_dwordx4 v[240:243], v[74:75], off offset:960
	s_waitcnt vmcnt(35)
	v_mfma_f32_16x16x32_bf16 v[0:3], v[88:91], v[84:87], v[0:3]
	v_mfma_f32_16x16x32_bf16 v[4:7], v[92:95], v[84:87], v[4:7]
	v_mfma_f32_16x16x32_bf16 v[8:11], v[96:99], v[84:87], v[8:11]
	v_mfma_f32_16x16x32_bf16 v[12:15], v[100:103], v[84:87], v[12:15]
	global_load_dwordx4 v[84:87], v[76:77], off offset:1024
	global_load_dwordx4 v[88:91], v[68:69], off offset:1024
	global_load_dwordx4 v[92:95], v[72:73], off offset:1024
	global_load_dwordx4 v[96:99], v[70:71], off offset:1024
	global_load_dwordx4 v[100:103], v[74:75], off offset:1024
	s_waitcnt vmcnt(35)
	v_mfma_f32_16x16x32_bf16 v[0:3], v[108:111], v[104:107], v[0:3]
	v_mfma_f32_16x16x32_bf16 v[4:7], v[112:115], v[104:107], v[4:7]
	v_mfma_f32_16x16x32_bf16 v[8:11], v[116:119], v[104:107], v[8:11]
	v_mfma_f32_16x16x32_bf16 v[12:15], v[120:123], v[104:107], v[12:15]
	global_load_dwordx4 v[104:107], v[76:77], off offset:1088
	global_load_dwordx4 v[108:111], v[68:69], off offset:1088
	global_load_dwordx4 v[112:115], v[72:73], off offset:1088
	global_load_dwordx4 v[116:119], v[70:71], off offset:1088
	global_load_dwordx4 v[120:123], v[74:75], off offset:1088
	s_waitcnt vmcnt(35)
	v_mfma_f32_16x16x32_bf16 v[0:3], v[128:131], v[124:127], v[0:3]
	v_mfma_f32_16x16x32_bf16 v[4:7], v[132:135], v[124:127], v[4:7]
	v_mfma_f32_16x16x32_bf16 v[8:11], v[136:139], v[124:127], v[8:11]
	v_mfma_f32_16x16x32_bf16 v[12:15], v[140:143], v[124:127], v[12:15]
	global_load_dwordx4 v[124:127], v[76:77], off offset:1152
	global_load_dwordx4 v[128:131], v[68:69], off offset:1152
	global_load_dwordx4 v[132:135], v[72:73], off offset:1152
	global_load_dwordx4 v[136:139], v[70:71], off offset:1152
	global_load_dwordx4 v[140:143], v[74:75], off offset:1152
	s_waitcnt vmcnt(35)
	v_mfma_f32_16x16x32_bf16 v[0:3], v[148:151], v[144:147], v[0:3]
	v_mfma_f32_16x16x32_bf16 v[4:7], v[152:155], v[144:147], v[4:7]
	v_mfma_f32_16x16x32_bf16 v[8:11], v[156:159], v[144:147], v[8:11]
	v_mfma_f32_16x16x32_bf16 v[12:15], v[160:163], v[144:147], v[12:15]
	global_load_dwordx4 v[144:147], v[76:77], off offset:1216
	global_load_dwordx4 v[148:151], v[68:69], off offset:1216
	global_load_dwordx4 v[152:155], v[72:73], off offset:1216
	global_load_dwordx4 v[156:159], v[70:71], off offset:1216
	global_load_dwordx4 v[160:163], v[74:75], off offset:1216
	s_waitcnt vmcnt(35)
	v_mfma_f32_16x16x32_bf16 v[0:3], v[168:171], v[164:167], v[0:3]
	v_mfma_f32_16x16x32_bf16 v[4:7], v[172:175], v[164:167], v[4:7]
	v_mfma_f32_16x16x32_bf16 v[8:11], v[176:179], v[164:167], v[8:11]
	v_mfma_f32_16x16x32_bf16 v[12:15], v[180:183], v[164:167], v[12:15]
	global_load_dwordx4 v[164:167], v[76:77], off offset:1280
	global_load_dwordx4 v[168:171], v[68:69], off offset:1280
	global_load_dwordx4 v[172:175], v[72:73], off offset:1280
	global_load_dwordx4 v[176:179], v[70:71], off offset:1280
	global_load_dwordx4 v[180:183], v[74:75], off offset:1280
	s_waitcnt vmcnt(35)
	v_mfma_f32_16x16x32_bf16 v[0:3], v[188:191], v[184:187], v[0:3]
	v_mfma_f32_16x16x32_bf16 v[4:7], v[192:195], v[184:187], v[4:7]
	v_mfma_f32_16x16x32_bf16 v[8:11], v[196:199], v[184:187], v[8:11]
	v_mfma_f32_16x16x32_bf16 v[12:15], v[200:203], v[184:187], v[12:15]
	global_load_dwordx4 v[184:187], v[76:77], off offset:1344
	global_load_dwordx4 v[188:191], v[68:69], off offset:1344
	global_load_dwordx4 v[192:195], v[72:73], off offset:1344
	global_load_dwordx4 v[196:199], v[70:71], off offset:1344
	global_load_dwordx4 v[200:203], v[74:75], off offset:1344
	s_waitcnt vmcnt(35)
; #define SK_LOAD(AR, BR, k0) do { _Pragma("unroll") for (int i = 0; i < UNR; ++i) { AR[i] = *(const bf16x8*)(ap + (k0) + 32 * i); \
;             _Pragma("unroll") for (int g = 0; g < NG; ++g) BR[g][i] = *(const bf16x8*)(bp[g] + (k0) + 32 * i); } } while (0)
; #define SK_MMA(AR, BR) do { _Pragma("unroll") for (int i = 0; i < UNR; ++i) _Pragma("unroll") for (int g = 0; g < NG; ++g) acc[g] = __builtin_amdgcn_mfma_f32_16x16x32_bf16(BR[g][i], AR[i], acc[g], 0, 0, 0); } while (0)
;     ...
;         for (int k = 0; k < KL; k += 64 * UNR) {
;             SK_LOAD(a1, b1, k + 32 * UNR);
;             SK_MMA(a0, b0);
;             if (k + 64 * UNR < KL) SK_LOAD(a0, b0, k + 64 * UNR);
;             SK_MMA(a1, b1);
	v_mfma_f32_16x16x32_bf16 v[0:3], v[208:211], v[204:207], v[0:3]
	v_mfma_f32_16x16x32_bf16 v[4:7], v[212:215], v[204:207], v[4:7]
	v_mfma_f32_16x16x32_bf16 v[8:11], v[216:219], v[204:207], v[8:11]
	v_mfma_f32_16x16x32_bf16 v[12:15], v[220:223], v[204:207], v[12:15]
	global_load_dwordx4 v[204:207], v[76:77], off offset:1408
	global_load_dwordx4 v[208:211], v[68:69], off offset:1408
	global_load_dwordx4 v[212:215], v[72:73], off offset:1408
	global_load_dwordx4 v[216:219], v[70:71], off offset:1408
	global_load_dwordx4 v[220:223], v[74:75], off offset:1408
	s_waitcnt vmcnt(35)
	v_mfma_f32_16x16x32_bf16 v[0:3], v[228:231], v[224:227], v[0:3]
	v_mfma_f32_16x16x32_bf16 v[4:7], v[232:235], v[224:227], v[4:7]
	v_mfma_f32_16x16x32_bf16 v[8:11], v[236:239], v[224:227], v[8:11]
	v_mfma_f32_16x16x32_bf16 v[12:15], v[240:243], v[224:227], v[12:15]
	global_load_dwordx4 v[224:227], v[76:77], off offset:1472
	global_load_dwordx4 v[228:231], v[68:69], off offset:1472
	global_load_dwordx4 v[232:235], v[72:73], off offset:1472
	global_load_dwordx4 v[236:239], v[70:71], off offset:1472
	global_load_dwordx4 v[240:243], v[74:75], off offset:1472
	s_waitcnt vmcnt(35)
	v_mfma_f32_16x16x32_bf16 v[0:3], v[88:91], v[84:87], v[0:3]
	v_mfma_f32_16x16x32_bf16 v[4:7], v[92:95], v[84:87], v[4:7]
	v_mfma_f32_16x16x32_bf16 v[8:11], v[96:99], v[84:87], v[8:11]
	v_mfma_f32_16x16x32_bf16 v[12:15], v[100:103], v[84:87], v[12:15]
	global_load_dwordx4 v[84:87], v[76:77], off offset:1536
	global_load_dwordx4 v[88:91], v[68:69], off offset:1536
	global_load_dwordx4 v[92:95], v[72:73], off offset:1536
	global_load_dwordx4 v[96:99], v[70:71], off offset:1536
	global_load_dwordx4 v[100:103], v[74:75], off offset:1536
	s_waitcnt vmcnt(35)
	v_mfma_f32_16x16x32_bf16 v[0:3], v[108:111], v[104:107], v[0:3]
	v_mfma_f32_16x16x32_bf16 v[4:7], v[112:115], v[104:107], v[4:7]
	v_mfma_f32_16x16x32_bf16 v[8:11], v[116:119], v[104:107], v[8:11]
	v_mfma_f32_16x16x32_bf16 v[12:15], v[120:123], v[104:107], v[12:15]
	global_load_dwordx4 v[104:107], v[76:77], off offset:1600
	global_load_dwordx4 v[108:111], v[68:69], off offset:1600
	global_load_dwordx4 v[112:115], v[72:73], off offset:1600
	global_load_dwordx4 v[116:119], v[70:71], off offset:1600
	global_load_dwordx4 v[120:123], v[74:75], off offset:1600
	s_waitcnt vmcnt(35)
	v_mfma_f32_16x16x32_bf16 v[0:3], v[128:131], v[124:127], v[0:3]
	v_mfma_f32_16x16x32_bf16 v[4:7], v[132:135], v[124:127], v[4:7]
	v_mfma_f32_16x16x32_bf16 v[8:11], v[136:139], v[124:127], v[8:11]
	v_mfma_f32_16x16x32_bf16 v[12:15], v[140:143], v[124:127], v[12:15]
	global_load_dwordx4 v[124:127], v[76:77], off offset:1664
	global_load_dwordx4 v[128:131], v[68:69], off offset:1664
	global_load_dwordx4 v[132:135], v[72:73], off offset:1664
	global_load_dwordx4 v[136:139], v[70:71], off offset:1664
	global_load_dwordx4 v[140:143], v[74:75], off offset:1664
	s_waitcnt vmcnt(35)
	v_mfma_f32_16x16x32_bf16 v[0:3], v[148:151], v[144:147], v[0:3]
	v_mfma_f32_16x16x32_bf16 v[4:7], v[152:155], v[144:147], v[4:7]
	v_mfma_f32_16x16x32_bf16 v[8:11], v[156:159], v[144:147], v[8:11]
	v_mfma_f32_16x16x32_bf16 v[12:15], v[160:163], v[144:147], v[12:15]
	global_load_dwordx4 v[144:147], v[76:77], off offset:1728
	global_load_dwordx4 v[148:151], v[68:69], off offset:1728
	global_load_dwordx4 v[152:155], v[72:73], off offset:1728
	global_load_dwordx4 v[156:159], v[70:71], off offset:1728
	global_load_dwordx4 v[160:163], v[74:75], off offset:1728
	s_waitcnt vmcnt(35)
	v_mfma_f32_16x16x32_bf16 v[0:3], v[168:171], v[164:167], v[0:3]
	v_mfma_f32_16x16x32_bf16 v[4:7], v[172:175], v[164:167], v[4:7]
	v_mfma_f32_16x16x32_bf16 v[8:11], v[176:179], v[164:167], v[8:11]
	v_mfma_f32_16x16x32_bf16 v[12:15], v[180:183], v[164:167], v[12:15]
	global_load_dwordx4 v[164:167], v[76:77], off offset:1792
	global_load_dwordx4 v[168:171], v[68:69], off offset:1792
	global_load_dwordx4 v[172:175], v[72:73], off offset:1792
	global_load_dwordx4 v[176:179], v[70:71], off offset:1792
	global_load_dwordx4 v[180:183], v[74:75], off offset:1792
	s_waitcnt vmcnt(35)
	v_mfma_f32_16x16x32_bf16 v[0:3], v[188:191], v[184:187], v[0:3]
	v_mfma_f32_16x16x32_bf16 v[4:7], v[192:195], v[184:187], v[4:7]
	v_mfma_f32_16x16x32_bf16 v[8:11], v[196:199], v[184:187], v[8:11]
	v_mfma_f32_16x16x32_bf16 v[12:15], v[200:203], v[184:187], v[12:15]
	global_load_dwordx4 v[184:187], v[76:77], off offset:1856
	global_load_dwordx4 v[188:191], v[68:69], off offset:1856
	global_load_dwordx4 v[192:195], v[72:73], off offset:1856
	global_load_dwordx4 v[196:199], v[70:71], off offset:1856
	global_load_dwordx4 v[200:203], v[74:75], off offset:1856
	s_waitcnt vmcnt(35)
	v_mfma_f32_16x16x32_bf16 v[0:3], v[208:211], v[204:207], v[0:3]
	v_mfma_f32_16x16x32_bf16 v[4:7], v[212:215], v[204:207], v[4:7]
	v_mfma_f32_16x16x32_bf16 v[8:11], v[216:219], v[204:207], v[8:11]
	v_mfma_f32_16x16x32_bf16 v[12:15], v[220:223], v[204:207], v[12:15]
	global_load_dwordx4 v[204:207], v[76:77], off offset:1920
	global_load_dwordx4 v[208:211], v[68:69], off offset:1920
	global_load_dwordx4 v[212:215], v[72:73], off offset:1920
	global_load_dwordx4 v[216:219], v[70:71], off offset:1920
	global_load_dwordx4 v[220:223], v[74:75], off offset:1920
	s_waitcnt vmcnt(35)
; __device__ __forceinline__ unsigned cvt_pk_bf16(float lo, float hi) { unsigned r; asm volatile("v_cvt_pk_bf16_f32 %0, %1, %2" : "=v"(r) : "v"(lo), "v"(hi)); return r; }
; #define SK_LOAD(AR, BR, k0) do { _Pragma("unroll") for (int i = 0; i < UNR; ++i) { AR[i] = *(const bf16x8*)(ap + (k0) + 32 * i); \
;             _Pragma("unroll") for (int g = 0; g < NG; ++g) BR[g][i] = *(const bf16x8*)(bp[g] + (k0) + 32 * i); } } while (0)
; #define SK_MMA(AR, BR) do { _Pragma("unroll") for (int i = 0; i < UNR; ++i) _Pragma("unroll") for (int g = 0; g < NG; ++g) acc[g] = __builtin_amdgcn_mfma_f32_16x16x32_bf16(BR[g][i], AR[i], acc[g], 0, 0, 0); } while (0)
; __device__ __forceinline__ float rs_sample(const float* ssps, int srow) { return rs_from(ssps + (size_t)srow * 64, 16, 1.0f / 1024.0f); }
;     __device__ __forceinline__ void operator()(const f32x4 (&acc)[2], int srow, int cgp, int kq) const { one(acc[0], srow, 2 * cgp, kq); one(acc[1], srow, 2 * cgp + 1, kq); }
;     ...
;             SK_MMA(a0, b0);
;             if (k + 64 * UNR < KL) SK_LOAD(a0, b0, k + 64 * UNR);
;             SK_MMA(a1, b1);
;     __device__ __forceinline__ void operator()(const f32x4 (&acc)[4], int srow, int cgp, int kq) const {
;         const float rs = rs_sample(ssps, srow);
; #pragma unroll
;         for (int q = 0; q < 2; ++q) { f32x4 o;
; #pragma unroll
;             for (int j = 0; j < 4; ++j) { const float g = acc[2 * q][j] * rs, up = acc[2 * q + 1][j] * rs; o[j] = g * __builtin_amdgcn_rcpf(1.0f + __expf(-g)) * up; }
;             u32x2 w; w.x = cvt_pk_bf16(o[0], o[1]); w.y = cvt_pk_bf16(o[2], o[3]);
;             *(u32x2*)(act + (size_t)(TP + srow) * FF + (2 * cgp + q) * 16 + 4 * kq) = w; }
;     }
	v_mfma_f32_16x16x32_bf16 v[0:3], v[228:231], v[224:227], v[0:3]
	v_mfma_f32_16x16x32_bf16 v[4:7], v[232:235], v[224:227], v[4:7]
	v_mfma_f32_16x16x32_bf16 v[8:11], v[236:239], v[224:227], v[8:11]
	v_mfma_f32_16x16x32_bf16 v[12:15], v[240:243], v[224:227], v[12:15]
	global_load_dwordx4 v[224:227], v[76:77], off offset:1984
	global_load_dwordx4 v[228:231], v[68:69], off offset:1984
	global_load_dwordx4 v[232:235], v[72:73], off offset:1984
	global_load_dwordx4 v[236:239], v[70:71], off offset:1984
	global_load_dwordx4 v[240:243], v[74:75], off offset:1984
	s_waitcnt vmcnt(35)
	v_mfma_f32_16x16x32_bf16 v[0:3], v[88:91], v[84:87], v[0:3]
	v_mfma_f32_16x16x32_bf16 v[4:7], v[92:95], v[84:87], v[4:7]
	v_mfma_f32_16x16x32_bf16 v[8:11], v[96:99], v[84:87], v[8:11]
	v_mfma_f32_16x16x32_bf16 v[12:15], v[100:103], v[84:87], v[12:15]
	s_waitcnt vmcnt(30)
	v_mfma_f32_16x16x32_bf16 v[0:3], v[108:111], v[104:107], v[0:3]
	v_mfma_f32_16x16x32_bf16 v[4:7], v[112:115], v[104:107], v[4:7]
	v_mfma_f32_16x16x32_bf16 v[8:11], v[116:119], v[104:107], v[8:11]
	v_mfma_f32_16x16x32_bf16 v[12:15], v[120:123], v[104:107], v[12:15]
	s_waitcnt vmcnt(25)
	v_mfma_f32_16x16x32_bf16 v[0:3], v[128:131], v[124:127], v[0:3]
	v_mfma_f32_16x16x32_bf16 v[4:7], v[132:135], v[124:127], v[4:7]
	v_mfma_f32_16x16x32_bf16 v[8:11], v[136:139], v[124:127], v[8:11]
	v_mfma_f32_16x16x32_bf16 v[12:15], v[140:143], v[124:127], v[12:15]
	s_waitcnt vmcnt(20)
	v_mfma_f32_16x16x32_bf16 v[0:3], v[148:151], v[144:147], v[0:3]
	v_mfma_f32_16x16x32_bf16 v[4:7], v[152:155], v[144:147], v[4:7]
	v_mfma_f32_16x16x32_bf16 v[8:11], v[156:159], v[144:147], v[8:11]
	v_mfma_f32_16x16x32_bf16 v[12:15], v[160:163], v[144:147], v[12:15]
	s_waitcnt vmcnt(15)
	v_mfma_f32_16x16x32_bf16 v[0:3], v[168:171], v[164:167], v[0:3]
	v_mfma_f32_16x16x32_bf16 v[4:7], v[172:175], v[164:167], v[4:7]
	v_mfma_f32_16x16x32_bf16 v[8:11], v[176:179], v[164:167], v[8:11]
	v_mfma_f32_16x16x32_bf16 v[12:15], v[180:183], v[164:167], v[12:15]
	s_waitcnt vmcnt(10)
	v_mfma_f32_16x16x32_bf16 v[0:3], v[188:191], v[184:187], v[0:3]
	v_mfma_f32_16x16x32_bf16 v[4:7], v[192:195], v[184:187], v[4:7]
	v_mfma_f32_16x16x32_bf16 v[8:11], v[196:199], v[184:187], v[8:11]
	v_mfma_f32_16x16x32_bf16 v[12:15], v[200:203], v[184:187], v[12:15]
	s_waitcnt vmcnt(5)
	v_mfma_f32_16x16x32_bf16 v[0:3], v[208:211], v[204:207], v[0:3]
	v_mfma_f32_16x16x32_bf16 v[4:7], v[212:215], v[204:207], v[4:7]
	v_mfma_f32_16x16x32_bf16 v[8:11], v[216:219], v[204:207], v[8:11]
	v_mfma_f32_16x16x32_bf16 v[12:15], v[220:223], v[204:207], v[12:15]
	s_waitcnt vmcnt(0)
	v_mfma_f32_16x16x32_bf16 v[0:3], v[228:231], v[224:227], v[0:3]
	v_mfma_f32_16x16x32_bf16 v[4:7], v[232:235], v[224:227], v[4:7]
	v_mfma_f32_16x16x32_bf16 v[8:11], v[236:239], v[224:227], v[8:11]
	v_mfma_f32_16x16x32_bf16 v[12:15], v[240:243], v[224:227], v[12:15]
	v_add_f32_e32 v16, v16, v17
	v_add_f32_e32 v18, v18, v19
	v_add_f32_e32 v20, v20, v21
	v_add_f32_e32 v22, v22, v23
	v_add_f32_e32 v24, v24, v25
	v_add_f32_e32 v26, v26, v27
	v_add_f32_e32 v28, v28, v29
	v_add_f32_e32 v30, v30, v31
	v_add_f32_e32 v16, v16, v18
	v_add_f32_e32 v20, v20, v22
	v_add_f32_e32 v24, v24, v26
	v_add_f32_e32 v28, v28, v30
	v_add_f32_e32 v16, v16, v20
	v_add_f32_e32 v24, v24, v28
	v_add_f32_e32 v16, v16, v24
	ds_bpermute_b32 v17, v41, v16
	s_waitcnt lgkmcnt(0)
	v_add_f32_e32 v16, v16, v17
	ds_bpermute_b32 v17, v42, v16
	s_waitcnt lgkmcnt(0)
	v_add_f32_e32 v16, v16, v17
	v_fmamk_f32 v16, v16, 0x3a800000, v80
	v_rsq_f32_e32 v16, v16
	s_nop 0
	v_pk_mul_f32 v[0:1], v[0:1], v[16:17] op_sel_hi:[1,0]
	v_pk_mul_f32 v[2:3], v[2:3], v[16:17] op_sel_hi:[1,0]
	v_pk_mul_f32 v[4:5], v[4:5], v[16:17] op_sel_hi:[1,0]
	v_pk_mul_f32 v[6:7], v[6:7], v[16:17] op_sel_hi:[1,0]
	v_pk_mul_f32 v[8:9], v[8:9], v[16:17] op_sel_hi:[1,0]
	v_pk_mul_f32 v[10:11], v[10:11], v[16:17] op_sel_hi:[1,0]
	v_pk_mul_f32 v[12:13], v[12:13], v[16:17] op_sel_hi:[1,0]
	v_pk_mul_f32 v[14:15], v[14:15], v[16:17] op_sel_hi:[1,0]
	v_mul_f32_e32 v44, 0xbfb8aa3b, v0
	v_mul_f32_e32 v45, 0xbfb8aa3b, v1
	v_mul_f32_e32 v46, 0xbfb8aa3b, v2
	v_mul_f32_e32 v47, 0xbfb8aa3b, v3
	v_mul_f32_e32 v48, 0xbfb8aa3b, v8
	v_mul_f32_e32 v49, 0xbfb8aa3b, v9
	v_mul_f32_e32 v50, 0xbfb8aa3b, v10
	v_mul_f32_e32 v51, 0xbfb8aa3b, v11
	v_exp_f32_e32 v44, v44
	v_exp_f32_e32 v45, v45
	v_exp_f32_e32 v46, v46
	v_exp_f32_e32 v47, v47
	v_exp_f32_e32 v48, v48
	v_exp_f32_e32 v49, v49
	v_exp_f32_e32 v50, v50
	v_exp_f32_e32 v51, v51
	v_add_f32_e32 v44, 1.0, v44
	v_add_f32_e32 v45, 1.0, v45
	v_add_f32_e32 v46, 1.0, v46
	v_add_f32_e32 v47, 1.0, v47
	v_add_f32_e32 v48, 1.0, v48
	v_add_f32_e32 v49, 1.0, v49
	v_add_f32_e32 v50, 1.0, v50
	v_add_f32_e32 v51, 1.0, v51
	v_rcp_f32_e32 v44, v44
	v_rcp_f32_e32 v45, v45
	v_rcp_f32_e32 v46, v46
	v_rcp_f32_e32 v47, v47
	v_rcp_f32_e32 v48, v48
	v_rcp_f32_e32 v49, v49
	v_rcp_f32_e32 v50, v50
	v_rcp_f32_e32 v51, v51
	v_mul_f32_e32 v44, v0, v44
	v_mul_f32_e32 v45, v1, v45
	v_mul_f32_e32 v46, v2, v46
	v_mul_f32_e32 v47, v3, v47
	v_mul_f32_e32 v48, v8, v48
	v_mul_f32_e32 v49, v9, v49
	v_mul_f32_e32 v50, v10, v50
	v_mul_f32_e32 v51, v11, v51
	v_mul_f32_e32 v44, v4, v44
	v_mul_f32_e32 v45, v5, v45
	v_mul_f32_e32 v46, v6, v46
	v_mul_f32_e32 v47, v7, v47
	v_mul_f32_e32 v48, v12, v48
	v_mul_f32_e32 v49, v13, v49
	v_mul_f32_e32 v50, v14, v50
	v_mul_f32_e32 v51, v15, v51
	v_cvt_pk_bf16_f32 v52, v44, v45
	v_cvt_pk_bf16_f32 v53, v46, v47
	v_cvt_pk_bf16_f32 v54, v48, v49
	v_cvt_pk_bf16_f32 v55, v50, v51
	global_store_dwordx2 v[38:39], v[52:53], off
	global_store_dwordx2 v[38:39], v[54:55], off offset:32
.Lsku_end:
	s_cbranch_scc1 .LBB0_358

;     __host__ __device__ bool next(int i, Unit& u) const {
;         const long L = (long)i * G + c; if (L >= nwg) return false;
;         int wgid = (int)L; { const int q = nwg / NXCD, r = nwg % NXCD, xcd = wgid % NXCD, off = wgid / NXCD; wgid = (xcd < r ? xcd * (q + 1) : r * (q + 1) + (xcd - r) * q) + off; }
;         const int nig = WGM * nN, gid = wgid / nig, fm = gid * WGM, gsz = (nM - fm) < WGM ? (nM - fm) : WGM;
;         u.pm = fm + ((wgid % nig) % gsz); u.pn = (wgid % nig) / gsz; return true;
;     }
;     __device__ __forceinline__ void operator()(AccRef acc, const pg8::Unit& u, int wr, int wc, int fr, int fq) const {
;     ...
;                     bf16_t* xp = xb + (size_t)row * D + col0 + bj * 128;
;                     f32x4 a, b; unpack8(*(const u32x4*)xp, a, b);
.LBB0_455:
	v_lshl_add_u32 v252, s64, 8, v156
	v_lshl_or_b32 v253, s14, 8, v158
	v_lshlrev_b32_e32 v253, 1, v253
	v_lshl_add_u32 v252, v252, 11, v253
	global_load_dwordx4 v[230:233], v252, s[42:43]
	global_load_dwordx4 v[234:237], v252, s[42:43] offset:256
	v_add_u32_e32 v253, 0x8000, v252
	global_load_dwordx4 v[238:241], v253, s[42:43]
	global_load_dwordx4 v[242:245], v253, s[42:43] offset:256
	v_add_u32_e32 v253, 0x10000, v252
	global_load_dwordx4 v[246:249], v253, s[42:43]
	global_load_dwordx4 v[250:253], v253, s[42:43] offset:256
	s_add_i32 s61, s61, 1
	s_mul_i32 s0, s61, s50
	s_mul_hi_u32 s1, s61, s51
	s_add_i32 s1, s1, s0
	s_mul_i32 s0, s61, s51
	s_add_u32 s4, s0, s18
	s_addc_u32 s5, s1, s58
	v_cmp_gt_i64_e32 vcc, s[4:5], v[142:143]
	v_cmp_lt_i64_e64 s[0:1], s[4:5], v[140:141]
	s_cbranch_vccnz .LBB0_461
	s_ashr_i32 s5, s4, 31
	s_lshr_b32 s5, s5, 29
	s_add_i32 s28, s4, s5
	s_and_b32 s5, s28, -8
	s_sub_i32 s29, s4, s5
	s_cmp_gt_i32 s29, -1
	s_mov_b64 s[4:5], -1
	s_cbranch_scc0 .LBB0_458
	s_lshl_b32 s62, s29, 6
	s_mov_b64 s[4:5], 0

; #define PG8_STAGE(bufoff, gbase, voff) do { _Pragma("unroll") for (int _i = 0; _i < 2; ++_i) \
;         __builtin_amdgcn_global_load_lds((const unsigned*)((const char*)(gbase) + (voff)[_i]), (PG8_LAS unsigned*)(lds + (bufoff) + ldsw + _i * 8192), 16, 0, 0); } while (0)
; #define PG8_LDA(dst, b, h) do { _Pragma("unroll") for (int m = 0; m < 4; ++m) _Pragma("unroll") for (int k = 0; k < 2; ++k) dst[m][k] = *(const PG8_LAS bf16x8*)(lds + PG8_SA(b, h) + aoff + m * 2048 + k * 1024); } while (0)
; #define PG8_LDB(dst, b, h) do { _Pragma("unroll") for (int n = 0; n < 2; ++n) _Pragma("unroll") for (int k = 0; k < 2; ++k) dst[n][k] = *(const PG8_LAS bf16x8*)(lds + PG8_SB(b, h) + boff + n * 2048 + k * 1024); } while (0)
; #define PG8_MMA(ai, bj, At, Bt) do { __builtin_amdgcn_s_setprio(1); _Pragma("unroll") for (int m = 0; m < 4; ++m) _Pragma("unroll") for (int n = 0; n < 2; ++n) _Pragma("unroll") for (int k = 0; k < 2; ++k) \
;         acc[ai][bj][m][n] = __builtin_amdgcn_mfma_f32_16x16x32_bf16(Bt[n][k], At[m][k], acc[ai][bj][m][n], 0, 0, 0); __builtin_amdgcn_s_setprio(0); } while (0)
; #define PG8_WAIT_V(n) asm volatile("s_waitcnt vmcnt(" #n ")" ::: "memory")
; #define PG8_WAIT_L(n) asm volatile("s_waitcnt lgkmcnt(" #n ")" ::: "memory")
; #define PG8_BAR __builtin_amdgcn_s_barrier()
; #define PG8_SCHED __builtin_amdgcn_sched_barrier(0)
; template <class Epi, class Sched, bool ALIGN_EPI = false, bool SP2 = false>
; __device__ __forceinline__ void gemm_phase(PG8_LAS unsigned char* lds, const Gemm g, const Sched& S, const Epi& E) {
;     ...
;             PG8_LDB(B0, 0, 0); PG8_LDB(B1, 0, 1); PG8_SCHED; PG8_LDA(At, 0, 0); PG8_STAGE(PG8_SA(1, 1), a1 + hstep, voffA);
;             PG8_WAIT_V(8); PG8_WAIT_L(0); PG8_BAR; PG8_MMA(0, 0, At, B0); PG8_MMA(0, 1, At, B1); PG8_BAR; PG8_SCHED;
;             PG8_LDA(At, 0, 1); PG8_STAGE(PG8_SB(0, 0), b2, voffB); PG8_STAGE(PG8_SB(0, 1), b2 + hstep, voffB); PG8_STAGE(PG8_SA(0, 0), a2, voffA);
;             PG8_WAIT_V(8); PG8_WAIT_L(0); PG8_BAR; PG8_MMA(1, 0, At, B0); PG8_MMA(1, 1, At, B1); PG8_BAR; PG8_SCHED;
.LBB0_467:
	ds_read_b128 v[144:147], v159
	ds_read_b128 v[148:151], v159 offset:1024
	ds_read_b128 v[152:155], v159 offset:2048
	ds_read_b128 v[164:167], v159 offset:3072
	ds_read_b128 v[168:171], v160
	ds_read_b128 v[172:175], v160 offset:1024
	ds_read_b128 v[180:183], v160 offset:2048
	ds_read_b128 v[184:187], v160 offset:3072
	s_add_i32 s67, s34, 2
	s_add_u32 s68, s30, 0x80
	s_addc_u32 s35, s31, 0
	s_cmp_eq_u32 s41, s34
	s_cselect_b32 s34, s0, s68
	s_cselect_b32 s35, s1, s35
	s_cselect_b32 s69, s29, s66
	s_cselect_b32 s68, s28, s65
	v_lshl_add_u64 v[176:177], s[30:31], 0, v[136:137]
	s_add_i32 m0, s17, 0xc000
	ds_read_b128 v[188:191], v161
	ds_read_b128 v[192:195], v161 offset:1024
	ds_read_b128 v[196:199], v161 offset:2048
	ds_read_b128 v[200:203], v161 offset:3072
	ds_read_b128 v[204:207], v161 offset:4096
	ds_read_b128 v[208:211], v161 offset:5120
	ds_read_b128 v[212:215], v161 offset:6144
	ds_read_b128 v[216:219], v161 offset:7168
	global_load_lds_dwordx4 v[176:177], off
	v_lshl_add_u64 v[176:177], s[30:31], 0, v[138:139]
	s_add_i32 m0, s17, 0xe000
	s_nop 0
	global_load_lds_dwordx4 v[176:177], off
	s_waitcnt vmcnt(8)
	s_waitcnt lgkmcnt(0)
	s_barrier
	s_setprio 1
	s_waitcnt lgkmcnt(0)
	v_mfma_f32_16x16x32_bf16 v[124:127], v[144:147], v[188:191], v[124:127]
	v_mfma_f32_16x16x32_bf16 v[120:123], v[152:155], v[188:191], v[120:123]
	v_mfma_f32_16x16x32_bf16 v[116:119], v[144:147], v[196:199], v[116:119]
	v_mfma_f32_16x16x32_bf16 v[112:115], v[152:155], v[196:199], v[112:115]
	v_mfma_f32_16x16x32_bf16 v[104:107], v[144:147], v[204:207], v[104:107]
	v_mfma_f32_16x16x32_bf16 v[96:99], v[152:155], v[204:207], v[96:99]
	v_mfma_f32_16x16x32_bf16 v[88:91], v[144:147], v[212:215], v[88:91]
	v_mfma_f32_16x16x32_bf16 v[80:83], v[152:155], v[212:215], v[80:83]
	v_mfma_f32_16x16x32_bf16 v[124:127], v[148:151], v[192:195], v[124:127]
	v_mfma_f32_16x16x32_bf16 v[120:123], v[164:167], v[192:195], v[120:123]
	v_mfma_f32_16x16x32_bf16 v[116:119], v[148:151], v[200:203], v[116:119]
	v_mfma_f32_16x16x32_bf16 v[112:115], v[164:167], v[200:203], v[112:115]
	v_mfma_f32_16x16x32_bf16 v[104:107], v[148:151], v[208:211], v[104:107]
	v_mfma_f32_16x16x32_bf16 v[96:99], v[164:167], v[208:211], v[96:99]
	v_mfma_f32_16x16x32_bf16 v[88:91], v[148:151], v[216:219], v[88:91]
	v_mfma_f32_16x16x32_bf16 v[80:83], v[164:167], v[216:219], v[80:83]
	s_setprio 0
	s_setprio 1
	v_mfma_f32_16x16x32_bf16 v[108:111], v[168:171], v[188:191], v[108:111]
	v_mfma_f32_16x16x32_bf16 v[100:103], v[180:183], v[188:191], v[100:103]
	v_mfma_f32_16x16x32_bf16 v[92:95], v[168:171], v[196:199], v[92:95]
	v_mfma_f32_16x16x32_bf16 v[84:87], v[180:183], v[196:199], v[84:87]
	v_mfma_f32_16x16x32_bf16 v[76:79], v[168:171], v[204:207], v[76:79]
	v_mfma_f32_16x16x32_bf16 v[72:75], v[180:183], v[204:207], v[72:75]
	v_mfma_f32_16x16x32_bf16 v[68:71], v[168:171], v[212:215], v[68:71]
	v_mfma_f32_16x16x32_bf16 v[64:67], v[180:183], v[212:215], v[64:67]
	v_mfma_f32_16x16x32_bf16 v[108:111], v[172:175], v[192:195], v[108:111]
	v_mfma_f32_16x16x32_bf16 v[100:103], v[184:187], v[192:195], v[100:103]
	v_mfma_f32_16x16x32_bf16 v[92:95], v[172:175], v[200:203], v[92:95]
	v_mfma_f32_16x16x32_bf16 v[84:87], v[184:187], v[200:203], v[84:87]
	v_mfma_f32_16x16x32_bf16 v[76:79], v[172:175], v[208:211], v[76:79]
	v_mfma_f32_16x16x32_bf16 v[72:75], v[184:187], v[208:211], v[72:75]
	v_mfma_f32_16x16x32_bf16 v[68:71], v[172:175], v[216:219], v[68:71]
	v_mfma_f32_16x16x32_bf16 v[64:67], v[184:187], v[216:219], v[64:67]
	s_setprio 0
	s_barrier
	s_add_i32 s70, s59, s16
	v_lshl_add_u64 v[176:177], s[68:69], 0, v[130:131]
	s_mov_b32 m0, s70
	ds_read_b128 v[188:191], v161 offset:16384
	ds_read_b128 v[192:195], v161 offset:17408
	ds_read_b128 v[196:199], v161 offset:18432
	ds_read_b128 v[200:203], v161 offset:19456
	ds_read_b128 v[204:207], v161 offset:20480
	ds_read_b128 v[208:211], v161 offset:21504
	ds_read_b128 v[212:215], v161 offset:22528
	ds_read_b128 v[216:219], v161 offset:23552
	global_load_lds_dwordx4 v[176:177], off
	s_add_i32 m0, s70, 0x2000
	v_lshl_add_u64 v[178:179], s[68:69], 0, v[134:135]
	s_add_u32 s68, s68, s6
	s_addc_u32 s69, s69, s7
	s_add_i32 s70, s60, s16
	global_load_lds_dwordx4 v[178:179], off
	v_lshl_add_u64 v[220:221], s[68:69], 0, v[130:131]
	s_mov_b32 m0, s70
	v_lshl_add_u64 v[222:223], s[68:69], 0, v[134:135]
	global_load_lds_dwordx4 v[220:221], off
	s_add_i32 m0, s70, 0x2000
	v_lshl_add_u64 v[224:225], s[34:35], 0, v[128:129]
	global_load_lds_dwordx4 v[222:223], off
	s_mov_b32 m0, s17
	v_lshl_add_u64 v[226:227], s[34:35], 0, v[132:133]
	global_load_lds_dwordx4 v[224:225], off
	s_mov_b32 m0, s19
	s_nop 0
	global_load_lds_dwordx4 v[226:227], off
	s_waitcnt vmcnt(8)
	s_waitcnt lgkmcnt(0)
	s_barrier
; #define PG8_STAGE(bufoff, gbase, voff) do { _Pragma("unroll") for (int _i = 0; _i < 2; ++_i) \
;         __builtin_amdgcn_global_load_lds((const unsigned*)((const char*)(gbase) + (voff)[_i]), (PG8_LAS unsigned*)(lds + (bufoff) + ldsw + _i * 8192), 16, 0, 0); } while (0)
; #define PG8_LDA(dst, b, h) do { _Pragma("unroll") for (int m = 0; m < 4; ++m) _Pragma("unroll") for (int k = 0; k < 2; ++k) dst[m][k] = *(const PG8_LAS bf16x8*)(lds + PG8_SA(b, h) + aoff + m * 2048 + k * 1024); } while (0)
; #define PG8_LDB(dst, b, h) do { _Pragma("unroll") for (int n = 0; n < 2; ++n) _Pragma("unroll") for (int k = 0; k < 2; ++k) dst[n][k] = *(const PG8_LAS bf16x8*)(lds + PG8_SB(b, h) + boff + n * 2048 + k * 1024); } while (0)
; #define PG8_MMA(ai, bj, At, Bt) do { __builtin_amdgcn_s_setprio(1); _Pragma("unroll") for (int m = 0; m < 4; ++m) _Pragma("unroll") for (int n = 0; n < 2; ++n) _Pragma("unroll") for (int k = 0; k < 2; ++k) \
;         acc[ai][bj][m][n] = __builtin_amdgcn_mfma_f32_16x16x32_bf16(Bt[n][k], At[m][k], acc[ai][bj][m][n], 0, 0, 0); __builtin_amdgcn_s_setprio(0); } while (0)
; #define PG8_WAIT_V(n) asm volatile("s_waitcnt vmcnt(" #n ")" ::: "memory")
; #define PG8_WAIT_L(n) asm volatile("s_waitcnt lgkmcnt(" #n ")" ::: "memory")
; #define PG8_BAR __builtin_amdgcn_s_barrier()
; #define PG8_SCHED __builtin_amdgcn_sched_barrier(0)
; template <class Epi, class Sched, bool ALIGN_EPI = false, bool SP2 = false>
; __device__ __forceinline__ void gemm_phase(PG8_LAS unsigned char* lds, const Gemm g, const Sched& S, const Epi& E) {
;     ...
;             PG8_WAIT_V(8); PG8_WAIT_L(0); PG8_BAR; PG8_MMA(1, 0, At, B0); PG8_MMA(1, 1, At, B1); PG8_BAR; PG8_SCHED;
;             PG8_LDB(B0, 1, 0); PG8_LDB(B1, 1, 1); PG8_SCHED; PG8_LDA(At, 1, 0); PG8_STAGE(PG8_SA(0, 1), a2 + hstep, voffA);
;             PG8_WAIT_V(8); PG8_WAIT_L(0); PG8_BAR; PG8_MMA(0, 0, At, B0); PG8_MMA(0, 1, At, B1); PG8_BAR; PG8_SCHED;
	s_setprio 1
	s_waitcnt lgkmcnt(0)
	v_mfma_f32_16x16x32_bf16 v[60:63], v[144:147], v[188:191], v[60:63]
	v_mfma_f32_16x16x32_bf16 v[56:59], v[152:155], v[188:191], v[56:59]
	v_mfma_f32_16x16x32_bf16 v[52:55], v[144:147], v[196:199], v[52:55]
	v_mfma_f32_16x16x32_bf16 v[48:51], v[152:155], v[196:199], v[48:51]
	v_mfma_f32_16x16x32_bf16 v[40:43], v[144:147], v[204:207], v[40:43]
	v_mfma_f32_16x16x32_bf16 v[32:35], v[152:155], v[204:207], v[32:35]
	v_mfma_f32_16x16x32_bf16 v[24:27], v[144:147], v[212:215], v[24:27]
	v_mfma_f32_16x16x32_bf16 v[16:19], v[152:155], v[212:215], v[16:19]
	v_mfma_f32_16x16x32_bf16 v[60:63], v[148:151], v[192:195], v[60:63]
	v_mfma_f32_16x16x32_bf16 v[56:59], v[164:167], v[192:195], v[56:59]
	v_mfma_f32_16x16x32_bf16 v[52:55], v[148:151], v[200:203], v[52:55]
	v_mfma_f32_16x16x32_bf16 v[48:51], v[164:167], v[200:203], v[48:51]
	v_mfma_f32_16x16x32_bf16 v[40:43], v[148:151], v[208:211], v[40:43]
	v_mfma_f32_16x16x32_bf16 v[32:35], v[164:167], v[208:211], v[32:35]
	v_mfma_f32_16x16x32_bf16 v[24:27], v[148:151], v[216:219], v[24:27]
	v_mfma_f32_16x16x32_bf16 v[16:19], v[164:167], v[216:219], v[16:19]
	s_setprio 0
	s_setprio 1
	v_mfma_f32_16x16x32_bf16 v[44:47], v[168:171], v[188:191], v[44:47]
	v_mfma_f32_16x16x32_bf16 v[36:39], v[180:183], v[188:191], v[36:39]
	v_mfma_f32_16x16x32_bf16 v[28:31], v[168:171], v[196:199], v[28:31]
	v_mfma_f32_16x16x32_bf16 v[20:23], v[180:183], v[196:199], v[20:23]
	v_mfma_f32_16x16x32_bf16 v[12:15], v[168:171], v[204:207], v[12:15]
	v_mfma_f32_16x16x32_bf16 v[8:11], v[180:183], v[204:207], v[8:11]
	v_mfma_f32_16x16x32_bf16 v[4:7], v[168:171], v[212:215], v[4:7]
	v_mfma_f32_16x16x32_bf16 v[0:3], v[180:183], v[212:215], v[0:3]
	v_mfma_f32_16x16x32_bf16 v[44:47], v[172:175], v[192:195], v[44:47]
	v_mfma_f32_16x16x32_bf16 v[36:39], v[184:187], v[192:195], v[36:39]
	v_mfma_f32_16x16x32_bf16 v[28:31], v[172:175], v[200:203], v[28:31]
	v_mfma_f32_16x16x32_bf16 v[20:23], v[184:187], v[200:203], v[20:23]
	v_mfma_f32_16x16x32_bf16 v[12:15], v[172:175], v[208:211], v[12:15]
	v_mfma_f32_16x16x32_bf16 v[8:11], v[184:187], v[208:211], v[8:11]
	v_mfma_f32_16x16x32_bf16 v[4:7], v[172:175], v[216:219], v[4:7]
	v_mfma_f32_16x16x32_bf16 v[0:3], v[184:187], v[216:219], v[0:3]
	s_setprio 0
	s_barrier
	s_add_i32 s68, 0, 0x18000
	v_add_u32_e32 v163, s68, v157
	s_add_i32 s69, 0, 0x1c000
	ds_read_b128 v[144:147], v163
	ds_read_b128 v[148:151], v163 offset:1024
	ds_read_b128 v[152:155], v163 offset:2048
	ds_read_b128 v[164:167], v163 offset:3072
	v_add_u32_e32 v163, s69, v157
	ds_read_b128 v[168:171], v163
	ds_read_b128 v[172:175], v163 offset:1024
	ds_read_b128 v[180:183], v163 offset:2048
	ds_read_b128 v[184:187], v163 offset:3072
	s_add_u32 s34, s34, s6
	s_addc_u32 s35, s35, s7
	s_mov_b32 m0, s33
	v_lshl_add_u64 v[228:229], s[34:35], 0, v[128:129]
	ds_read_b128 v[188:191], v161 offset:32768
	ds_read_b128 v[192:195], v161 offset:33792
	ds_read_b128 v[196:199], v161 offset:34816
	ds_read_b128 v[200:203], v161 offset:35840
	ds_read_b128 v[204:207], v161 offset:36864
	ds_read_b128 v[208:211], v161 offset:37888
	ds_read_b128 v[212:215], v161 offset:38912
	ds_read_b128 v[216:219], v161 offset:39936
	global_load_lds_dwordx4 v[228:229], off
	v_lshl_add_u64 v[228:229], s[34:35], 0, v[132:133]
	s_mov_b32 m0, s36
	s_nop 0
	global_load_lds_dwordx4 v[228:229], off
	s_waitcnt vmcnt(8)
	s_waitcnt lgkmcnt(0)
	s_barrier
	s_setprio 1
	s_waitcnt lgkmcnt(0)
	v_mfma_f32_16x16x32_bf16 v[124:127], v[144:147], v[188:191], v[124:127]
	v_mfma_f32_16x16x32_bf16 v[120:123], v[152:155], v[188:191], v[120:123]
	v_mfma_f32_16x16x32_bf16 v[116:119], v[144:147], v[196:199], v[116:119]
	v_mfma_f32_16x16x32_bf16 v[112:115], v[152:155], v[196:199], v[112:115]
	v_mfma_f32_16x16x32_bf16 v[104:107], v[144:147], v[204:207], v[104:107]
	v_mfma_f32_16x16x32_bf16 v[96:99], v[152:155], v[204:207], v[96:99]
	v_mfma_f32_16x16x32_bf16 v[88:91], v[144:147], v[212:215], v[88:91]
	v_mfma_f32_16x16x32_bf16 v[80:83], v[152:155], v[212:215], v[80:83]
	v_mfma_f32_16x16x32_bf16 v[124:127], v[148:151], v[192:195], v[124:127]
	v_mfma_f32_16x16x32_bf16 v[120:123], v[164:167], v[192:195], v[120:123]
	v_mfma_f32_16x16x32_bf16 v[116:119], v[148:151], v[200:203], v[116:119]
	v_mfma_f32_16x16x32_bf16 v[112:115], v[164:167], v[200:203], v[112:115]
	v_mfma_f32_16x16x32_bf16 v[104:107], v[148:151], v[208:211], v[104:107]
	v_mfma_f32_16x16x32_bf16 v[96:99], v[164:167], v[208:211], v[96:99]
	v_mfma_f32_16x16x32_bf16 v[88:91], v[148:151], v[216:219], v[88:91]
	v_mfma_f32_16x16x32_bf16 v[80:83], v[164:167], v[216:219], v[80:83]
	s_setprio 0
	s_setprio 1
	v_mfma_f32_16x16x32_bf16 v[108:111], v[168:171], v[188:191], v[108:111]
	v_mfma_f32_16x16x32_bf16 v[100:103], v[180:183], v[188:191], v[100:103]
	v_mfma_f32_16x16x32_bf16 v[92:95], v[168:171], v[196:199], v[92:95]
	v_mfma_f32_16x16x32_bf16 v[84:87], v[180:183], v[196:199], v[84:87]
	v_mfma_f32_16x16x32_bf16 v[76:79], v[168:171], v[204:207], v[76:79]
	v_mfma_f32_16x16x32_bf16 v[72:75], v[180:183], v[204:207], v[72:75]
	v_mfma_f32_16x16x32_bf16 v[68:71], v[168:171], v[212:215], v[68:71]
	v_mfma_f32_16x16x32_bf16 v[64:67], v[180:183], v[212:215], v[64:67]
	v_mfma_f32_16x16x32_bf16 v[108:111], v[172:175], v[192:195], v[108:111]
	v_mfma_f32_16x16x32_bf16 v[100:103], v[184:187], v[192:195], v[100:103]
	v_mfma_f32_16x16x32_bf16 v[92:95], v[172:175], v[200:203], v[92:95]
	v_mfma_f32_16x16x32_bf16 v[84:87], v[184:187], v[200:203], v[84:87]
	v_mfma_f32_16x16x32_bf16 v[76:79], v[172:175], v[208:211], v[76:79]
	v_mfma_f32_16x16x32_bf16 v[72:75], v[184:187], v[208:211], v[72:75]
	v_mfma_f32_16x16x32_bf16 v[68:71], v[172:175], v[216:219], v[68:71]
	v_mfma_f32_16x16x32_bf16 v[64:67], v[184:187], v[216:219], v[64:67]
	s_setprio 0
	s_barrier
; #define PG8_STAGE(bufoff, gbase, voff) do { _Pragma("unroll") for (int _i = 0; _i < 2; ++_i) \
;         __builtin_amdgcn_global_load_lds((const unsigned*)((const char*)(gbase) + (voff)[_i]), (PG8_LAS unsigned*)(lds + (bufoff) + ldsw + _i * 8192), 16, 0, 0); } while (0)
; #define PG8_LDA(dst, b, h) do { _Pragma("unroll") for (int m = 0; m < 4; ++m) _Pragma("unroll") for (int k = 0; k < 2; ++k) dst[m][k] = *(const PG8_LAS bf16x8*)(lds + PG8_SA(b, h) + aoff + m * 2048 + k * 1024); } while (0)
; #define PG8_MMA(ai, bj, At, Bt) do { __builtin_amdgcn_s_setprio(1); _Pragma("unroll") for (int m = 0; m < 4; ++m) _Pragma("unroll") for (int n = 0; n < 2; ++n) _Pragma("unroll") for (int k = 0; k < 2; ++k) \
;         acc[ai][bj][m][n] = __builtin_amdgcn_mfma_f32_16x16x32_bf16(Bt[n][k], At[m][k], acc[ai][bj][m][n], 0, 0, 0); __builtin_amdgcn_s_setprio(0); } while (0)
; #define PG8_WAIT_V(n) asm volatile("s_waitcnt vmcnt(" #n ")" ::: "memory")
; #define PG8_BAR __builtin_amdgcn_s_barrier()
; template <class Epi, class Sched, bool ALIGN_EPI = false, bool SP2 = false>
; __device__ __forceinline__ void gemm_phase(PG8_LAS unsigned char* lds, const Gemm g, const Sched& S, const Epi& E) {
;     ...
;             PG8_LDA(At, 1, 1); PG8_STAGE(PG8_SB(1, 0), b3, voffB); PG8_STAGE(PG8_SB(1, 1), b3 + hstep, voffB); PG8_STAGE(PG8_SA(1, 0), a3, voffA);
;             PG8_WAIT_V(8); PG8_WAIT_L(0); PG8_BAR; PG8_MMA(1, 0, At, B0); PG8_MMA(1, 1, At, B1); PG8_BAR; PG8_SCHED;
;     __device__ __forceinline__ void operator()(AccRef acc, const pg8::Unit& u, int wr, int wc, int fr, int fq) const {
;         const int row0 = u.pm * 256 + wr * 64 + fr, col0 = u.pn * 256 + wc * 32 + 8 * fq;
; #pragma unroll
;         for (int ai = 0; ai < 2; ++ai)
; #pragma unroll
;             for (int m = 0; m < 4; ++m) {
;                 const int row = row0 + ai * 128 + m * 16; float ss = 0.f;
; #pragma unroll
;                 for (int bj = 0; bj < 2; ++bj) {
;                     bf16_t* xp = xb + (size_t)row * D + col0 + bj * 128;
;                     f32x4 a, b; unpack8(*(const u32x4*)xp, a, b);
;                     a += acc[ai][bj][m][0] * alpha; b += acc[ai][bj][m][1] * alpha;
;                     *(u32x4*)xp = pack8(a, b);
;                     ss += (a[0] * a[0] + a[1] * a[1]) + (a[2] * a[2] + a[3] * a[3]) + (b[0] * b[0] + b[1] * b[1]) + (b[2] * b[2] + b[3] * b[3]);
;                 }
	s_add_i32 s34, s68, s16
	v_lshl_add_u64 v[176:177], v[176:177], 0, s[22:23]
	s_mov_b32 m0, s34
	ds_read_b128 v[188:191], v161 offset:49152
	ds_read_b128 v[192:195], v161 offset:50176
	ds_read_b128 v[196:199], v161 offset:51200
	ds_read_b128 v[200:203], v161 offset:52224
	ds_read_b128 v[204:207], v161 offset:53248
	ds_read_b128 v[208:211], v161 offset:54272
	ds_read_b128 v[212:215], v161 offset:55296
	ds_read_b128 v[216:219], v161 offset:56320
	global_load_lds_dwordx4 v[176:177], off
	v_lshl_add_u64 v[176:177], v[178:179], 0, s[22:23]
	s_add_i32 m0, s34, 0x2000
	s_add_i32 s34, s69, s16
	global_load_lds_dwordx4 v[176:177], off
	v_lshl_add_u64 v[176:177], v[220:221], 0, s[22:23]
	s_mov_b32 m0, s34
	s_nop 0
	global_load_lds_dwordx4 v[176:177], off
	v_lshl_add_u64 v[176:177], v[222:223], 0, s[22:23]
	s_add_i32 m0, s34, 0x2000
	s_nop 0
	global_load_lds_dwordx4 v[176:177], off
	v_lshl_add_u64 v[176:177], v[224:225], 0, s[22:23]
	s_mov_b32 m0, s37
	s_nop 0
	global_load_lds_dwordx4 v[176:177], off
	v_lshl_add_u64 v[176:177], v[226:227], 0, s[22:23]
	s_mov_b32 m0, s38
	s_nop 0
	global_load_lds_dwordx4 v[176:177], off
	s_waitcnt vmcnt(8)
	s_waitcnt lgkmcnt(0)
	s_barrier
	s_setprio 1
	s_waitcnt lgkmcnt(0)
	v_mfma_f32_16x16x32_bf16 v[60:63], v[144:147], v[188:191], v[60:63]
	v_mfma_f32_16x16x32_bf16 v[56:59], v[152:155], v[188:191], v[56:59]
	v_mfma_f32_16x16x32_bf16 v[52:55], v[144:147], v[196:199], v[52:55]
	v_mfma_f32_16x16x32_bf16 v[48:51], v[152:155], v[196:199], v[48:51]
	v_mfma_f32_16x16x32_bf16 v[40:43], v[144:147], v[204:207], v[40:43]
	v_mfma_f32_16x16x32_bf16 v[32:35], v[152:155], v[204:207], v[32:35]
	v_mfma_f32_16x16x32_bf16 v[24:27], v[144:147], v[212:215], v[24:27]
	v_mfma_f32_16x16x32_bf16 v[16:19], v[152:155], v[212:215], v[16:19]
	v_mfma_f32_16x16x32_bf16 v[60:63], v[148:151], v[192:195], v[60:63]
	v_mfma_f32_16x16x32_bf16 v[56:59], v[164:167], v[192:195], v[56:59]
	v_mfma_f32_16x16x32_bf16 v[52:55], v[148:151], v[200:203], v[52:55]
	v_mfma_f32_16x16x32_bf16 v[48:51], v[164:167], v[200:203], v[48:51]
	v_mfma_f32_16x16x32_bf16 v[40:43], v[148:151], v[208:211], v[40:43]
	v_mfma_f32_16x16x32_bf16 v[32:35], v[164:167], v[208:211], v[32:35]
	v_mfma_f32_16x16x32_bf16 v[24:27], v[148:151], v[216:219], v[24:27]
	v_mfma_f32_16x16x32_bf16 v[16:19], v[164:167], v[216:219], v[16:19]
	s_setprio 0
	s_setprio 1
	v_mfma_f32_16x16x32_bf16 v[44:47], v[168:171], v[188:191], v[44:47]
	v_mfma_f32_16x16x32_bf16 v[36:39], v[180:183], v[188:191], v[36:39]
	v_mfma_f32_16x16x32_bf16 v[28:31], v[168:171], v[196:199], v[28:31]
	v_mfma_f32_16x16x32_bf16 v[20:23], v[180:183], v[196:199], v[20:23]
	v_mfma_f32_16x16x32_bf16 v[12:15], v[168:171], v[204:207], v[12:15]
	v_mfma_f32_16x16x32_bf16 v[8:11], v[180:183], v[204:207], v[8:11]
	v_mfma_f32_16x16x32_bf16 v[4:7], v[168:171], v[212:215], v[4:7]
	v_mfma_f32_16x16x32_bf16 v[0:3], v[180:183], v[212:215], v[0:3]
	v_mfma_f32_16x16x32_bf16 v[44:47], v[172:175], v[192:195], v[44:47]
	v_mfma_f32_16x16x32_bf16 v[36:39], v[184:187], v[192:195], v[36:39]
	v_mfma_f32_16x16x32_bf16 v[28:31], v[172:175], v[200:203], v[28:31]
	v_mfma_f32_16x16x32_bf16 v[20:23], v[184:187], v[200:203], v[20:23]
	v_mfma_f32_16x16x32_bf16 v[12:15], v[172:175], v[208:211], v[12:15]
	v_mfma_f32_16x16x32_bf16 v[8:11], v[184:187], v[208:211], v[8:11]
	v_mfma_f32_16x16x32_bf16 v[4:7], v[172:175], v[216:219], v[4:7]
	v_mfma_f32_16x16x32_bf16 v[0:3], v[184:187], v[216:219], v[0:3]
	s_setprio 0
	s_barrier
	s_add_u32 s30, s30, 0x100
	s_addc_u32 s31, s31, 0
	s_add_u32 s65, s65, 0x100
	s_addc_u32 s66, s66, 0
	s_cmp_ge_i32 s67, s40
	s_mov_b32 s34, s67
	s_cbranch_scc0 .LBB0_467
.LBB0_469:
	s_and_b64 vcc, exec, s[26:27]
	s_cbranch_vccz .LBB0_471
	s_barrier
.LBB0_471:
.Lres_beg0:
	v_lshl_add_u32 v170, s64, 8, v156
	v_lshl_or_b32 v169, s14, 8, v158
	v_lshlrev_b32_e32 v169, 1, v169
	v_lshl_add_u32 v168, v170, 11, v169
	v_add_u32_e32 v169, 0x18000, v168
	global_load_dwordx4 v[180:183], v169, s[42:43]
	global_load_dwordx4 v[184:187], v169, s[42:43] offset:256
	v_add_u32_e32 v169, 0x40000, v168
	global_load_dwordx4 v[188:191], v169, s[42:43]
	global_load_dwordx4 v[192:195], v169, s[42:43] offset:256
	v_add_u32_e32 v169, 0x48000, v168
	global_load_dwordx4 v[196:199], v169, s[42:43]
	global_load_dwordx4 v[200:203], v169, s[42:43] offset:256
	v_add_u32_e32 v169, 0x50000, v168
	global_load_dwordx4 v[204:207], v169, s[42:43]
	global_load_dwordx4 v[208:211], v169, s[42:43] offset:256
	v_bfe_u32 v171, v158, 5, 2
	v_lshl_add_u32 v171, s14, 2, v171
	v_lshlrev_b32_e32 v171, 2, v171
	v_lshl_add_u32 v170, v170, 6, v171
	v_add_u32_e32 v173, 0x2000, v170
	v_mbcnt_lo_u32_b32 v172, -1, 0
	v_mbcnt_hi_u32_b32 v172, -1, v172
	v_xor_b32_e32 v171, 16, v172
	v_xor_b32_e32 v172, 32, v172
	v_lshlrev_b32_e32 v171, 2, v171
	v_lshlrev_b32_e32 v172, 2, v172
	v_mov_b32_e32 v169, v168
	s_waitcnt vmcnt(8)
;     __device__ __forceinline__ void operator()(AccRef acc, const pg8::Unit& u, int wr, int wc, int fr, int fq) const {
;     ...
;                 const int row = row0 + ai * 128 + m * 16; float ss = 0.f;
; #pragma unroll
;                 for (int bj = 0; bj < 2; ++bj) {
;                     bf16_t* xp = xb + (size_t)row * D + col0 + bj * 128;
;                     f32x4 a, b; unpack8(*(const u32x4*)xp, a, b);
;                     a += acc[ai][bj][m][0] * alpha; b += acc[ai][bj][m][1] * alpha;
;                     *(u32x4*)xp = pack8(a, b);
;                     ss += (a[0] * a[0] + a[1] * a[1]) + (a[2] * a[2] + a[3] * a[3]) + (b[0] * b[0] + b[1] * b[1]) + (b[2] * b[2] + b[3] * b[3]);
;                 }
	v_pk_mul_f32 v[124:125], v[124:125], 0.5 op_sel_hi:[1,0]
	v_pk_mul_f32 v[126:127], v[126:127], 0.5 op_sel_hi:[1,0]
	v_pk_mul_f32 v[120:121], v[120:121], 0.5 op_sel_hi:[1,0]
	v_pk_mul_f32 v[122:123], v[122:123], 0.5 op_sel_hi:[1,0]
	v_lshlrev_b32_e32 v212, 16, v231
	v_and_b32_e32 v213, 0xffff0000, v231
	v_and_b32_e32 v231, 0xffff0000, v230
	v_lshlrev_b32_e32 v230, 16, v230
	v_lshlrev_b32_e32 v214, 16, v233
	v_and_b32_e32 v215, 0xffff0000, v233
	v_and_b32_e32 v233, 0xffff0000, v232
	v_lshlrev_b32_e32 v232, 16, v232
	v_pk_add_f32 v[230:231], v[124:125], v[230:231]
	v_pk_add_f32 v[212:213], v[126:127], v[212:213]
	v_pk_add_f32 v[232:233], v[120:121], v[232:233]
	v_pk_add_f32 v[214:215], v[122:123], v[214:215]
	v_cvt_pk_bf16_f32 v124, v230, v231
	v_cvt_pk_bf16_f32 v125, v212, v213
	v_cvt_pk_bf16_f32 v126, v232, v233
	v_cvt_pk_bf16_f32 v127, v214, v215
	global_store_dwordx4 v169, v[124:127], s[42:43]
	v_mul_f32_e32 v120, v231, v231
	v_mul_f32_e32 v121, v213, v213
	v_mul_f32_e32 v122, v233, v233
	v_mul_f32_e32 v123, v215, v215
	v_fmac_f32_e32 v120, v230, v230
	v_fmac_f32_e32 v121, v212, v212
	v_fmac_f32_e32 v122, v232, v232
	v_fmac_f32_e32 v123, v214, v214
	v_add_f32_e32 v120, v120, v121
	v_add_f32_e32 v120, v122, v120
	v_add_f32_e32 v120, v123, v120
	s_nop 0
	v_pk_mul_f32 v[108:109], v[108:109], 0.5 op_sel_hi:[1,0]
	v_pk_mul_f32 v[110:111], v[110:111], 0.5 op_sel_hi:[1,0]
	v_pk_mul_f32 v[100:101], v[100:101], 0.5 op_sel_hi:[1,0]
	v_pk_mul_f32 v[102:103], v[102:103], 0.5 op_sel_hi:[1,0]
	v_lshlrev_b32_e32 v212, 16, v235
	v_and_b32_e32 v213, 0xffff0000, v235
	v_and_b32_e32 v235, 0xffff0000, v234
	v_lshlrev_b32_e32 v234, 16, v234
	v_lshlrev_b32_e32 v214, 16, v237
	v_and_b32_e32 v215, 0xffff0000, v237
	v_and_b32_e32 v237, 0xffff0000, v236
	v_lshlrev_b32_e32 v236, 16, v236
	v_pk_add_f32 v[234:235], v[108:109], v[234:235]
	v_pk_add_f32 v[212:213], v[110:111], v[212:213]
	v_pk_add_f32 v[236:237], v[100:101], v[236:237]
	v_pk_add_f32 v[214:215], v[102:103], v[214:215]
	v_cvt_pk_bf16_f32 v108, v234, v235
	v_cvt_pk_bf16_f32 v109, v212, v213
	v_cvt_pk_bf16_f32 v110, v236, v237
	v_cvt_pk_bf16_f32 v111, v214, v215
	global_store_dwordx4 v169, v[108:111], s[42:43] offset:256
	v_mul_f32_e32 v100, v235, v235
	v_mul_f32_e32 v101, v213, v213
	v_mul_f32_e32 v102, v237, v237
	v_mul_f32_e32 v103, v215, v215
	v_fmac_f32_e32 v100, v234, v234
	v_fmac_f32_e32 v101, v212, v212
	v_fmac_f32_e32 v102, v236, v236
	v_fmac_f32_e32 v103, v214, v214
	v_add_f32_e32 v100, v100, v101
	v_add_f32_e32 v100, v102, v100
	v_add_f32_e32 v100, v103, v100
	v_add_f32_e32 v120, v120, v100
	v_add_u32_e32 v169, 0x58000, v168
	global_load_dwordx4 v[230:233], v169, s[42:43]
	global_load_dwordx4 v[234:237], v169, s[42:43] offset:256
	v_add_u32_e32 v169, 0x8000, v168
	s_nop 0
	v_pk_mul_f32 v[116:117], v[116:117], 0.5 op_sel_hi:[1,0]
	v_pk_mul_f32 v[118:119], v[118:119], 0.5 op_sel_hi:[1,0]
	v_pk_mul_f32 v[112:113], v[112:113], 0.5 op_sel_hi:[1,0]
	v_pk_mul_f32 v[114:115], v[114:115], 0.5 op_sel_hi:[1,0]
	v_lshlrev_b32_e32 v212, 16, v239
	v_and_b32_e32 v213, 0xffff0000, v239
	v_and_b32_e32 v239, 0xffff0000, v238
	v_lshlrev_b32_e32 v238, 16, v238
	v_lshlrev_b32_e32 v214, 16, v241
	v_and_b32_e32 v215, 0xffff0000, v241
	v_and_b32_e32 v241, 0xffff0000, v240
	v_lshlrev_b32_e32 v240, 16, v240
	v_pk_add_f32 v[238:239], v[116:117], v[238:239]
	v_pk_add_f32 v[212:213], v[118:119], v[212:213]
	v_pk_add_f32 v[240:241], v[112:113], v[240:241]
	v_pk_add_f32 v[214:215], v[114:115], v[214:215]
	v_cvt_pk_bf16_f32 v116, v238, v239
	v_cvt_pk_bf16_f32 v117, v212, v213
	v_cvt_pk_bf16_f32 v118, v240, v241
	v_cvt_pk_bf16_f32 v119, v214, v215
	global_store_dwordx4 v169, v[116:119], s[42:43]
	v_mul_f32_e32 v112, v239, v239
	v_mul_f32_e32 v113, v213, v213
	v_mul_f32_e32 v114, v241, v241
	v_mul_f32_e32 v115, v215, v215
	v_fmac_f32_e32 v112, v238, v238
	v_fmac_f32_e32 v113, v212, v212
	v_fmac_f32_e32 v114, v240, v240
	v_fmac_f32_e32 v115, v214, v214
	v_add_f32_e32 v112, v112, v113
	v_add_f32_e32 v112, v114, v112
	v_add_f32_e32 v112, v115, v112
	s_nop 0
	v_pk_mul_f32 v[92:93], v[92:93], 0.5 op_sel_hi:[1,0]
	v_pk_mul_f32 v[94:95], v[94:95], 0.5 op_sel_hi:[1,0]
	v_pk_mul_f32 v[84:85], v[84:85], 0.5 op_sel_hi:[1,0]
	v_pk_mul_f32 v[86:87], v[86:87], 0.5 op_sel_hi:[1,0]
	v_lshlrev_b32_e32 v212, 16, v243
	v_and_b32_e32 v213, 0xffff0000, v243
	v_and_b32_e32 v243, 0xffff0000, v242
	v_lshlrev_b32_e32 v242, 16, v242
	v_lshlrev_b32_e32 v214, 16, v245
	v_and_b32_e32 v215, 0xffff0000, v245
	v_and_b32_e32 v245, 0xffff0000, v244
	v_lshlrev_b32_e32 v244, 16, v244
	v_pk_add_f32 v[242:243], v[92:93], v[242:243]
	v_pk_add_f32 v[212:213], v[94:95], v[212:213]
	v_pk_add_f32 v[244:245], v[84:85], v[244:245]
	v_pk_add_f32 v[214:215], v[86:87], v[214:215]
	v_cvt_pk_bf16_f32 v92, v242, v243
	v_cvt_pk_bf16_f32 v93, v212, v213
	v_cvt_pk_bf16_f32 v94, v244, v245
	v_cvt_pk_bf16_f32 v95, v214, v215
	global_store_dwordx4 v169, v[92:95], s[42:43] offset:256
	v_mul_f32_e32 v84, v243, v243
	v_mul_f32_e32 v85, v213, v213
	v_mul_f32_e32 v86, v245, v245
	v_mul_f32_e32 v87, v215, v215
	v_fmac_f32_e32 v84, v242, v242
	v_fmac_f32_e32 v85, v212, v212
	v_fmac_f32_e32 v86, v244, v244
	v_fmac_f32_e32 v87, v214, v214
	v_add_f32_e32 v84, v84, v85
	v_add_f32_e32 v84, v86, v84
	v_add_f32_e32 v84, v87, v84
	v_add_f32_e32 v112, v112, v84
	v_add_u32_e32 v169, 0x10000, v168
	s_nop 0
	v_pk_mul_f32 v[104:105], v[104:105], 0.5 op_sel_hi:[1,0]
	v_pk_mul_f32 v[106:107], v[106:107], 0.5 op_sel_hi:[1,0]
	v_pk_mul_f32 v[96:97], v[96:97], 0.5 op_sel_hi:[1,0]
	v_pk_mul_f32 v[98:99], v[98:99], 0.5 op_sel_hi:[1,0]
	v_lshlrev_b32_e32 v212, 16, v247
	v_and_b32_e32 v213, 0xffff0000, v247
;     __device__ __forceinline__ void operator()(AccRef acc, const pg8::Unit& u, int wr, int wc, int fr, int fq) const {
;     ...
;                 const int row = row0 + ai * 128 + m * 16; float ss = 0.f;
; #pragma unroll
;                 for (int bj = 0; bj < 2; ++bj) {
;                     bf16_t* xp = xb + (size_t)row * D + col0 + bj * 128;
;                     f32x4 a, b; unpack8(*(const u32x4*)xp, a, b);
;                     a += acc[ai][bj][m][0] * alpha; b += acc[ai][bj][m][1] * alpha;
;                     *(u32x4*)xp = pack8(a, b);
;                     ss += (a[0] * a[0] + a[1] * a[1]) + (a[2] * a[2] + a[3] * a[3]) + (b[0] * b[0] + b[1] * b[1]) + (b[2] * b[2] + b[3] * b[3]);
;                 }
	v_and_b32_e32 v247, 0xffff0000, v246
	v_lshlrev_b32_e32 v246, 16, v246
	v_lshlrev_b32_e32 v214, 16, v249
	v_and_b32_e32 v215, 0xffff0000, v249
	v_and_b32_e32 v249, 0xffff0000, v248
	v_lshlrev_b32_e32 v248, 16, v248
	v_pk_add_f32 v[246:247], v[104:105], v[246:247]
	v_pk_add_f32 v[212:213], v[106:107], v[212:213]
	v_pk_add_f32 v[248:249], v[96:97], v[248:249]
	v_pk_add_f32 v[214:215], v[98:99], v[214:215]
	v_cvt_pk_bf16_f32 v104, v246, v247
	v_cvt_pk_bf16_f32 v105, v212, v213
	v_cvt_pk_bf16_f32 v106, v248, v249
	v_cvt_pk_bf16_f32 v107, v214, v215
	global_store_dwordx4 v169, v[104:107], s[42:43]
	v_mul_f32_e32 v96, v247, v247
	v_mul_f32_e32 v97, v213, v213
	v_mul_f32_e32 v98, v249, v249
	v_mul_f32_e32 v99, v215, v215
	v_fmac_f32_e32 v96, v246, v246
	v_fmac_f32_e32 v97, v212, v212
	v_fmac_f32_e32 v98, v248, v248
	v_fmac_f32_e32 v99, v214, v214
	v_add_f32_e32 v96, v96, v97
	v_add_f32_e32 v96, v98, v96
	v_add_f32_e32 v96, v99, v96
	s_nop 0
	v_pk_mul_f32 v[76:77], v[76:77], 0.5 op_sel_hi:[1,0]
	v_pk_mul_f32 v[78:79], v[78:79], 0.5 op_sel_hi:[1,0]
	v_pk_mul_f32 v[72:73], v[72:73], 0.5 op_sel_hi:[1,0]
	v_pk_mul_f32 v[74:75], v[74:75], 0.5 op_sel_hi:[1,0]
	v_lshlrev_b32_e32 v212, 16, v251
	v_and_b32_e32 v213, 0xffff0000, v251
	v_and_b32_e32 v251, 0xffff0000, v250
	v_lshlrev_b32_e32 v250, 16, v250
	v_lshlrev_b32_e32 v214, 16, v253
	v_and_b32_e32 v215, 0xffff0000, v253
	v_and_b32_e32 v253, 0xffff0000, v252
	v_lshlrev_b32_e32 v252, 16, v252
	v_pk_add_f32 v[250:251], v[76:77], v[250:251]
	v_pk_add_f32 v[212:213], v[78:79], v[212:213]
	v_pk_add_f32 v[252:253], v[72:73], v[252:253]
	v_pk_add_f32 v[214:215], v[74:75], v[214:215]
	v_cvt_pk_bf16_f32 v76, v250, v251
	v_cvt_pk_bf16_f32 v77, v212, v213
	v_cvt_pk_bf16_f32 v78, v252, v253
	v_cvt_pk_bf16_f32 v79, v214, v215
	global_store_dwordx4 v169, v[76:79], s[42:43] offset:256
	v_mul_f32_e32 v72, v251, v251
	v_mul_f32_e32 v73, v213, v213
	v_mul_f32_e32 v74, v253, v253
	v_mul_f32_e32 v75, v215, v215
	v_fmac_f32_e32 v72, v250, v250
	v_fmac_f32_e32 v73, v212, v212
	v_fmac_f32_e32 v74, v252, v252
	v_fmac_f32_e32 v75, v214, v214
	v_add_f32_e32 v72, v72, v73
	v_add_f32_e32 v72, v74, v72
	v_add_f32_e32 v72, v75, v72
	v_add_f32_e32 v96, v96, v72
	v_add_u32_e32 v169, 0x18000, v168
	s_waitcnt vmcnt(15)
	v_pk_mul_f32 v[88:89], v[88:89], 0.5 op_sel_hi:[1,0]
	v_pk_mul_f32 v[90:91], v[90:91], 0.5 op_sel_hi:[1,0]
	v_pk_mul_f32 v[80:81], v[80:81], 0.5 op_sel_hi:[1,0]
	v_pk_mul_f32 v[82:83], v[82:83], 0.5 op_sel_hi:[1,0]
	v_lshlrev_b32_e32 v212, 16, v181
	v_and_b32_e32 v213, 0xffff0000, v181
	v_and_b32_e32 v181, 0xffff0000, v180
	v_lshlrev_b32_e32 v180, 16, v180
	v_lshlrev_b32_e32 v214, 16, v183
	v_and_b32_e32 v215, 0xffff0000, v183
	v_and_b32_e32 v183, 0xffff0000, v182
	v_lshlrev_b32_e32 v182, 16, v182
	v_pk_add_f32 v[180:181], v[88:89], v[180:181]
	v_pk_add_f32 v[212:213], v[90:91], v[212:213]
	v_pk_add_f32 v[182:183], v[80:81], v[182:183]
	v_pk_add_f32 v[214:215], v[82:83], v[214:215]
	v_cvt_pk_bf16_f32 v88, v180, v181
	v_cvt_pk_bf16_f32 v89, v212, v213
	v_cvt_pk_bf16_f32 v90, v182, v183
	v_cvt_pk_bf16_f32 v91, v214, v215
	global_store_dwordx4 v169, v[88:91], s[42:43]
	v_mul_f32_e32 v80, v181, v181
	v_mul_f32_e32 v81, v213, v213
	v_mul_f32_e32 v82, v183, v183
	v_mul_f32_e32 v83, v215, v215
	v_fmac_f32_e32 v80, v180, v180
	v_fmac_f32_e32 v81, v212, v212
	v_fmac_f32_e32 v82, v182, v182
	v_fmac_f32_e32 v83, v214, v214
	v_add_f32_e32 v80, v80, v81
	v_add_f32_e32 v80, v82, v80
	v_add_f32_e32 v80, v83, v80
	s_waitcnt vmcnt(15)
	v_pk_mul_f32 v[68:69], v[68:69], 0.5 op_sel_hi:[1,0]
	v_pk_mul_f32 v[70:71], v[70:71], 0.5 op_sel_hi:[1,0]
	v_pk_mul_f32 v[64:65], v[64:65], 0.5 op_sel_hi:[1,0]
	v_pk_mul_f32 v[66:67], v[66:67], 0.5 op_sel_hi:[1,0]
	v_lshlrev_b32_e32 v212, 16, v185
	v_and_b32_e32 v213, 0xffff0000, v185
	v_and_b32_e32 v185, 0xffff0000, v184
	v_lshlrev_b32_e32 v184, 16, v184
	v_lshlrev_b32_e32 v214, 16, v187
	v_and_b32_e32 v215, 0xffff0000, v187
	v_and_b32_e32 v187, 0xffff0000, v186
	v_lshlrev_b32_e32 v186, 16, v186
	v_pk_add_f32 v[184:185], v[68:69], v[184:185]
	v_pk_add_f32 v[212:213], v[70:71], v[212:213]
	v_pk_add_f32 v[186:187], v[64:65], v[186:187]
	v_pk_add_f32 v[214:215], v[66:67], v[214:215]
	v_cvt_pk_bf16_f32 v68, v184, v185
	v_cvt_pk_bf16_f32 v69, v212, v213
	v_cvt_pk_bf16_f32 v70, v186, v187
	v_cvt_pk_bf16_f32 v71, v214, v215
	global_store_dwordx4 v169, v[68:71], s[42:43] offset:256
	v_mul_f32_e32 v64, v185, v185
	v_mul_f32_e32 v65, v213, v213
	v_mul_f32_e32 v66, v187, v187
	v_mul_f32_e32 v67, v215, v215
	v_fmac_f32_e32 v64, v184, v184
	v_fmac_f32_e32 v65, v212, v212
	v_fmac_f32_e32 v66, v186, v186
	v_fmac_f32_e32 v67, v214, v214
	v_add_f32_e32 v64, v64, v65
	v_add_f32_e32 v64, v66, v64
	v_add_f32_e32 v64, v67, v64
	v_add_f32_e32 v80, v80, v64
	v_add_u32_e32 v169, 0x40000, v168
	s_waitcnt vmcnt(15)
	v_pk_mul_f32 v[60:61], v[60:61], 0.5 op_sel_hi:[1,0]
	v_pk_mul_f32 v[62:63], v[62:63], 0.5 op_sel_hi:[1,0]
	v_pk_mul_f32 v[56:57], v[56:57], 0.5 op_sel_hi:[1,0]
	v_pk_mul_f32 v[58:59], v[58:59], 0.5 op_sel_hi:[1,0]
	v_lshlrev_b32_e32 v212, 16, v189
	v_and_b32_e32 v213, 0xffff0000, v189
	v_and_b32_e32 v189, 0xffff0000, v188
	v_lshlrev_b32_e32 v188, 16, v188
	v_lshlrev_b32_e32 v214, 16, v191
	v_and_b32_e32 v215, 0xffff0000, v191
	v_and_b32_e32 v191, 0xffff0000, v190
	v_lshlrev_b32_e32 v190, 16, v190
	v_pk_add_f32 v[188:189], v[60:61], v[188:189]
	v_pk_add_f32 v[212:213], v[62:63], v[212:213]
	v_pk_add_f32 v[190:191], v[56:57], v[190:191]
	v_pk_add_f32 v[214:215], v[58:59], v[214:215]
	v_cvt_pk_bf16_f32 v60, v188, v189
	v_cvt_pk_bf16_f32 v61, v212, v213
	v_cvt_pk_bf16_f32 v62, v190, v191
	v_cvt_pk_bf16_f32 v63, v214, v215
	global_store_dwordx4 v169, v[60:63], s[42:43]
	v_mul_f32_e32 v56, v189, v189
	v_mul_f32_e32 v57, v213, v213
	v_mul_f32_e32 v58, v191, v191
	v_mul_f32_e32 v59, v215, v215
	v_fmac_f32_e32 v56, v188, v188
	v_fmac_f32_e32 v57, v212, v212
	v_fmac_f32_e32 v58, v190, v190
	v_fmac_f32_e32 v59, v214, v214
	v_add_f32_e32 v56, v56, v57
	v_add_f32_e32 v56, v58, v56
	v_add_f32_e32 v56, v59, v56
	s_waitcnt vmcnt(15)
;     __device__ __forceinline__ void operator()(AccRef acc, const pg8::Unit& u, int wr, int wc, int fr, int fq) const {
;     ...
;                 const int row = row0 + ai * 128 + m * 16; float ss = 0.f;
; #pragma unroll
;                 for (int bj = 0; bj < 2; ++bj) {
;                     bf16_t* xp = xb + (size_t)row * D + col0 + bj * 128;
;                     f32x4 a, b; unpack8(*(const u32x4*)xp, a, b);
;                     a += acc[ai][bj][m][0] * alpha; b += acc[ai][bj][m][1] * alpha;
;                     *(u32x4*)xp = pack8(a, b);
;                     ss += (a[0] * a[0] + a[1] * a[1]) + (a[2] * a[2] + a[3] * a[3]) + (b[0] * b[0] + b[1] * b[1]) + (b[2] * b[2] + b[3] * b[3]);
;                 }
	v_pk_mul_f32 v[44:45], v[44:45], 0.5 op_sel_hi:[1,0]
	v_pk_mul_f32 v[46:47], v[46:47], 0.5 op_sel_hi:[1,0]
	v_pk_mul_f32 v[36:37], v[36:37], 0.5 op_sel_hi:[1,0]
	v_pk_mul_f32 v[38:39], v[38:39], 0.5 op_sel_hi:[1,0]
	v_lshlrev_b32_e32 v212, 16, v193
	v_and_b32_e32 v213, 0xffff0000, v193
	v_and_b32_e32 v193, 0xffff0000, v192
	v_lshlrev_b32_e32 v192, 16, v192
	v_lshlrev_b32_e32 v214, 16, v195
	v_and_b32_e32 v215, 0xffff0000, v195
	v_and_b32_e32 v195, 0xffff0000, v194
	v_lshlrev_b32_e32 v194, 16, v194
	v_pk_add_f32 v[192:193], v[44:45], v[192:193]
	v_pk_add_f32 v[212:213], v[46:47], v[212:213]
	v_pk_add_f32 v[194:195], v[36:37], v[194:195]
	v_pk_add_f32 v[214:215], v[38:39], v[214:215]
	v_cvt_pk_bf16_f32 v44, v192, v193
	v_cvt_pk_bf16_f32 v45, v212, v213
	v_cvt_pk_bf16_f32 v46, v194, v195
	v_cvt_pk_bf16_f32 v47, v214, v215
	global_store_dwordx4 v169, v[44:47], s[42:43] offset:256
	v_mul_f32_e32 v36, v193, v193
	v_mul_f32_e32 v37, v213, v213
	v_mul_f32_e32 v38, v195, v195
	v_mul_f32_e32 v39, v215, v215
	v_fmac_f32_e32 v36, v192, v192
	v_fmac_f32_e32 v37, v212, v212
	v_fmac_f32_e32 v38, v194, v194
	v_fmac_f32_e32 v39, v214, v214
	v_add_f32_e32 v36, v36, v37
	v_add_f32_e32 v36, v38, v36
	v_add_f32_e32 v36, v39, v36
	v_add_f32_e32 v56, v56, v36
	v_add_u32_e32 v169, 0x48000, v168
	s_waitcnt vmcnt(15)
	v_pk_mul_f32 v[52:53], v[52:53], 0.5 op_sel_hi:[1,0]
	v_pk_mul_f32 v[54:55], v[54:55], 0.5 op_sel_hi:[1,0]
	v_pk_mul_f32 v[48:49], v[48:49], 0.5 op_sel_hi:[1,0]
	v_pk_mul_f32 v[50:51], v[50:51], 0.5 op_sel_hi:[1,0]
	v_lshlrev_b32_e32 v212, 16, v197
	v_and_b32_e32 v213, 0xffff0000, v197
	v_and_b32_e32 v197, 0xffff0000, v196
	v_lshlrev_b32_e32 v196, 16, v196
	v_lshlrev_b32_e32 v214, 16, v199
	v_and_b32_e32 v215, 0xffff0000, v199
	v_and_b32_e32 v199, 0xffff0000, v198
	v_lshlrev_b32_e32 v198, 16, v198
	v_pk_add_f32 v[196:197], v[52:53], v[196:197]
	v_pk_add_f32 v[212:213], v[54:55], v[212:213]
	v_pk_add_f32 v[198:199], v[48:49], v[198:199]
	v_pk_add_f32 v[214:215], v[50:51], v[214:215]
	v_cvt_pk_bf16_f32 v52, v196, v197
	v_cvt_pk_bf16_f32 v53, v212, v213
	v_cvt_pk_bf16_f32 v54, v198, v199
	v_cvt_pk_bf16_f32 v55, v214, v215
	global_store_dwordx4 v169, v[52:55], s[42:43]
	v_mul_f32_e32 v48, v197, v197
	v_mul_f32_e32 v49, v213, v213
	v_mul_f32_e32 v50, v199, v199
	v_mul_f32_e32 v51, v215, v215
	v_fmac_f32_e32 v48, v196, v196
	v_fmac_f32_e32 v49, v212, v212
	v_fmac_f32_e32 v50, v198, v198
	v_fmac_f32_e32 v51, v214, v214
	v_add_f32_e32 v48, v48, v49
	v_add_f32_e32 v48, v50, v48
	v_add_f32_e32 v48, v51, v48
	s_waitcnt vmcnt(15)
	v_pk_mul_f32 v[28:29], v[28:29], 0.5 op_sel_hi:[1,0]
	v_pk_mul_f32 v[30:31], v[30:31], 0.5 op_sel_hi:[1,0]
	v_pk_mul_f32 v[20:21], v[20:21], 0.5 op_sel_hi:[1,0]
	v_pk_mul_f32 v[22:23], v[22:23], 0.5 op_sel_hi:[1,0]
	v_lshlrev_b32_e32 v212, 16, v201
	v_and_b32_e32 v213, 0xffff0000, v201
	v_and_b32_e32 v201, 0xffff0000, v200
	v_lshlrev_b32_e32 v200, 16, v200
	v_lshlrev_b32_e32 v214, 16, v203
	v_and_b32_e32 v215, 0xffff0000, v203
	v_and_b32_e32 v203, 0xffff0000, v202
	v_lshlrev_b32_e32 v202, 16, v202
	v_pk_add_f32 v[200:201], v[28:29], v[200:201]
	v_pk_add_f32 v[212:213], v[30:31], v[212:213]
	v_pk_add_f32 v[202:203], v[20:21], v[202:203]
	v_pk_add_f32 v[214:215], v[22:23], v[214:215]
	v_cvt_pk_bf16_f32 v28, v200, v201
	v_cvt_pk_bf16_f32 v29, v212, v213
	v_cvt_pk_bf16_f32 v30, v202, v203
	v_cvt_pk_bf16_f32 v31, v214, v215
	global_store_dwordx4 v169, v[28:31], s[42:43] offset:256
	v_mul_f32_e32 v20, v201, v201
	v_mul_f32_e32 v21, v213, v213
	v_mul_f32_e32 v22, v203, v203
	v_mul_f32_e32 v23, v215, v215
	v_fmac_f32_e32 v20, v200, v200
	v_fmac_f32_e32 v21, v212, v212
	v_fmac_f32_e32 v22, v202, v202
	v_fmac_f32_e32 v23, v214, v214
	v_add_f32_e32 v20, v20, v21
	v_add_f32_e32 v20, v22, v20
	v_add_f32_e32 v20, v23, v20
	v_add_f32_e32 v48, v48, v20
	v_add_u32_e32 v169, 0x50000, v168
	s_waitcnt vmcnt(15)
	v_pk_mul_f32 v[40:41], v[40:41], 0.5 op_sel_hi:[1,0]
	v_pk_mul_f32 v[42:43], v[42:43], 0.5 op_sel_hi:[1,0]
	v_pk_mul_f32 v[32:33], v[32:33], 0.5 op_sel_hi:[1,0]
	v_pk_mul_f32 v[34:35], v[34:35], 0.5 op_sel_hi:[1,0]
	v_lshlrev_b32_e32 v212, 16, v205
	v_and_b32_e32 v213, 0xffff0000, v205
	v_and_b32_e32 v205, 0xffff0000, v204
	v_lshlrev_b32_e32 v204, 16, v204
	v_lshlrev_b32_e32 v214, 16, v207
	v_and_b32_e32 v215, 0xffff0000, v207
	v_and_b32_e32 v207, 0xffff0000, v206
	v_lshlrev_b32_e32 v206, 16, v206
	v_pk_add_f32 v[204:205], v[40:41], v[204:205]
	v_pk_add_f32 v[212:213], v[42:43], v[212:213]
	v_pk_add_f32 v[206:207], v[32:33], v[206:207]
	v_pk_add_f32 v[214:215], v[34:35], v[214:215]
	v_cvt_pk_bf16_f32 v40, v204, v205
	v_cvt_pk_bf16_f32 v41, v212, v213
	v_cvt_pk_bf16_f32 v42, v206, v207
	v_cvt_pk_bf16_f32 v43, v214, v215
	global_store_dwordx4 v169, v[40:43], s[42:43]
	v_mul_f32_e32 v32, v205, v205
	v_mul_f32_e32 v33, v213, v213
	v_mul_f32_e32 v34, v207, v207
	v_mul_f32_e32 v35, v215, v215
	v_fmac_f32_e32 v32, v204, v204
	v_fmac_f32_e32 v33, v212, v212
	v_fmac_f32_e32 v34, v206, v206
	v_fmac_f32_e32 v35, v214, v214
	v_add_f32_e32 v32, v32, v33
	v_add_f32_e32 v32, v34, v32
	v_add_f32_e32 v32, v35, v32
	s_waitcnt vmcnt(15)
;     __device__ __forceinline__ void operator()(AccRef acc, const pg8::Unit& u, int wr, int wc, int fr, int fq) const {
;     ...
;                 const int row = row0 + ai * 128 + m * 16; float ss = 0.f;
; #pragma unroll
;                 for (int bj = 0; bj < 2; ++bj) {
;                     bf16_t* xp = xb + (size_t)row * D + col0 + bj * 128;
;                     f32x4 a, b; unpack8(*(const u32x4*)xp, a, b);
;                     a += acc[ai][bj][m][0] * alpha; b += acc[ai][bj][m][1] * alpha;
;                     *(u32x4*)xp = pack8(a, b);
;                     ss += (a[0] * a[0] + a[1] * a[1]) + (a[2] * a[2] + a[3] * a[3]) + (b[0] * b[0] + b[1] * b[1]) + (b[2] * b[2] + b[3] * b[3]);
;                 }
;                 ss += __shfl_xor(ss, 16); ss += __shfl_xor(ss, 32);
;                 if (fq == 0) ssp[(size_t)row * 16 + u.pn * 4 + wc] = ss;
;             }
	v_pk_mul_f32 v[12:13], v[12:13], 0.5 op_sel_hi:[1,0]
	v_pk_mul_f32 v[14:15], v[14:15], 0.5 op_sel_hi:[1,0]
	v_pk_mul_f32 v[8:9], v[8:9], 0.5 op_sel_hi:[1,0]
	v_pk_mul_f32 v[10:11], v[10:11], 0.5 op_sel_hi:[1,0]
	v_lshlrev_b32_e32 v212, 16, v209
	v_and_b32_e32 v213, 0xffff0000, v209
	v_and_b32_e32 v209, 0xffff0000, v208
	v_lshlrev_b32_e32 v208, 16, v208
	v_lshlrev_b32_e32 v214, 16, v211
	v_and_b32_e32 v215, 0xffff0000, v211
	v_and_b32_e32 v211, 0xffff0000, v210
	v_lshlrev_b32_e32 v210, 16, v210
	v_pk_add_f32 v[208:209], v[12:13], v[208:209]
	v_pk_add_f32 v[212:213], v[14:15], v[212:213]
	v_pk_add_f32 v[210:211], v[8:9], v[210:211]
	v_pk_add_f32 v[214:215], v[10:11], v[214:215]
	v_cvt_pk_bf16_f32 v12, v208, v209
	v_cvt_pk_bf16_f32 v13, v212, v213
	v_cvt_pk_bf16_f32 v14, v210, v211
	v_cvt_pk_bf16_f32 v15, v214, v215
	global_store_dwordx4 v169, v[12:15], s[42:43] offset:256
	v_mul_f32_e32 v8, v209, v209
	v_mul_f32_e32 v9, v213, v213
	v_mul_f32_e32 v10, v211, v211
	v_mul_f32_e32 v11, v215, v215
	v_fmac_f32_e32 v8, v208, v208
	v_fmac_f32_e32 v9, v212, v212
	v_fmac_f32_e32 v10, v210, v210
	v_fmac_f32_e32 v11, v214, v214
	v_add_f32_e32 v8, v8, v9
	v_add_f32_e32 v8, v10, v8
	v_add_f32_e32 v8, v11, v8
	v_add_f32_e32 v32, v32, v8
	v_add_u32_e32 v169, 0x58000, v168
	s_waitcnt vmcnt(13)
	v_pk_mul_f32 v[24:25], v[24:25], 0.5 op_sel_hi:[1,0]
	v_pk_mul_f32 v[26:27], v[26:27], 0.5 op_sel_hi:[1,0]
	v_pk_mul_f32 v[16:17], v[16:17], 0.5 op_sel_hi:[1,0]
	v_pk_mul_f32 v[18:19], v[18:19], 0.5 op_sel_hi:[1,0]
	v_lshlrev_b32_e32 v212, 16, v231
	v_and_b32_e32 v213, 0xffff0000, v231
	v_and_b32_e32 v231, 0xffff0000, v230
	v_lshlrev_b32_e32 v230, 16, v230
	v_lshlrev_b32_e32 v214, 16, v233
	v_and_b32_e32 v215, 0xffff0000, v233
	v_and_b32_e32 v233, 0xffff0000, v232
	v_lshlrev_b32_e32 v232, 16, v232
	v_pk_add_f32 v[230:231], v[24:25], v[230:231]
	v_pk_add_f32 v[212:213], v[26:27], v[212:213]
	v_pk_add_f32 v[232:233], v[16:17], v[232:233]
	v_pk_add_f32 v[214:215], v[18:19], v[214:215]
	v_cvt_pk_bf16_f32 v24, v230, v231
	v_cvt_pk_bf16_f32 v25, v212, v213
	v_cvt_pk_bf16_f32 v26, v232, v233
	v_cvt_pk_bf16_f32 v27, v214, v215
	global_store_dwordx4 v169, v[24:27], s[42:43]
	v_mul_f32_e32 v16, v231, v231
	v_mul_f32_e32 v17, v213, v213
	v_mul_f32_e32 v18, v233, v233
	v_mul_f32_e32 v19, v215, v215
	v_fmac_f32_e32 v16, v230, v230
	v_fmac_f32_e32 v17, v212, v212
	v_fmac_f32_e32 v18, v232, v232
	v_fmac_f32_e32 v19, v214, v214
	v_add_f32_e32 v16, v16, v17
	v_add_f32_e32 v16, v18, v16
	v_add_f32_e32 v16, v19, v16
	s_waitcnt vmcnt(13)
	v_pk_mul_f32 v[4:5], v[4:5], 0.5 op_sel_hi:[1,0]
	v_pk_mul_f32 v[6:7], v[6:7], 0.5 op_sel_hi:[1,0]
	v_pk_mul_f32 v[0:1], v[0:1], 0.5 op_sel_hi:[1,0]
	v_pk_mul_f32 v[2:3], v[2:3], 0.5 op_sel_hi:[1,0]
	v_lshlrev_b32_e32 v212, 16, v235
	v_and_b32_e32 v213, 0xffff0000, v235
	v_and_b32_e32 v235, 0xffff0000, v234
	v_lshlrev_b32_e32 v234, 16, v234
	v_lshlrev_b32_e32 v214, 16, v237
	v_and_b32_e32 v215, 0xffff0000, v237
	v_and_b32_e32 v237, 0xffff0000, v236
	v_lshlrev_b32_e32 v236, 16, v236
	v_pk_add_f32 v[234:235], v[4:5], v[234:235]
	v_pk_add_f32 v[212:213], v[6:7], v[212:213]
	v_pk_add_f32 v[236:237], v[0:1], v[236:237]
	v_pk_add_f32 v[214:215], v[2:3], v[214:215]
	v_cvt_pk_bf16_f32 v4, v234, v235
	v_cvt_pk_bf16_f32 v5, v212, v213
	v_cvt_pk_bf16_f32 v6, v236, v237
	v_cvt_pk_bf16_f32 v7, v214, v215
	global_store_dwordx4 v169, v[4:7], s[42:43] offset:256
	v_mul_f32_e32 v0, v235, v235
	v_mul_f32_e32 v1, v213, v213
	v_mul_f32_e32 v2, v237, v237
	v_mul_f32_e32 v3, v215, v215
	v_fmac_f32_e32 v0, v234, v234
	v_fmac_f32_e32 v1, v212, v212
	v_fmac_f32_e32 v2, v236, v236
	v_fmac_f32_e32 v3, v214, v214
	v_add_f32_e32 v0, v0, v1
	v_add_f32_e32 v0, v2, v0
	v_add_f32_e32 v0, v3, v0
	v_add_f32_e32 v16, v16, v0
	ds_bpermute_b32 v121, v171, v120
	ds_bpermute_b32 v113, v171, v112
	ds_bpermute_b32 v97, v171, v96
	ds_bpermute_b32 v81, v171, v80
	ds_bpermute_b32 v57, v171, v56
	ds_bpermute_b32 v49, v171, v48
	ds_bpermute_b32 v33, v171, v32
	ds_bpermute_b32 v17, v171, v16
	s_waitcnt lgkmcnt(0)
	v_add_f32_e32 v120, v120, v121
	v_add_f32_e32 v112, v112, v113
	v_add_f32_e32 v96, v96, v97
	v_add_f32_e32 v80, v80, v81
	v_add_f32_e32 v56, v56, v57
	v_add_f32_e32 v48, v48, v49
	v_add_f32_e32 v32, v32, v33
	v_add_f32_e32 v16, v16, v17
	ds_bpermute_b32 v121, v172, v120
	ds_bpermute_b32 v113, v172, v112
	ds_bpermute_b32 v97, v172, v96
	ds_bpermute_b32 v81, v172, v80
	ds_bpermute_b32 v57, v172, v56
	ds_bpermute_b32 v49, v172, v48
	ds_bpermute_b32 v33, v172, v32
	ds_bpermute_b32 v17, v172, v16
	s_waitcnt lgkmcnt(0)
	v_add_f32_e32 v120, v120, v121
	v_add_f32_e32 v112, v112, v113
	v_add_f32_e32 v96, v96, v97
	v_add_f32_e32 v80, v80, v81
	v_add_f32_e32 v56, v56, v57
	v_add_f32_e32 v48, v48, v49
	v_add_f32_e32 v32, v32, v33
	v_add_f32_e32 v16, v16, v17
	s_and_saveexec_b64 s[34:35], s[2:3]
	global_store_dword v170, v120, s[46:47]
	global_store_dword v170, v112, s[46:47] offset:1024
	global_store_dword v170, v96, s[46:47] offset:2048
	global_store_dword v170, v80, s[46:47] offset:3072
	global_store_dword v173, v56, s[46:47]
	global_store_dword v173, v48, s[46:47] offset:1024
	global_store_dword v173, v32, s[46:47] offset:2048
	global_store_dword v173, v16, s[46:47] offset:3072
	s_or_b64 exec, exec, s[34:35]
	s_and_b64 vcc, exec, s[4:5]
	s_mov_b64 s[4:5], -1
.Lres_end0:
	s_cbranch_vccnz .LBB0_454
	s_andn2_b64 vcc, exec, s[20:21]
	s_cbranch_vccnz .LBB0_453
	s_barrier
	s_branch .LBB0_453

;     __host__ __device__ bool next(int i, Unit& u) const {
;         const long L = (long)i * G + c; if (L >= nwg) return false;
;         int wgid = (int)L; { const int q = nwg / NXCD, r = nwg % NXCD, xcd = wgid % NXCD, off = wgid / NXCD; wgid = (xcd < r ? xcd * (q + 1) : r * (q + 1) + (xcd - r) * q) + off; }
;     __device__ __forceinline__ void operator()(AccRef acc, const pg8::Unit& u, int wr, int wc, int fr, int fq) const {
;     ...
;                     bf16_t* xp = xb + (size_t)row * D + col0 + bj * 128;
;                     f32x4 a, b; unpack8(*(const u32x4*)xp, a, b);
.LBB0_1210:
	v_lshl_add_u32 v252, s62, 8, v148
	v_lshl_or_b32 v253, s14, 8, v150
	v_lshlrev_b32_e32 v253, 1, v253
	v_lshl_add_u32 v252, v252, 11, v253
	global_load_dwordx4 v[230:233], v252, s[42:43]
	global_load_dwordx4 v[234:237], v252, s[42:43] offset:256
	v_add_u32_e32 v253, 0x8000, v252
	global_load_dwordx4 v[238:241], v253, s[42:43]
	global_load_dwordx4 v[242:245], v253, s[42:43] offset:256
	v_add_u32_e32 v253, 0x10000, v252
	global_load_dwordx4 v[246:249], v253, s[42:43]
	global_load_dwordx4 v[250:253], v253, s[42:43] offset:256
	s_add_i32 s59, s59, 1
	s_mul_i32 s0, s59, s50
	s_mul_hi_u32 s1, s59, s51
	s_add_i32 s1, s1, s0
	s_mul_i32 s0, s59, s51
	s_add_u32 s4, s0, s18
	s_addc_u32 s5, s1, s56
	v_cmp_gt_i64_e32 vcc, s[4:5], v[142:143]
	v_cmp_lt_i64_e64 s[0:1], s[4:5], v[140:141]
	s_cbranch_vccnz .LBB0_1216
	s_ashr_i32 s5, s4, 31
	s_lshr_b32 s5, s5, 29
	s_add_i32 s28, s4, s5
	s_and_b32 s5, s28, -8
	s_sub_i32 s29, s4, s5
	s_cmp_gt_i32 s29, -1
	s_mov_b64 s[4:5], -1
	s_cbranch_scc0 .LBB0_1213
	s_lshl_b32 s60, s29, 6
	s_mov_b64 s[4:5], 0

;     __device__ __forceinline__ void operator()(const f32x4 (&acc)[2], int srow, int cgp, int kq) const { one(acc[0], srow, 2 * cgp, kq); one(acc[1], srow, 2 * cgp + 1, kq); }
;     __device__ __forceinline__ void operator()(AccRef acc, const pg8::Unit& u, int wr, int wc, int fr, int fq) const {
;         const int row0 = u.pm * 256 + wr * 64 + fr, col0 = u.pn * 256 + wc * 32 + 8 * fq;
; #pragma unroll
;         for (int ai = 0; ai < 2; ++ai)
; #pragma unroll
;             for (int m = 0; m < 4; ++m) {
;                 const int row = row0 + ai * 128 + m * 16; float ss = 0.f;
; #pragma unroll
;                 for (int bj = 0; bj < 2; ++bj) {
;                     bf16_t* xp = xb + (size_t)row * D + col0 + bj * 128;
;                     f32x4 a, b; unpack8(*(const u32x4*)xp, a, b);
;                     a += acc[ai][bj][m][0] * alpha; b += acc[ai][bj][m][1] * alpha;
;                     *(u32x4*)xp = pack8(a, b);
;                     ss += (a[0] * a[0] + a[1] * a[1]) + (a[2] * a[2] + a[3] * a[3]) + (b[0] * b[0] + b[1] * b[1]) + (b[2] * b[2] + b[3] * b[3]);
;                 }
.LBB0_1225:
.Lres_beg1:
	v_lshl_add_u32 v170, s62, 8, v148
	v_lshl_or_b32 v169, s14, 8, v150
	v_lshlrev_b32_e32 v169, 1, v169
	v_lshl_add_u32 v168, v170, 11, v169
	v_add_u32_e32 v169, 0x18000, v168
	global_load_dwordx4 v[180:183], v169, s[42:43]
	global_load_dwordx4 v[184:187], v169, s[42:43] offset:256
	v_add_u32_e32 v169, 0x40000, v168
	global_load_dwordx4 v[188:191], v169, s[42:43]
	global_load_dwordx4 v[192:195], v169, s[42:43] offset:256
	v_add_u32_e32 v169, 0x48000, v168
	global_load_dwordx4 v[196:199], v169, s[42:43]
	global_load_dwordx4 v[200:203], v169, s[42:43] offset:256
	v_add_u32_e32 v169, 0x50000, v168
	global_load_dwordx4 v[204:207], v169, s[42:43]
	global_load_dwordx4 v[208:211], v169, s[42:43] offset:256
	v_bfe_u32 v171, v150, 5, 2
	v_lshl_add_u32 v171, s14, 2, v171
	v_lshlrev_b32_e32 v171, 2, v171
	v_lshl_add_u32 v170, v170, 6, v171
	v_add_u32_e32 v173, 0x2000, v170
	v_mbcnt_lo_u32_b32 v172, -1, 0
	v_mbcnt_hi_u32_b32 v172, -1, v172
	v_xor_b32_e32 v171, 16, v172
	v_xor_b32_e32 v172, 32, v172
	v_lshlrev_b32_e32 v171, 2, v171
	v_lshlrev_b32_e32 v172, 2, v172
	v_mov_b32_e32 v169, v168
	s_waitcnt vmcnt(8)
	v_lshlrev_b32_e32 v212, 16, v231
	v_and_b32_e32 v213, 0xffff0000, v231
	v_and_b32_e32 v231, 0xffff0000, v230
	v_lshlrev_b32_e32 v230, 16, v230
	v_lshlrev_b32_e32 v214, 16, v233
	v_and_b32_e32 v215, 0xffff0000, v233
	v_and_b32_e32 v233, 0xffff0000, v232
	v_lshlrev_b32_e32 v232, 16, v232
	v_pk_add_f32 v[230:231], v[124:125], v[230:231]
	v_pk_add_f32 v[212:213], v[126:127], v[212:213]
	v_pk_add_f32 v[232:233], v[120:121], v[232:233]
	v_pk_add_f32 v[214:215], v[122:123], v[214:215]
	v_cvt_pk_bf16_f32 v124, v230, v231
	v_cvt_pk_bf16_f32 v125, v212, v213
	v_cvt_pk_bf16_f32 v126, v232, v233
	v_cvt_pk_bf16_f32 v127, v214, v215
	global_store_dwordx4 v169, v[124:127], s[42:43]
	v_mul_f32_e32 v120, v231, v231
	v_mul_f32_e32 v121, v213, v213
	v_mul_f32_e32 v122, v233, v233
	v_mul_f32_e32 v123, v215, v215
	v_fmac_f32_e32 v120, v230, v230
	v_fmac_f32_e32 v121, v212, v212
	v_fmac_f32_e32 v122, v232, v232
	v_fmac_f32_e32 v123, v214, v214
	v_add_f32_e32 v120, v120, v121
	v_add_f32_e32 v120, v122, v120
	v_add_f32_e32 v120, v123, v120
	s_nop 0
	v_lshlrev_b32_e32 v212, 16, v235
	v_and_b32_e32 v213, 0xffff0000, v235
	v_and_b32_e32 v235, 0xffff0000, v234
	v_lshlrev_b32_e32 v234, 16, v234
	v_lshlrev_b32_e32 v214, 16, v237
	v_and_b32_e32 v215, 0xffff0000, v237
	v_and_b32_e32 v237, 0xffff0000, v236
	v_lshlrev_b32_e32 v236, 16, v236
	v_pk_add_f32 v[234:235], v[116:117], v[234:235]
	v_pk_add_f32 v[212:213], v[118:119], v[212:213]
	v_pk_add_f32 v[236:237], v[112:113], v[236:237]
	v_pk_add_f32 v[214:215], v[114:115], v[214:215]
	v_cvt_pk_bf16_f32 v116, v234, v235
	v_cvt_pk_bf16_f32 v117, v212, v213
	v_cvt_pk_bf16_f32 v118, v236, v237
	v_cvt_pk_bf16_f32 v119, v214, v215
	global_store_dwordx4 v169, v[116:119], s[42:43] offset:256
	v_mul_f32_e32 v112, v235, v235
	v_mul_f32_e32 v113, v213, v213
	v_mul_f32_e32 v114, v237, v237
	v_mul_f32_e32 v115, v215, v215
	v_fmac_f32_e32 v112, v234, v234
	v_fmac_f32_e32 v113, v212, v212
	v_fmac_f32_e32 v114, v236, v236
	v_fmac_f32_e32 v115, v214, v214
	v_add_f32_e32 v112, v112, v113
	v_add_f32_e32 v112, v114, v112
	v_add_f32_e32 v112, v115, v112
	v_add_f32_e32 v120, v120, v112
	v_add_u32_e32 v169, 0x58000, v168
	global_load_dwordx4 v[230:233], v169, s[42:43]
	global_load_dwordx4 v[234:237], v169, s[42:43] offset:256
	v_add_u32_e32 v169, 0x8000, v168
	s_nop 0
	v_lshlrev_b32_e32 v212, 16, v239
	v_and_b32_e32 v213, 0xffff0000, v239
	v_and_b32_e32 v239, 0xffff0000, v238
	v_lshlrev_b32_e32 v238, 16, v238
	v_lshlrev_b32_e32 v214, 16, v241
	v_and_b32_e32 v215, 0xffff0000, v241
	v_and_b32_e32 v241, 0xffff0000, v240
	v_lshlrev_b32_e32 v240, 16, v240
	v_pk_add_f32 v[238:239], v[108:109], v[238:239]
	v_pk_add_f32 v[212:213], v[110:111], v[212:213]
	v_pk_add_f32 v[240:241], v[104:105], v[240:241]
	v_pk_add_f32 v[214:215], v[106:107], v[214:215]
	v_cvt_pk_bf16_f32 v108, v238, v239
	v_cvt_pk_bf16_f32 v109, v212, v213
	v_cvt_pk_bf16_f32 v110, v240, v241
	v_cvt_pk_bf16_f32 v111, v214, v215
	global_store_dwordx4 v169, v[108:111], s[42:43]
	v_mul_f32_e32 v104, v239, v239
	v_mul_f32_e32 v105, v213, v213
	v_mul_f32_e32 v106, v241, v241
	v_mul_f32_e32 v107, v215, v215
	v_fmac_f32_e32 v104, v238, v238
	v_fmac_f32_e32 v105, v212, v212
	v_fmac_f32_e32 v106, v240, v240
	v_fmac_f32_e32 v107, v214, v214
	v_add_f32_e32 v104, v104, v105
	v_add_f32_e32 v104, v106, v104
	v_add_f32_e32 v104, v107, v104
	s_nop 0
	v_lshlrev_b32_e32 v212, 16, v243
	v_and_b32_e32 v213, 0xffff0000, v243
	v_and_b32_e32 v243, 0xffff0000, v242
	v_lshlrev_b32_e32 v242, 16, v242
	v_lshlrev_b32_e32 v214, 16, v245
	v_and_b32_e32 v215, 0xffff0000, v245
	v_and_b32_e32 v245, 0xffff0000, v244
	v_lshlrev_b32_e32 v244, 16, v244
	v_pk_add_f32 v[242:243], v[100:101], v[242:243]
	v_pk_add_f32 v[212:213], v[102:103], v[212:213]
	v_pk_add_f32 v[244:245], v[96:97], v[244:245]
	v_pk_add_f32 v[214:215], v[98:99], v[214:215]
	v_cvt_pk_bf16_f32 v100, v242, v243
	v_cvt_pk_bf16_f32 v101, v212, v213
	v_cvt_pk_bf16_f32 v102, v244, v245
	v_cvt_pk_bf16_f32 v103, v214, v215
	global_store_dwordx4 v169, v[100:103], s[42:43] offset:256
	v_mul_f32_e32 v96, v243, v243
	v_mul_f32_e32 v97, v213, v213
	v_mul_f32_e32 v98, v245, v245
	v_mul_f32_e32 v99, v215, v215
	v_fmac_f32_e32 v96, v242, v242
	v_fmac_f32_e32 v97, v212, v212
	v_fmac_f32_e32 v98, v244, v244
	v_fmac_f32_e32 v99, v214, v214
	v_add_f32_e32 v96, v96, v97
	v_add_f32_e32 v96, v98, v96
	v_add_f32_e32 v96, v99, v96
	v_add_f32_e32 v104, v104, v96
	v_add_u32_e32 v169, 0x10000, v168
	s_nop 0
	v_lshlrev_b32_e32 v212, 16, v247
	v_and_b32_e32 v213, 0xffff0000, v247
;     __device__ __forceinline__ void operator()(AccRef acc, const pg8::Unit& u, int wr, int wc, int fr, int fq) const {
;     ...
;                 const int row = row0 + ai * 128 + m * 16; float ss = 0.f;
; #pragma unroll
;                 for (int bj = 0; bj < 2; ++bj) {
;                     bf16_t* xp = xb + (size_t)row * D + col0 + bj * 128;
;                     f32x4 a, b; unpack8(*(const u32x4*)xp, a, b);
;                     a += acc[ai][bj][m][0] * alpha; b += acc[ai][bj][m][1] * alpha;
;                     *(u32x4*)xp = pack8(a, b);
;                     ss += (a[0] * a[0] + a[1] * a[1]) + (a[2] * a[2] + a[3] * a[3]) + (b[0] * b[0] + b[1] * b[1]) + (b[2] * b[2] + b[3] * b[3]);
;                 }
	v_and_b32_e32 v247, 0xffff0000, v246
	v_lshlrev_b32_e32 v246, 16, v246
	v_lshlrev_b32_e32 v214, 16, v249
	v_and_b32_e32 v215, 0xffff0000, v249
	v_and_b32_e32 v249, 0xffff0000, v248
	v_lshlrev_b32_e32 v248, 16, v248
	v_pk_add_f32 v[246:247], v[92:93], v[246:247]
	v_pk_add_f32 v[212:213], v[94:95], v[212:213]
	v_pk_add_f32 v[248:249], v[88:89], v[248:249]
	v_pk_add_f32 v[214:215], v[90:91], v[214:215]
	v_cvt_pk_bf16_f32 v92, v246, v247
	v_cvt_pk_bf16_f32 v93, v212, v213
	v_cvt_pk_bf16_f32 v94, v248, v249
	v_cvt_pk_bf16_f32 v95, v214, v215
	global_store_dwordx4 v169, v[92:95], s[42:43]
	v_mul_f32_e32 v88, v247, v247
	v_mul_f32_e32 v89, v213, v213
	v_mul_f32_e32 v90, v249, v249
	v_mul_f32_e32 v91, v215, v215
	v_fmac_f32_e32 v88, v246, v246
	v_fmac_f32_e32 v89, v212, v212
	v_fmac_f32_e32 v90, v248, v248
	v_fmac_f32_e32 v91, v214, v214
	v_add_f32_e32 v88, v88, v89
	v_add_f32_e32 v88, v90, v88
	v_add_f32_e32 v88, v91, v88
	s_nop 0
	v_lshlrev_b32_e32 v212, 16, v251
	v_and_b32_e32 v213, 0xffff0000, v251
	v_and_b32_e32 v251, 0xffff0000, v250
	v_lshlrev_b32_e32 v250, 16, v250
	v_lshlrev_b32_e32 v214, 16, v253
	v_and_b32_e32 v215, 0xffff0000, v253
	v_and_b32_e32 v253, 0xffff0000, v252
	v_lshlrev_b32_e32 v252, 16, v252
	v_pk_add_f32 v[250:251], v[84:85], v[250:251]
	v_pk_add_f32 v[212:213], v[86:87], v[212:213]
	v_pk_add_f32 v[252:253], v[80:81], v[252:253]
	v_pk_add_f32 v[214:215], v[82:83], v[214:215]
	v_cvt_pk_bf16_f32 v84, v250, v251
	v_cvt_pk_bf16_f32 v85, v212, v213
	v_cvt_pk_bf16_f32 v86, v252, v253
	v_cvt_pk_bf16_f32 v87, v214, v215
	global_store_dwordx4 v169, v[84:87], s[42:43] offset:256
	v_mul_f32_e32 v80, v251, v251
	v_mul_f32_e32 v81, v213, v213
	v_mul_f32_e32 v82, v253, v253
	v_mul_f32_e32 v83, v215, v215
	v_fmac_f32_e32 v80, v250, v250
	v_fmac_f32_e32 v81, v212, v212
	v_fmac_f32_e32 v82, v252, v252
	v_fmac_f32_e32 v83, v214, v214
	v_add_f32_e32 v80, v80, v81
	v_add_f32_e32 v80, v82, v80
	v_add_f32_e32 v80, v83, v80
	v_add_f32_e32 v88, v88, v80
	v_add_u32_e32 v169, 0x18000, v168
	s_waitcnt vmcnt(15)
	v_lshlrev_b32_e32 v212, 16, v181
	v_and_b32_e32 v213, 0xffff0000, v181
	v_and_b32_e32 v181, 0xffff0000, v180
	v_lshlrev_b32_e32 v180, 16, v180
	v_lshlrev_b32_e32 v214, 16, v183
	v_and_b32_e32 v215, 0xffff0000, v183
	v_and_b32_e32 v183, 0xffff0000, v182
	v_lshlrev_b32_e32 v182, 16, v182
	v_pk_add_f32 v[180:181], v[76:77], v[180:181]
	v_pk_add_f32 v[212:213], v[78:79], v[212:213]
	v_pk_add_f32 v[182:183], v[72:73], v[182:183]
	v_pk_add_f32 v[214:215], v[74:75], v[214:215]
	v_cvt_pk_bf16_f32 v76, v180, v181
	v_cvt_pk_bf16_f32 v77, v212, v213
	v_cvt_pk_bf16_f32 v78, v182, v183
	v_cvt_pk_bf16_f32 v79, v214, v215
	global_store_dwordx4 v169, v[76:79], s[42:43]
	v_mul_f32_e32 v72, v181, v181
	v_mul_f32_e32 v73, v213, v213
	v_mul_f32_e32 v74, v183, v183
	v_mul_f32_e32 v75, v215, v215
	v_fmac_f32_e32 v72, v180, v180
	v_fmac_f32_e32 v73, v212, v212
	v_fmac_f32_e32 v74, v182, v182
	v_fmac_f32_e32 v75, v214, v214
	v_add_f32_e32 v72, v72, v73
	v_add_f32_e32 v72, v74, v72
	v_add_f32_e32 v72, v75, v72
	s_waitcnt vmcnt(15)
	v_lshlrev_b32_e32 v212, 16, v185
	v_and_b32_e32 v213, 0xffff0000, v185
	v_and_b32_e32 v185, 0xffff0000, v184
	v_lshlrev_b32_e32 v184, 16, v184
	v_lshlrev_b32_e32 v214, 16, v187
	v_and_b32_e32 v215, 0xffff0000, v187
	v_and_b32_e32 v187, 0xffff0000, v186
	v_lshlrev_b32_e32 v186, 16, v186
	v_pk_add_f32 v[184:185], v[68:69], v[184:185]
	v_pk_add_f32 v[212:213], v[70:71], v[212:213]
	v_pk_add_f32 v[186:187], v[64:65], v[186:187]
	v_pk_add_f32 v[214:215], v[66:67], v[214:215]
	v_cvt_pk_bf16_f32 v68, v184, v185
	v_cvt_pk_bf16_f32 v69, v212, v213
	v_cvt_pk_bf16_f32 v70, v186, v187
	v_cvt_pk_bf16_f32 v71, v214, v215
	global_store_dwordx4 v169, v[68:71], s[42:43] offset:256
	v_mul_f32_e32 v64, v185, v185
	v_mul_f32_e32 v65, v213, v213
	v_mul_f32_e32 v66, v187, v187
	v_mul_f32_e32 v67, v215, v215
	v_fmac_f32_e32 v64, v184, v184
	v_fmac_f32_e32 v65, v212, v212
	v_fmac_f32_e32 v66, v186, v186
	v_fmac_f32_e32 v67, v214, v214
	v_add_f32_e32 v64, v64, v65
	v_add_f32_e32 v64, v66, v64
	v_add_f32_e32 v64, v67, v64
	v_add_f32_e32 v72, v72, v64
	v_add_u32_e32 v169, 0x40000, v168
	s_waitcnt vmcnt(15)
	v_lshlrev_b32_e32 v212, 16, v189
	v_and_b32_e32 v213, 0xffff0000, v189
	v_and_b32_e32 v189, 0xffff0000, v188
	v_lshlrev_b32_e32 v188, 16, v188
	v_lshlrev_b32_e32 v214, 16, v191
	v_and_b32_e32 v215, 0xffff0000, v191
	v_and_b32_e32 v191, 0xffff0000, v190
	v_lshlrev_b32_e32 v190, 16, v190
	v_pk_add_f32 v[188:189], v[60:61], v[188:189]
	v_pk_add_f32 v[212:213], v[62:63], v[212:213]
	v_pk_add_f32 v[190:191], v[56:57], v[190:191]
	v_pk_add_f32 v[214:215], v[58:59], v[214:215]
	v_cvt_pk_bf16_f32 v60, v188, v189
	v_cvt_pk_bf16_f32 v61, v212, v213
	v_cvt_pk_bf16_f32 v62, v190, v191
	v_cvt_pk_bf16_f32 v63, v214, v215
	global_store_dwordx4 v169, v[60:63], s[42:43]
	v_mul_f32_e32 v56, v189, v189
	v_mul_f32_e32 v57, v213, v213
	v_mul_f32_e32 v58, v191, v191
	v_mul_f32_e32 v59, v215, v215
	v_fmac_f32_e32 v56, v188, v188
	v_fmac_f32_e32 v57, v212, v212
	v_fmac_f32_e32 v58, v190, v190
	v_fmac_f32_e32 v59, v214, v214
	v_add_f32_e32 v56, v56, v57
	v_add_f32_e32 v56, v58, v56
	v_add_f32_e32 v56, v59, v56
	s_waitcnt vmcnt(15)
;     __device__ __forceinline__ void operator()(AccRef acc, const pg8::Unit& u, int wr, int wc, int fr, int fq) const {
;     ...
;                 const int row = row0 + ai * 128 + m * 16; float ss = 0.f;
; #pragma unroll
;                 for (int bj = 0; bj < 2; ++bj) {
;                     bf16_t* xp = xb + (size_t)row * D + col0 + bj * 128;
;                     f32x4 a, b; unpack8(*(const u32x4*)xp, a, b);
;                     a += acc[ai][bj][m][0] * alpha; b += acc[ai][bj][m][1] * alpha;
;                     *(u32x4*)xp = pack8(a, b);
;                     ss += (a[0] * a[0] + a[1] * a[1]) + (a[2] * a[2] + a[3] * a[3]) + (b[0] * b[0] + b[1] * b[1]) + (b[2] * b[2] + b[3] * b[3]);
;                 }
	v_lshlrev_b32_e32 v212, 16, v193
	v_and_b32_e32 v213, 0xffff0000, v193
	v_and_b32_e32 v193, 0xffff0000, v192
	v_lshlrev_b32_e32 v192, 16, v192
	v_lshlrev_b32_e32 v214, 16, v195
	v_and_b32_e32 v215, 0xffff0000, v195
	v_and_b32_e32 v195, 0xffff0000, v194
	v_lshlrev_b32_e32 v194, 16, v194
	v_pk_add_f32 v[192:193], v[52:53], v[192:193]
	v_pk_add_f32 v[212:213], v[54:55], v[212:213]
	v_pk_add_f32 v[194:195], v[48:49], v[194:195]
	v_pk_add_f32 v[214:215], v[50:51], v[214:215]
	v_cvt_pk_bf16_f32 v52, v192, v193
	v_cvt_pk_bf16_f32 v53, v212, v213
	v_cvt_pk_bf16_f32 v54, v194, v195
	v_cvt_pk_bf16_f32 v55, v214, v215
	global_store_dwordx4 v169, v[52:55], s[42:43] offset:256
	v_mul_f32_e32 v48, v193, v193
	v_mul_f32_e32 v49, v213, v213
	v_mul_f32_e32 v50, v195, v195
	v_mul_f32_e32 v51, v215, v215
	v_fmac_f32_e32 v48, v192, v192
	v_fmac_f32_e32 v49, v212, v212
	v_fmac_f32_e32 v50, v194, v194
	v_fmac_f32_e32 v51, v214, v214
	v_add_f32_e32 v48, v48, v49
	v_add_f32_e32 v48, v50, v48
	v_add_f32_e32 v48, v51, v48
	v_add_f32_e32 v56, v56, v48
	v_add_u32_e32 v169, 0x48000, v168
	s_waitcnt vmcnt(15)
	v_lshlrev_b32_e32 v212, 16, v197
	v_and_b32_e32 v213, 0xffff0000, v197
	v_and_b32_e32 v197, 0xffff0000, v196
	v_lshlrev_b32_e32 v196, 16, v196
	v_lshlrev_b32_e32 v214, 16, v199
	v_and_b32_e32 v215, 0xffff0000, v199
	v_and_b32_e32 v199, 0xffff0000, v198
	v_lshlrev_b32_e32 v198, 16, v198
	v_pk_add_f32 v[196:197], v[44:45], v[196:197]
	v_pk_add_f32 v[212:213], v[46:47], v[212:213]
	v_pk_add_f32 v[198:199], v[40:41], v[198:199]
	v_pk_add_f32 v[214:215], v[42:43], v[214:215]
	v_cvt_pk_bf16_f32 v44, v196, v197
	v_cvt_pk_bf16_f32 v45, v212, v213
	v_cvt_pk_bf16_f32 v46, v198, v199
	v_cvt_pk_bf16_f32 v47, v214, v215
	global_store_dwordx4 v169, v[44:47], s[42:43]
	v_mul_f32_e32 v40, v197, v197
	v_mul_f32_e32 v41, v213, v213
	v_mul_f32_e32 v42, v199, v199
	v_mul_f32_e32 v43, v215, v215
	v_fmac_f32_e32 v40, v196, v196
	v_fmac_f32_e32 v41, v212, v212
	v_fmac_f32_e32 v42, v198, v198
	v_fmac_f32_e32 v43, v214, v214
	v_add_f32_e32 v40, v40, v41
	v_add_f32_e32 v40, v42, v40
	v_add_f32_e32 v40, v43, v40
	s_waitcnt vmcnt(15)
	v_lshlrev_b32_e32 v212, 16, v201
	v_and_b32_e32 v213, 0xffff0000, v201
	v_and_b32_e32 v201, 0xffff0000, v200
	v_lshlrev_b32_e32 v200, 16, v200
	v_lshlrev_b32_e32 v214, 16, v203
	v_and_b32_e32 v215, 0xffff0000, v203
	v_and_b32_e32 v203, 0xffff0000, v202
	v_lshlrev_b32_e32 v202, 16, v202
	v_pk_add_f32 v[200:201], v[36:37], v[200:201]
	v_pk_add_f32 v[212:213], v[38:39], v[212:213]
	v_pk_add_f32 v[202:203], v[32:33], v[202:203]
	v_pk_add_f32 v[214:215], v[34:35], v[214:215]
	v_cvt_pk_bf16_f32 v36, v200, v201
	v_cvt_pk_bf16_f32 v37, v212, v213
	v_cvt_pk_bf16_f32 v38, v202, v203
	v_cvt_pk_bf16_f32 v39, v214, v215
	global_store_dwordx4 v169, v[36:39], s[42:43] offset:256
	v_mul_f32_e32 v32, v201, v201
	v_mul_f32_e32 v33, v213, v213
	v_mul_f32_e32 v34, v203, v203
	v_mul_f32_e32 v35, v215, v215
	v_fmac_f32_e32 v32, v200, v200
	v_fmac_f32_e32 v33, v212, v212
	v_fmac_f32_e32 v34, v202, v202
	v_fmac_f32_e32 v35, v214, v214
	v_add_f32_e32 v32, v32, v33
	v_add_f32_e32 v32, v34, v32
	v_add_f32_e32 v32, v35, v32
	v_add_f32_e32 v40, v40, v32
	v_add_u32_e32 v169, 0x50000, v168
	s_waitcnt vmcnt(15)
	v_lshlrev_b32_e32 v212, 16, v205
	v_and_b32_e32 v213, 0xffff0000, v205
	v_and_b32_e32 v205, 0xffff0000, v204
	v_lshlrev_b32_e32 v204, 16, v204
	v_lshlrev_b32_e32 v214, 16, v207
	v_and_b32_e32 v215, 0xffff0000, v207
	v_and_b32_e32 v207, 0xffff0000, v206
	v_lshlrev_b32_e32 v206, 16, v206
	v_pk_add_f32 v[204:205], v[28:29], v[204:205]
	v_pk_add_f32 v[212:213], v[30:31], v[212:213]
	v_pk_add_f32 v[206:207], v[24:25], v[206:207]
	v_pk_add_f32 v[214:215], v[26:27], v[214:215]
	v_cvt_pk_bf16_f32 v28, v204, v205
	v_cvt_pk_bf16_f32 v29, v212, v213
	v_cvt_pk_bf16_f32 v30, v206, v207
	v_cvt_pk_bf16_f32 v31, v214, v215
	global_store_dwordx4 v169, v[28:31], s[42:43]
	v_mul_f32_e32 v24, v205, v205
	v_mul_f32_e32 v25, v213, v213
	v_mul_f32_e32 v26, v207, v207
	v_mul_f32_e32 v27, v215, v215
	v_fmac_f32_e32 v24, v204, v204
	v_fmac_f32_e32 v25, v212, v212
	v_fmac_f32_e32 v26, v206, v206
	v_fmac_f32_e32 v27, v214, v214
	v_add_f32_e32 v24, v24, v25
	v_add_f32_e32 v24, v26, v24
	v_add_f32_e32 v24, v27, v24
	s_waitcnt vmcnt(15)
;     __device__ __forceinline__ void operator()(AccRef acc, const pg8::Unit& u, int wr, int wc, int fr, int fq) const {
;     ...
;                 const int row = row0 + ai * 128 + m * 16; float ss = 0.f;
; #pragma unroll
;                 for (int bj = 0; bj < 2; ++bj) {
;                     bf16_t* xp = xb + (size_t)row * D + col0 + bj * 128;
;                     f32x4 a, b; unpack8(*(const u32x4*)xp, a, b);
;                     a += acc[ai][bj][m][0] * alpha; b += acc[ai][bj][m][1] * alpha;
;                     *(u32x4*)xp = pack8(a, b);
;                     ss += (a[0] * a[0] + a[1] * a[1]) + (a[2] * a[2] + a[3] * a[3]) + (b[0] * b[0] + b[1] * b[1]) + (b[2] * b[2] + b[3] * b[3]);
;                 }
;                 ss += __shfl_xor(ss, 16); ss += __shfl_xor(ss, 32);
;                 if (fq == 0) ssp[(size_t)row * 16 + u.pn * 4 + wc] = ss;
;             }
	v_lshlrev_b32_e32 v212, 16, v209
	v_and_b32_e32 v213, 0xffff0000, v209
	v_and_b32_e32 v209, 0xffff0000, v208
	v_lshlrev_b32_e32 v208, 16, v208
	v_lshlrev_b32_e32 v214, 16, v211
	v_and_b32_e32 v215, 0xffff0000, v211
	v_and_b32_e32 v211, 0xffff0000, v210
	v_lshlrev_b32_e32 v210, 16, v210
	v_pk_add_f32 v[208:209], v[20:21], v[208:209]
	v_pk_add_f32 v[212:213], v[22:23], v[212:213]
	v_pk_add_f32 v[210:211], v[16:17], v[210:211]
	v_pk_add_f32 v[214:215], v[18:19], v[214:215]
	v_cvt_pk_bf16_f32 v20, v208, v209
	v_cvt_pk_bf16_f32 v21, v212, v213
	v_cvt_pk_bf16_f32 v22, v210, v211
	v_cvt_pk_bf16_f32 v23, v214, v215
	global_store_dwordx4 v169, v[20:23], s[42:43] offset:256
	v_mul_f32_e32 v16, v209, v209
	v_mul_f32_e32 v17, v213, v213
	v_mul_f32_e32 v18, v211, v211
	v_mul_f32_e32 v19, v215, v215
	v_fmac_f32_e32 v16, v208, v208
	v_fmac_f32_e32 v17, v212, v212
	v_fmac_f32_e32 v18, v210, v210
	v_fmac_f32_e32 v19, v214, v214
	v_add_f32_e32 v16, v16, v17
	v_add_f32_e32 v16, v18, v16
	v_add_f32_e32 v16, v19, v16
	v_add_f32_e32 v24, v24, v16
	v_add_u32_e32 v169, 0x58000, v168
	s_waitcnt vmcnt(13)
	v_lshlrev_b32_e32 v212, 16, v231
	v_and_b32_e32 v213, 0xffff0000, v231
	v_and_b32_e32 v231, 0xffff0000, v230
	v_lshlrev_b32_e32 v230, 16, v230
	v_lshlrev_b32_e32 v214, 16, v233
	v_and_b32_e32 v215, 0xffff0000, v233
	v_and_b32_e32 v233, 0xffff0000, v232
	v_lshlrev_b32_e32 v232, 16, v232
	v_pk_add_f32 v[230:231], v[12:13], v[230:231]
	v_pk_add_f32 v[212:213], v[14:15], v[212:213]
	v_pk_add_f32 v[232:233], v[8:9], v[232:233]
	v_pk_add_f32 v[214:215], v[10:11], v[214:215]
	v_cvt_pk_bf16_f32 v12, v230, v231
	v_cvt_pk_bf16_f32 v13, v212, v213
	v_cvt_pk_bf16_f32 v14, v232, v233
	v_cvt_pk_bf16_f32 v15, v214, v215
	global_store_dwordx4 v169, v[12:15], s[42:43]
	v_mul_f32_e32 v8, v231, v231
	v_mul_f32_e32 v9, v213, v213
	v_mul_f32_e32 v10, v233, v233
	v_mul_f32_e32 v11, v215, v215
	v_fmac_f32_e32 v8, v230, v230
	v_fmac_f32_e32 v9, v212, v212
	v_fmac_f32_e32 v10, v232, v232
	v_fmac_f32_e32 v11, v214, v214
	v_add_f32_e32 v8, v8, v9
	v_add_f32_e32 v8, v10, v8
	v_add_f32_e32 v8, v11, v8
	s_waitcnt vmcnt(13)
	v_lshlrev_b32_e32 v212, 16, v235
	v_and_b32_e32 v213, 0xffff0000, v235
	v_and_b32_e32 v235, 0xffff0000, v234
	v_lshlrev_b32_e32 v234, 16, v234
	v_lshlrev_b32_e32 v214, 16, v237
	v_and_b32_e32 v215, 0xffff0000, v237
	v_and_b32_e32 v237, 0xffff0000, v236
	v_lshlrev_b32_e32 v236, 16, v236
	v_pk_add_f32 v[234:235], v[4:5], v[234:235]
	v_pk_add_f32 v[212:213], v[6:7], v[212:213]
	v_pk_add_f32 v[236:237], v[0:1], v[236:237]
	v_pk_add_f32 v[214:215], v[2:3], v[214:215]
	v_cvt_pk_bf16_f32 v4, v234, v235
	v_cvt_pk_bf16_f32 v5, v212, v213
	v_cvt_pk_bf16_f32 v6, v236, v237
	v_cvt_pk_bf16_f32 v7, v214, v215
	global_store_dwordx4 v169, v[4:7], s[42:43] offset:256
	v_mul_f32_e32 v0, v235, v235
	v_mul_f32_e32 v1, v213, v213
	v_mul_f32_e32 v2, v237, v237
	v_mul_f32_e32 v3, v215, v215
	v_fmac_f32_e32 v0, v234, v234
	v_fmac_f32_e32 v1, v212, v212
	v_fmac_f32_e32 v2, v236, v236
	v_fmac_f32_e32 v3, v214, v214
	v_add_f32_e32 v0, v0, v1
	v_add_f32_e32 v0, v2, v0
	v_add_f32_e32 v0, v3, v0
	v_add_f32_e32 v8, v8, v0
	ds_bpermute_b32 v121, v171, v120
	ds_bpermute_b32 v105, v171, v104
	ds_bpermute_b32 v89, v171, v88
	ds_bpermute_b32 v73, v171, v72
	ds_bpermute_b32 v57, v171, v56
	ds_bpermute_b32 v41, v171, v40
	ds_bpermute_b32 v25, v171, v24
	ds_bpermute_b32 v9, v171, v8
	s_waitcnt lgkmcnt(0)
	v_add_f32_e32 v120, v120, v121
	v_add_f32_e32 v104, v104, v105
	v_add_f32_e32 v88, v88, v89
	v_add_f32_e32 v72, v72, v73
	v_add_f32_e32 v56, v56, v57
	v_add_f32_e32 v40, v40, v41
	v_add_f32_e32 v24, v24, v25
	v_add_f32_e32 v8, v8, v9
	ds_bpermute_b32 v121, v172, v120
	ds_bpermute_b32 v105, v172, v104
	ds_bpermute_b32 v89, v172, v88
	ds_bpermute_b32 v73, v172, v72
	ds_bpermute_b32 v57, v172, v56
	ds_bpermute_b32 v41, v172, v40
	ds_bpermute_b32 v25, v172, v24
	ds_bpermute_b32 v9, v172, v8
	s_waitcnt lgkmcnt(0)
	v_add_f32_e32 v120, v120, v121
	v_add_f32_e32 v104, v104, v105
	v_add_f32_e32 v88, v88, v89
	v_add_f32_e32 v72, v72, v73
	v_add_f32_e32 v56, v56, v57
	v_add_f32_e32 v40, v40, v41
	v_add_f32_e32 v24, v24, v25
	v_add_f32_e32 v8, v8, v9
	s_and_saveexec_b64 s[34:35], s[2:3]
	global_store_dword v170, v120, s[46:47]
	global_store_dword v170, v104, s[46:47] offset:1024
	global_store_dword v170, v88, s[46:47] offset:2048
	global_store_dword v170, v72, s[46:47] offset:3072
	global_store_dword v173, v56, s[46:47]
	global_store_dword v173, v40, s[46:47] offset:1024
	global_store_dword v173, v24, s[46:47] offset:2048
	global_store_dword v173, v8, s[46:47] offset:3072
	s_or_b64 exec, exec, s[34:35]
	s_and_b64 vcc, exec, s[4:5]
	s_mov_b64 s[4:5], -1

;     __host__ __device__ bool next(int i, Unit& u) const {
;         const long L = (long)i * G + c; if (L >= nwg) return false;
;         int wgid = (int)L; { const int q = nwg / NXCD, r = nwg % NXCD, xcd = wgid % NXCD, off = wgid / NXCD; wgid = (xcd < r ? xcd * (q + 1) : r * (q + 1) + (xcd - r) * q) + off; }
;     __device__ __forceinline__ void operator()(AccRef acc, const pg8::Unit& u, int wr, int wc, int fr, int fq) const {
;     ...
;                     bf16_t* xp = xb + (size_t)row * D + col0 + bj * 128;
;                     f32x4 a, b; unpack8(*(const u32x4*)xp, a, b);
.LBB0_1399:
	v_lshl_add_u32 v252, s62, 8, v156
	v_lshl_or_b32 v253, s14, 8, v158
	v_lshlrev_b32_e32 v253, 1, v253
	v_lshl_add_u32 v252, v252, 11, v253
	global_load_dwordx4 v[230:233], v252, s[42:43]
	global_load_dwordx4 v[234:237], v252, s[42:43] offset:256
	v_add_u32_e32 v253, 0x8000, v252
	global_load_dwordx4 v[238:241], v253, s[42:43]
	global_load_dwordx4 v[242:245], v253, s[42:43] offset:256
	v_add_u32_e32 v253, 0x10000, v252
	global_load_dwordx4 v[246:249], v253, s[42:43]
	global_load_dwordx4 v[250:253], v253, s[42:43] offset:256
	s_add_i32 s59, s59, 1
	s_mul_i32 s0, s59, s50
	s_mul_hi_u32 s1, s59, s51
	s_add_i32 s1, s1, s0
	s_mul_i32 s0, s59, s51
	s_add_u32 s4, s0, s18
	s_addc_u32 s5, s1, s56
	v_cmp_gt_i64_e32 vcc, s[4:5], v[142:143]
	v_cmp_lt_i64_e64 s[0:1], s[4:5], v[140:141]
	s_cbranch_vccnz .LBB0_1405
	s_ashr_i32 s5, s4, 31
	s_lshr_b32 s5, s5, 29
	s_add_i32 s28, s4, s5
	s_and_b32 s5, s28, -8
	s_sub_i32 s29, s4, s5
	s_cmp_gt_i32 s29, -1
	s_mov_b64 s[4:5], -1
	s_cbranch_scc0 .LBB0_1402
	s_lshl_b32 s60, s29, 6
	s_mov_b64 s[4:5], 0

; #define PG8_STAGE(bufoff, gbase, voff) do { _Pragma("unroll") for (int _i = 0; _i < 2; ++_i) \
;         __builtin_amdgcn_global_load_lds((const unsigned*)((const char*)(gbase) + (voff)[_i]), (PG8_LAS unsigned*)(lds + (bufoff) + ldsw + _i * 8192), 16, 0, 0); } while (0)
; #define PG8_LDA(dst, b, h) do { _Pragma("unroll") for (int m = 0; m < 4; ++m) _Pragma("unroll") for (int k = 0; k < 2; ++k) dst[m][k] = *(const PG8_LAS bf16x8*)(lds + PG8_SA(b, h) + aoff + m * 2048 + k * 1024); } while (0)
; #define PG8_LDB(dst, b, h) do { _Pragma("unroll") for (int n = 0; n < 2; ++n) _Pragma("unroll") for (int k = 0; k < 2; ++k) dst[n][k] = *(const PG8_LAS bf16x8*)(lds + PG8_SB(b, h) + boff + n * 2048 + k * 1024); } while (0)
; #define PG8_MMA(ai, bj, At, Bt) do { __builtin_amdgcn_s_setprio(1); _Pragma("unroll") for (int m = 0; m < 4; ++m) _Pragma("unroll") for (int n = 0; n < 2; ++n) _Pragma("unroll") for (int k = 0; k < 2; ++k) \
;         acc[ai][bj][m][n] = __builtin_amdgcn_mfma_f32_16x16x32_bf16(Bt[n][k], At[m][k], acc[ai][bj][m][n], 0, 0, 0); __builtin_amdgcn_s_setprio(0); } while (0)
; #define PG8_WAIT_V(n) asm volatile("s_waitcnt vmcnt(" #n ")" ::: "memory")
; #define PG8_WAIT_L(n) asm volatile("s_waitcnt lgkmcnt(" #n ")" ::: "memory")
; #define PG8_BAR __builtin_amdgcn_s_barrier()
; #define PG8_SCHED __builtin_amdgcn_sched_barrier(0)
; template <class Epi, class Sched, bool ALIGN_EPI = false, bool SP2 = false>
; __device__ __forceinline__ void gemm_phase(PG8_LAS unsigned char* lds, const Gemm g, const Sched& S, const Epi& E) {
;     ...
;             PG8_LDB(B0, 0, 0); PG8_LDB(B1, 0, 1); PG8_SCHED; PG8_LDA(At, 0, 0); PG8_STAGE(PG8_SA(1, 1), a1 + hstep, voffA);
;             PG8_WAIT_V(8); PG8_WAIT_L(0); PG8_BAR; PG8_MMA(0, 0, At, B0); PG8_MMA(0, 1, At, B1); PG8_BAR; PG8_SCHED;
;             PG8_LDA(At, 0, 1); PG8_STAGE(PG8_SB(0, 0), b2, voffB); PG8_STAGE(PG8_SB(0, 1), b2 + hstep, voffB); PG8_STAGE(PG8_SA(0, 0), a2, voffA);
;             PG8_WAIT_V(8); PG8_WAIT_L(0); PG8_BAR; PG8_MMA(1, 0, At, B0); PG8_MMA(1, 1, At, B1); PG8_BAR; PG8_SCHED;
.LBB0_1411:
	ds_read_b128 v[144:147], v159
	ds_read_b128 v[148:151], v159 offset:1024
	ds_read_b128 v[152:155], v159 offset:2048
	ds_read_b128 v[164:167], v159 offset:3072
	ds_read_b128 v[168:171], v160
	ds_read_b128 v[172:175], v160 offset:1024
	ds_read_b128 v[180:183], v160 offset:2048
	ds_read_b128 v[184:187], v160 offset:3072
	s_add_i32 s65, s34, 2
	s_add_u32 s66, s30, 0x80
	s_addc_u32 s35, s31, 0
	s_cmp_eq_u32 s41, s34
	s_cselect_b32 s34, s0, s66
	s_cselect_b32 s35, s1, s35
	s_cselect_b32 s67, s29, s64
	s_cselect_b32 s66, s28, s63
	v_lshl_add_u64 v[176:177], s[30:31], 0, v[136:137]
	s_add_i32 m0, s17, 0xc000
	ds_read_b128 v[188:191], v161
	ds_read_b128 v[192:195], v161 offset:1024
	ds_read_b128 v[196:199], v161 offset:2048
	ds_read_b128 v[200:203], v161 offset:3072
	ds_read_b128 v[204:207], v161 offset:4096
	ds_read_b128 v[208:211], v161 offset:5120
	ds_read_b128 v[212:215], v161 offset:6144
	ds_read_b128 v[216:219], v161 offset:7168
	global_load_lds_dwordx4 v[176:177], off
	v_lshl_add_u64 v[176:177], s[30:31], 0, v[138:139]
	s_add_i32 m0, s17, 0xe000
	s_nop 0
	global_load_lds_dwordx4 v[176:177], off
	s_waitcnt vmcnt(8)
	s_waitcnt lgkmcnt(0)
	s_barrier
	s_setprio 1
	s_waitcnt lgkmcnt(0)
	v_mfma_f32_16x16x32_bf16 v[124:127], v[144:147], v[188:191], v[124:127]
	v_mfma_f32_16x16x32_bf16 v[120:123], v[152:155], v[188:191], v[120:123]
	v_mfma_f32_16x16x32_bf16 v[116:119], v[144:147], v[196:199], v[116:119]
	v_mfma_f32_16x16x32_bf16 v[112:115], v[152:155], v[196:199], v[112:115]
	v_mfma_f32_16x16x32_bf16 v[104:107], v[144:147], v[204:207], v[104:107]
	v_mfma_f32_16x16x32_bf16 v[96:99], v[152:155], v[204:207], v[96:99]
	v_mfma_f32_16x16x32_bf16 v[88:91], v[144:147], v[212:215], v[88:91]
	v_mfma_f32_16x16x32_bf16 v[80:83], v[152:155], v[212:215], v[80:83]
	v_mfma_f32_16x16x32_bf16 v[124:127], v[148:151], v[192:195], v[124:127]
	v_mfma_f32_16x16x32_bf16 v[120:123], v[164:167], v[192:195], v[120:123]
	v_mfma_f32_16x16x32_bf16 v[116:119], v[148:151], v[200:203], v[116:119]
	v_mfma_f32_16x16x32_bf16 v[112:115], v[164:167], v[200:203], v[112:115]
	v_mfma_f32_16x16x32_bf16 v[104:107], v[148:151], v[208:211], v[104:107]
	v_mfma_f32_16x16x32_bf16 v[96:99], v[164:167], v[208:211], v[96:99]
	v_mfma_f32_16x16x32_bf16 v[88:91], v[148:151], v[216:219], v[88:91]
	v_mfma_f32_16x16x32_bf16 v[80:83], v[164:167], v[216:219], v[80:83]
	s_setprio 0
	s_setprio 1
	v_mfma_f32_16x16x32_bf16 v[108:111], v[168:171], v[188:191], v[108:111]
	v_mfma_f32_16x16x32_bf16 v[100:103], v[180:183], v[188:191], v[100:103]
	v_mfma_f32_16x16x32_bf16 v[92:95], v[168:171], v[196:199], v[92:95]
	v_mfma_f32_16x16x32_bf16 v[84:87], v[180:183], v[196:199], v[84:87]
	v_mfma_f32_16x16x32_bf16 v[76:79], v[168:171], v[204:207], v[76:79]
	v_mfma_f32_16x16x32_bf16 v[72:75], v[180:183], v[204:207], v[72:75]
	v_mfma_f32_16x16x32_bf16 v[68:71], v[168:171], v[212:215], v[68:71]
	v_mfma_f32_16x16x32_bf16 v[64:67], v[180:183], v[212:215], v[64:67]
	v_mfma_f32_16x16x32_bf16 v[108:111], v[172:175], v[192:195], v[108:111]
	v_mfma_f32_16x16x32_bf16 v[100:103], v[184:187], v[192:195], v[100:103]
	v_mfma_f32_16x16x32_bf16 v[92:95], v[172:175], v[200:203], v[92:95]
	v_mfma_f32_16x16x32_bf16 v[84:87], v[184:187], v[200:203], v[84:87]
	v_mfma_f32_16x16x32_bf16 v[76:79], v[172:175], v[208:211], v[76:79]
	v_mfma_f32_16x16x32_bf16 v[72:75], v[184:187], v[208:211], v[72:75]
	v_mfma_f32_16x16x32_bf16 v[68:71], v[172:175], v[216:219], v[68:71]
	v_mfma_f32_16x16x32_bf16 v[64:67], v[184:187], v[216:219], v[64:67]
	s_setprio 0
	s_barrier
	s_add_i32 s68, s57, s16
	v_lshl_add_u64 v[176:177], s[66:67], 0, v[130:131]
	s_mov_b32 m0, s68
	ds_read_b128 v[188:191], v161 offset:16384
	ds_read_b128 v[192:195], v161 offset:17408
	ds_read_b128 v[196:199], v161 offset:18432
	ds_read_b128 v[200:203], v161 offset:19456
	ds_read_b128 v[204:207], v161 offset:20480
	ds_read_b128 v[208:211], v161 offset:21504
	ds_read_b128 v[212:215], v161 offset:22528
	ds_read_b128 v[216:219], v161 offset:23552
	global_load_lds_dwordx4 v[176:177], off
	s_add_i32 m0, s68, 0x2000
	v_lshl_add_u64 v[178:179], s[66:67], 0, v[134:135]
	s_add_u32 s66, s66, s6
	s_addc_u32 s67, s67, s7
	s_add_i32 s68, s58, s16
	global_load_lds_dwordx4 v[178:179], off
	v_lshl_add_u64 v[220:221], s[66:67], 0, v[130:131]
	s_mov_b32 m0, s68
	v_lshl_add_u64 v[222:223], s[66:67], 0, v[134:135]
	global_load_lds_dwordx4 v[220:221], off
	s_add_i32 m0, s68, 0x2000
	v_lshl_add_u64 v[224:225], s[34:35], 0, v[128:129]
	global_load_lds_dwordx4 v[222:223], off
	s_mov_b32 m0, s17
	v_lshl_add_u64 v[226:227], s[34:35], 0, v[132:133]
	global_load_lds_dwordx4 v[224:225], off
	s_mov_b32 m0, s19
	s_nop 0
	global_load_lds_dwordx4 v[226:227], off
	s_waitcnt vmcnt(8)
	s_waitcnt lgkmcnt(0)
	s_barrier
; #define PG8_STAGE(bufoff, gbase, voff) do { _Pragma("unroll") for (int _i = 0; _i < 2; ++_i) \
;         __builtin_amdgcn_global_load_lds((const unsigned*)((const char*)(gbase) + (voff)[_i]), (PG8_LAS unsigned*)(lds + (bufoff) + ldsw + _i * 8192), 16, 0, 0); } while (0)
; #define PG8_LDA(dst, b, h) do { _Pragma("unroll") for (int m = 0; m < 4; ++m) _Pragma("unroll") for (int k = 0; k < 2; ++k) dst[m][k] = *(const PG8_LAS bf16x8*)(lds + PG8_SA(b, h) + aoff + m * 2048 + k * 1024); } while (0)
; #define PG8_LDB(dst, b, h) do { _Pragma("unroll") for (int n = 0; n < 2; ++n) _Pragma("unroll") for (int k = 0; k < 2; ++k) dst[n][k] = *(const PG8_LAS bf16x8*)(lds + PG8_SB(b, h) + boff + n * 2048 + k * 1024); } while (0)
; #define PG8_MMA(ai, bj, At, Bt) do { __builtin_amdgcn_s_setprio(1); _Pragma("unroll") for (int m = 0; m < 4; ++m) _Pragma("unroll") for (int n = 0; n < 2; ++n) _Pragma("unroll") for (int k = 0; k < 2; ++k) \
;         acc[ai][bj][m][n] = __builtin_amdgcn_mfma_f32_16x16x32_bf16(Bt[n][k], At[m][k], acc[ai][bj][m][n], 0, 0, 0); __builtin_amdgcn_s_setprio(0); } while (0)
; #define PG8_WAIT_V(n) asm volatile("s_waitcnt vmcnt(" #n ")" ::: "memory")
; #define PG8_WAIT_L(n) asm volatile("s_waitcnt lgkmcnt(" #n ")" ::: "memory")
; #define PG8_BAR __builtin_amdgcn_s_barrier()
; #define PG8_SCHED __builtin_amdgcn_sched_barrier(0)
; template <class Epi, class Sched, bool ALIGN_EPI = false, bool SP2 = false>
; __device__ __forceinline__ void gemm_phase(PG8_LAS unsigned char* lds, const Gemm g, const Sched& S, const Epi& E) {
;     ...
;             PG8_WAIT_V(8); PG8_WAIT_L(0); PG8_BAR; PG8_MMA(1, 0, At, B0); PG8_MMA(1, 1, At, B1); PG8_BAR; PG8_SCHED;
;             PG8_LDB(B0, 1, 0); PG8_LDB(B1, 1, 1); PG8_SCHED; PG8_LDA(At, 1, 0); PG8_STAGE(PG8_SA(0, 1), a2 + hstep, voffA);
;             PG8_WAIT_V(8); PG8_WAIT_L(0); PG8_BAR; PG8_MMA(0, 0, At, B0); PG8_MMA(0, 1, At, B1); PG8_BAR; PG8_SCHED;
	s_setprio 1
	s_waitcnt lgkmcnt(0)
	v_mfma_f32_16x16x32_bf16 v[60:63], v[144:147], v[188:191], v[60:63]
	v_mfma_f32_16x16x32_bf16 v[56:59], v[152:155], v[188:191], v[56:59]
	v_mfma_f32_16x16x32_bf16 v[52:55], v[144:147], v[196:199], v[52:55]
	v_mfma_f32_16x16x32_bf16 v[48:51], v[152:155], v[196:199], v[48:51]
	v_mfma_f32_16x16x32_bf16 v[40:43], v[144:147], v[204:207], v[40:43]
	v_mfma_f32_16x16x32_bf16 v[32:35], v[152:155], v[204:207], v[32:35]
	v_mfma_f32_16x16x32_bf16 v[24:27], v[144:147], v[212:215], v[24:27]
	v_mfma_f32_16x16x32_bf16 v[16:19], v[152:155], v[212:215], v[16:19]
	v_mfma_f32_16x16x32_bf16 v[60:63], v[148:151], v[192:195], v[60:63]
	v_mfma_f32_16x16x32_bf16 v[56:59], v[164:167], v[192:195], v[56:59]
	v_mfma_f32_16x16x32_bf16 v[52:55], v[148:151], v[200:203], v[52:55]
	v_mfma_f32_16x16x32_bf16 v[48:51], v[164:167], v[200:203], v[48:51]
	v_mfma_f32_16x16x32_bf16 v[40:43], v[148:151], v[208:211], v[40:43]
	v_mfma_f32_16x16x32_bf16 v[32:35], v[164:167], v[208:211], v[32:35]
	v_mfma_f32_16x16x32_bf16 v[24:27], v[148:151], v[216:219], v[24:27]
	v_mfma_f32_16x16x32_bf16 v[16:19], v[164:167], v[216:219], v[16:19]
	s_setprio 0
	s_setprio 1
	v_mfma_f32_16x16x32_bf16 v[44:47], v[168:171], v[188:191], v[44:47]
	v_mfma_f32_16x16x32_bf16 v[36:39], v[180:183], v[188:191], v[36:39]
	v_mfma_f32_16x16x32_bf16 v[28:31], v[168:171], v[196:199], v[28:31]
	v_mfma_f32_16x16x32_bf16 v[20:23], v[180:183], v[196:199], v[20:23]
	v_mfma_f32_16x16x32_bf16 v[12:15], v[168:171], v[204:207], v[12:15]
	v_mfma_f32_16x16x32_bf16 v[8:11], v[180:183], v[204:207], v[8:11]
	v_mfma_f32_16x16x32_bf16 v[4:7], v[168:171], v[212:215], v[4:7]
	v_mfma_f32_16x16x32_bf16 v[0:3], v[180:183], v[212:215], v[0:3]
	v_mfma_f32_16x16x32_bf16 v[44:47], v[172:175], v[192:195], v[44:47]
	v_mfma_f32_16x16x32_bf16 v[36:39], v[184:187], v[192:195], v[36:39]
	v_mfma_f32_16x16x32_bf16 v[28:31], v[172:175], v[200:203], v[28:31]
	v_mfma_f32_16x16x32_bf16 v[20:23], v[184:187], v[200:203], v[20:23]
	v_mfma_f32_16x16x32_bf16 v[12:15], v[172:175], v[208:211], v[12:15]
	v_mfma_f32_16x16x32_bf16 v[8:11], v[184:187], v[208:211], v[8:11]
	v_mfma_f32_16x16x32_bf16 v[4:7], v[172:175], v[216:219], v[4:7]
	v_mfma_f32_16x16x32_bf16 v[0:3], v[184:187], v[216:219], v[0:3]
	s_setprio 0
	s_barrier
	s_add_i32 s66, 0, 0x18000
	v_add_u32_e32 v163, s66, v157
	s_add_i32 s67, 0, 0x1c000
	ds_read_b128 v[144:147], v163
	ds_read_b128 v[148:151], v163 offset:1024
	ds_read_b128 v[152:155], v163 offset:2048
	ds_read_b128 v[164:167], v163 offset:3072
	v_add_u32_e32 v163, s67, v157
	ds_read_b128 v[168:171], v163
	ds_read_b128 v[172:175], v163 offset:1024
	ds_read_b128 v[180:183], v163 offset:2048
	ds_read_b128 v[184:187], v163 offset:3072
	s_add_u32 s34, s34, s6
	s_addc_u32 s35, s35, s7
	s_mov_b32 m0, s33
	v_lshl_add_u64 v[228:229], s[34:35], 0, v[128:129]
	ds_read_b128 v[188:191], v161 offset:32768
	ds_read_b128 v[192:195], v161 offset:33792
	ds_read_b128 v[196:199], v161 offset:34816
	ds_read_b128 v[200:203], v161 offset:35840
	ds_read_b128 v[204:207], v161 offset:36864
	ds_read_b128 v[208:211], v161 offset:37888
	ds_read_b128 v[212:215], v161 offset:38912
	ds_read_b128 v[216:219], v161 offset:39936
	global_load_lds_dwordx4 v[228:229], off
	v_lshl_add_u64 v[228:229], s[34:35], 0, v[132:133]
	s_mov_b32 m0, s36
	s_nop 0
	global_load_lds_dwordx4 v[228:229], off
	s_waitcnt vmcnt(8)
	s_waitcnt lgkmcnt(0)
	s_barrier
	s_setprio 1
	s_waitcnt lgkmcnt(0)
	v_mfma_f32_16x16x32_bf16 v[124:127], v[144:147], v[188:191], v[124:127]
	v_mfma_f32_16x16x32_bf16 v[120:123], v[152:155], v[188:191], v[120:123]
	v_mfma_f32_16x16x32_bf16 v[116:119], v[144:147], v[196:199], v[116:119]
	v_mfma_f32_16x16x32_bf16 v[112:115], v[152:155], v[196:199], v[112:115]
	v_mfma_f32_16x16x32_bf16 v[104:107], v[144:147], v[204:207], v[104:107]
	v_mfma_f32_16x16x32_bf16 v[96:99], v[152:155], v[204:207], v[96:99]
	v_mfma_f32_16x16x32_bf16 v[88:91], v[144:147], v[212:215], v[88:91]
	v_mfma_f32_16x16x32_bf16 v[80:83], v[152:155], v[212:215], v[80:83]
	v_mfma_f32_16x16x32_bf16 v[124:127], v[148:151], v[192:195], v[124:127]
	v_mfma_f32_16x16x32_bf16 v[120:123], v[164:167], v[192:195], v[120:123]
	v_mfma_f32_16x16x32_bf16 v[116:119], v[148:151], v[200:203], v[116:119]
	v_mfma_f32_16x16x32_bf16 v[112:115], v[164:167], v[200:203], v[112:115]
	v_mfma_f32_16x16x32_bf16 v[104:107], v[148:151], v[208:211], v[104:107]
	v_mfma_f32_16x16x32_bf16 v[96:99], v[164:167], v[208:211], v[96:99]
	v_mfma_f32_16x16x32_bf16 v[88:91], v[148:151], v[216:219], v[88:91]
	v_mfma_f32_16x16x32_bf16 v[80:83], v[164:167], v[216:219], v[80:83]
	s_setprio 0
	s_setprio 1
	v_mfma_f32_16x16x32_bf16 v[108:111], v[168:171], v[188:191], v[108:111]
	v_mfma_f32_16x16x32_bf16 v[100:103], v[180:183], v[188:191], v[100:103]
	v_mfma_f32_16x16x32_bf16 v[92:95], v[168:171], v[196:199], v[92:95]
	v_mfma_f32_16x16x32_bf16 v[84:87], v[180:183], v[196:199], v[84:87]
	v_mfma_f32_16x16x32_bf16 v[76:79], v[168:171], v[204:207], v[76:79]
	v_mfma_f32_16x16x32_bf16 v[72:75], v[180:183], v[204:207], v[72:75]
	v_mfma_f32_16x16x32_bf16 v[68:71], v[168:171], v[212:215], v[68:71]
	v_mfma_f32_16x16x32_bf16 v[64:67], v[180:183], v[212:215], v[64:67]
	v_mfma_f32_16x16x32_bf16 v[108:111], v[172:175], v[192:195], v[108:111]
	v_mfma_f32_16x16x32_bf16 v[100:103], v[184:187], v[192:195], v[100:103]
	v_mfma_f32_16x16x32_bf16 v[92:95], v[172:175], v[200:203], v[92:95]
	v_mfma_f32_16x16x32_bf16 v[84:87], v[184:187], v[200:203], v[84:87]
	v_mfma_f32_16x16x32_bf16 v[76:79], v[172:175], v[208:211], v[76:79]
	v_mfma_f32_16x16x32_bf16 v[72:75], v[184:187], v[208:211], v[72:75]
	v_mfma_f32_16x16x32_bf16 v[68:71], v[172:175], v[216:219], v[68:71]
	v_mfma_f32_16x16x32_bf16 v[64:67], v[184:187], v[216:219], v[64:67]
	s_setprio 0
	s_barrier
; #define PG8_STAGE(bufoff, gbase, voff) do { _Pragma("unroll") for (int _i = 0; _i < 2; ++_i) \
;         __builtin_amdgcn_global_load_lds((const unsigned*)((const char*)(gbase) + (voff)[_i]), (PG8_LAS unsigned*)(lds + (bufoff) + ldsw + _i * 8192), 16, 0, 0); } while (0)
; #define PG8_LDA(dst, b, h) do { _Pragma("unroll") for (int m = 0; m < 4; ++m) _Pragma("unroll") for (int k = 0; k < 2; ++k) dst[m][k] = *(const PG8_LAS bf16x8*)(lds + PG8_SA(b, h) + aoff + m * 2048 + k * 1024); } while (0)
; #define PG8_MMA(ai, bj, At, Bt) do { __builtin_amdgcn_s_setprio(1); _Pragma("unroll") for (int m = 0; m < 4; ++m) _Pragma("unroll") for (int n = 0; n < 2; ++n) _Pragma("unroll") for (int k = 0; k < 2; ++k) \
;         acc[ai][bj][m][n] = __builtin_amdgcn_mfma_f32_16x16x32_bf16(Bt[n][k], At[m][k], acc[ai][bj][m][n], 0, 0, 0); __builtin_amdgcn_s_setprio(0); } while (0)
; #define PG8_WAIT_V(n) asm volatile("s_waitcnt vmcnt(" #n ")" ::: "memory")
; #define PG8_WAIT_L(n) asm volatile("s_waitcnt lgkmcnt(" #n ")" ::: "memory")
; #define PG8_BAR __builtin_amdgcn_s_barrier()
; #define PG8_SCHED __builtin_amdgcn_sched_barrier(0)
; template <class Epi, class Sched, bool ALIGN_EPI = false, bool SP2 = false>
; __device__ __forceinline__ void gemm_phase(PG8_LAS unsigned char* lds, const Gemm g, const Sched& S, const Epi& E) {
;     ...
;             PG8_LDA(At, 1, 1); PG8_STAGE(PG8_SB(1, 0), b3, voffB); PG8_STAGE(PG8_SB(1, 1), b3 + hstep, voffB); PG8_STAGE(PG8_SA(1, 0), a3, voffA);
;             PG8_WAIT_V(8); PG8_WAIT_L(0); PG8_BAR; PG8_MMA(1, 0, At, B0); PG8_MMA(1, 1, At, B1); PG8_BAR; PG8_SCHED;
;     __device__ __forceinline__ void operator()(AccRef acc, const pg8::Unit& u, int wr, int wc, int fr, int fq) const {
;     ...
;                 const int row = row0 + ai * 128 + m * 16; float ss = 0.f;
; #pragma unroll
;                 for (int bj = 0; bj < 2; ++bj) {
;                     bf16_t* xp = xb + (size_t)row * D + col0 + bj * 128;
;                     f32x4 a, b; unpack8(*(const u32x4*)xp, a, b);
	s_add_i32 s34, s66, s16
	v_lshl_add_u64 v[176:177], v[176:177], 0, s[22:23]
	s_mov_b32 m0, s34
	ds_read_b128 v[188:191], v161 offset:49152
	ds_read_b128 v[192:195], v161 offset:50176
	ds_read_b128 v[196:199], v161 offset:51200
	ds_read_b128 v[200:203], v161 offset:52224
	ds_read_b128 v[204:207], v161 offset:53248
	ds_read_b128 v[208:211], v161 offset:54272
	ds_read_b128 v[212:215], v161 offset:55296
	ds_read_b128 v[216:219], v161 offset:56320
	global_load_lds_dwordx4 v[176:177], off
	v_lshl_add_u64 v[176:177], v[178:179], 0, s[22:23]
	s_add_i32 m0, s34, 0x2000
	s_add_i32 s34, s67, s16
	global_load_lds_dwordx4 v[176:177], off
	v_lshl_add_u64 v[176:177], v[220:221], 0, s[22:23]
	s_mov_b32 m0, s34
	s_nop 0
	global_load_lds_dwordx4 v[176:177], off
	v_lshl_add_u64 v[176:177], v[222:223], 0, s[22:23]
	s_add_i32 m0, s34, 0x2000
	s_nop 0
	global_load_lds_dwordx4 v[176:177], off
	v_lshl_add_u64 v[176:177], v[224:225], 0, s[22:23]
	s_mov_b32 m0, s37
	s_nop 0
	global_load_lds_dwordx4 v[176:177], off
	v_lshl_add_u64 v[176:177], v[226:227], 0, s[22:23]
	s_mov_b32 m0, s38
	s_nop 0
	global_load_lds_dwordx4 v[176:177], off
	s_waitcnt vmcnt(8)
	s_waitcnt lgkmcnt(0)
	s_barrier
	s_setprio 1
	s_waitcnt lgkmcnt(0)
	v_mfma_f32_16x16x32_bf16 v[60:63], v[144:147], v[188:191], v[60:63]
	v_mfma_f32_16x16x32_bf16 v[56:59], v[152:155], v[188:191], v[56:59]
	v_mfma_f32_16x16x32_bf16 v[52:55], v[144:147], v[196:199], v[52:55]
	v_mfma_f32_16x16x32_bf16 v[48:51], v[152:155], v[196:199], v[48:51]
	v_mfma_f32_16x16x32_bf16 v[40:43], v[144:147], v[204:207], v[40:43]
	v_mfma_f32_16x16x32_bf16 v[32:35], v[152:155], v[204:207], v[32:35]
	v_mfma_f32_16x16x32_bf16 v[24:27], v[144:147], v[212:215], v[24:27]
	v_mfma_f32_16x16x32_bf16 v[16:19], v[152:155], v[212:215], v[16:19]
	v_mfma_f32_16x16x32_bf16 v[60:63], v[148:151], v[192:195], v[60:63]
	v_mfma_f32_16x16x32_bf16 v[56:59], v[164:167], v[192:195], v[56:59]
	v_mfma_f32_16x16x32_bf16 v[52:55], v[148:151], v[200:203], v[52:55]
	v_mfma_f32_16x16x32_bf16 v[48:51], v[164:167], v[200:203], v[48:51]
	v_mfma_f32_16x16x32_bf16 v[40:43], v[148:151], v[208:211], v[40:43]
	v_mfma_f32_16x16x32_bf16 v[32:35], v[164:167], v[208:211], v[32:35]
	v_mfma_f32_16x16x32_bf16 v[24:27], v[148:151], v[216:219], v[24:27]
	v_mfma_f32_16x16x32_bf16 v[16:19], v[164:167], v[216:219], v[16:19]
	s_setprio 0
	s_setprio 1
	v_mfma_f32_16x16x32_bf16 v[44:47], v[168:171], v[188:191], v[44:47]
	v_mfma_f32_16x16x32_bf16 v[36:39], v[180:183], v[188:191], v[36:39]
	v_mfma_f32_16x16x32_bf16 v[28:31], v[168:171], v[196:199], v[28:31]
	v_mfma_f32_16x16x32_bf16 v[20:23], v[180:183], v[196:199], v[20:23]
	v_mfma_f32_16x16x32_bf16 v[12:15], v[168:171], v[204:207], v[12:15]
	v_mfma_f32_16x16x32_bf16 v[8:11], v[180:183], v[204:207], v[8:11]
	v_mfma_f32_16x16x32_bf16 v[4:7], v[168:171], v[212:215], v[4:7]
	v_mfma_f32_16x16x32_bf16 v[0:3], v[180:183], v[212:215], v[0:3]
	v_mfma_f32_16x16x32_bf16 v[44:47], v[172:175], v[192:195], v[44:47]
	v_mfma_f32_16x16x32_bf16 v[36:39], v[184:187], v[192:195], v[36:39]
	v_mfma_f32_16x16x32_bf16 v[28:31], v[172:175], v[200:203], v[28:31]
	v_mfma_f32_16x16x32_bf16 v[20:23], v[184:187], v[200:203], v[20:23]
	v_mfma_f32_16x16x32_bf16 v[12:15], v[172:175], v[208:211], v[12:15]
	v_mfma_f32_16x16x32_bf16 v[8:11], v[184:187], v[208:211], v[8:11]
	v_mfma_f32_16x16x32_bf16 v[4:7], v[172:175], v[216:219], v[4:7]
	v_mfma_f32_16x16x32_bf16 v[0:3], v[184:187], v[216:219], v[0:3]
	s_setprio 0
	s_barrier
	s_add_u32 s30, s30, 0x100
	s_addc_u32 s31, s31, 0
	s_add_u32 s63, s63, 0x100
	s_addc_u32 s64, s64, 0
	s_cmp_ge_i32 s65, s40
	s_mov_b32 s34, s65
	s_cbranch_scc0 .LBB0_1411
.LBB0_1413:
	s_and_b64 vcc, exec, s[26:27]
	s_cbranch_vccz .LBB0_1415
	s_barrier
.LBB0_1415:
.Lres_beg2:
	v_lshl_add_u32 v170, s62, 8, v156
	v_lshl_or_b32 v169, s14, 8, v158
	v_lshlrev_b32_e32 v169, 1, v169
	v_lshl_add_u32 v168, v170, 11, v169
	v_add_u32_e32 v169, 0x18000, v168
	global_load_dwordx4 v[180:183], v169, s[42:43]
	global_load_dwordx4 v[184:187], v169, s[42:43] offset:256
	v_add_u32_e32 v169, 0x40000, v168
	global_load_dwordx4 v[188:191], v169, s[42:43]
	global_load_dwordx4 v[192:195], v169, s[42:43] offset:256
	v_add_u32_e32 v169, 0x48000, v168
	global_load_dwordx4 v[196:199], v169, s[42:43]
	global_load_dwordx4 v[200:203], v169, s[42:43] offset:256
	v_add_u32_e32 v169, 0x50000, v168
	global_load_dwordx4 v[204:207], v169, s[42:43]
	global_load_dwordx4 v[208:211], v169, s[42:43] offset:256
	v_bfe_u32 v171, v158, 5, 2
	v_lshl_add_u32 v171, s14, 2, v171
	v_lshlrev_b32_e32 v171, 2, v171
	v_lshl_add_u32 v170, v170, 6, v171
	v_add_u32_e32 v173, 0x2000, v170
	v_mbcnt_lo_u32_b32 v172, -1, 0
	v_mbcnt_hi_u32_b32 v172, -1, v172
	v_xor_b32_e32 v171, 16, v172
	v_xor_b32_e32 v172, 32, v172
	v_lshlrev_b32_e32 v171, 2, v171
	v_lshlrev_b32_e32 v172, 2, v172
	v_mov_b32_e32 v169, v168
	s_waitcnt vmcnt(8)
;     __device__ __forceinline__ void operator()(AccRef acc, const pg8::Unit& u, int wr, int wc, int fr, int fq) const {
;     ...
;                 const int row = row0 + ai * 128 + m * 16; float ss = 0.f;
; #pragma unroll
;                 for (int bj = 0; bj < 2; ++bj) {
;                     bf16_t* xp = xb + (size_t)row * D + col0 + bj * 128;
;                     f32x4 a, b; unpack8(*(const u32x4*)xp, a, b);
;                     a += acc[ai][bj][m][0] * alpha; b += acc[ai][bj][m][1] * alpha;
;                     *(u32x4*)xp = pack8(a, b);
;                     ss += (a[0] * a[0] + a[1] * a[1]) + (a[2] * a[2] + a[3] * a[3]) + (b[0] * b[0] + b[1] * b[1]) + (b[2] * b[2] + b[3] * b[3]);
;                 }
	v_pk_mul_f32 v[124:125], v[124:125], 0.5 op_sel_hi:[1,0]
	v_pk_mul_f32 v[126:127], v[126:127], 0.5 op_sel_hi:[1,0]
	v_pk_mul_f32 v[120:121], v[120:121], 0.5 op_sel_hi:[1,0]
	v_pk_mul_f32 v[122:123], v[122:123], 0.5 op_sel_hi:[1,0]
	v_lshlrev_b32_e32 v212, 16, v231
	v_and_b32_e32 v213, 0xffff0000, v231
	v_and_b32_e32 v231, 0xffff0000, v230
	v_lshlrev_b32_e32 v230, 16, v230
	v_lshlrev_b32_e32 v214, 16, v233
	v_and_b32_e32 v215, 0xffff0000, v233
	v_and_b32_e32 v233, 0xffff0000, v232
	v_lshlrev_b32_e32 v232, 16, v232
	v_pk_add_f32 v[230:231], v[124:125], v[230:231]
	v_pk_add_f32 v[212:213], v[126:127], v[212:213]
	v_pk_add_f32 v[232:233], v[120:121], v[232:233]
	v_pk_add_f32 v[214:215], v[122:123], v[214:215]
	v_cvt_pk_bf16_f32 v124, v230, v231
	v_cvt_pk_bf16_f32 v125, v212, v213
	v_cvt_pk_bf16_f32 v126, v232, v233
	v_cvt_pk_bf16_f32 v127, v214, v215
	global_store_dwordx4 v169, v[124:127], s[42:43]
	v_mul_f32_e32 v120, v231, v231
	v_mul_f32_e32 v121, v213, v213
	v_mul_f32_e32 v122, v233, v233
	v_mul_f32_e32 v123, v215, v215
	v_fmac_f32_e32 v120, v230, v230
	v_fmac_f32_e32 v121, v212, v212
	v_fmac_f32_e32 v122, v232, v232
	v_fmac_f32_e32 v123, v214, v214
	v_add_f32_e32 v120, v120, v121
	v_add_f32_e32 v120, v122, v120
	v_add_f32_e32 v120, v123, v120
	s_nop 0
	v_pk_mul_f32 v[108:109], v[108:109], 0.5 op_sel_hi:[1,0]
	v_pk_mul_f32 v[110:111], v[110:111], 0.5 op_sel_hi:[1,0]
	v_pk_mul_f32 v[100:101], v[100:101], 0.5 op_sel_hi:[1,0]
	v_pk_mul_f32 v[102:103], v[102:103], 0.5 op_sel_hi:[1,0]
	v_lshlrev_b32_e32 v212, 16, v235
	v_and_b32_e32 v213, 0xffff0000, v235
	v_and_b32_e32 v235, 0xffff0000, v234
	v_lshlrev_b32_e32 v234, 16, v234
	v_lshlrev_b32_e32 v214, 16, v237
	v_and_b32_e32 v215, 0xffff0000, v237
	v_and_b32_e32 v237, 0xffff0000, v236
	v_lshlrev_b32_e32 v236, 16, v236
	v_pk_add_f32 v[234:235], v[108:109], v[234:235]
	v_pk_add_f32 v[212:213], v[110:111], v[212:213]
	v_pk_add_f32 v[236:237], v[100:101], v[236:237]
	v_pk_add_f32 v[214:215], v[102:103], v[214:215]
	v_cvt_pk_bf16_f32 v108, v234, v235
	v_cvt_pk_bf16_f32 v109, v212, v213
	v_cvt_pk_bf16_f32 v110, v236, v237
	v_cvt_pk_bf16_f32 v111, v214, v215
	global_store_dwordx4 v169, v[108:111], s[42:43] offset:256
	v_mul_f32_e32 v100, v235, v235
	v_mul_f32_e32 v101, v213, v213
	v_mul_f32_e32 v102, v237, v237
	v_mul_f32_e32 v103, v215, v215
	v_fmac_f32_e32 v100, v234, v234
	v_fmac_f32_e32 v101, v212, v212
	v_fmac_f32_e32 v102, v236, v236
	v_fmac_f32_e32 v103, v214, v214
	v_add_f32_e32 v100, v100, v101
	v_add_f32_e32 v100, v102, v100
	v_add_f32_e32 v100, v103, v100
	v_add_f32_e32 v120, v120, v100
	v_add_u32_e32 v169, 0x58000, v168
	global_load_dwordx4 v[230:233], v169, s[42:43]
	global_load_dwordx4 v[234:237], v169, s[42:43] offset:256
	v_add_u32_e32 v169, 0x8000, v168
	s_nop 0
	v_pk_mul_f32 v[116:117], v[116:117], 0.5 op_sel_hi:[1,0]
	v_pk_mul_f32 v[118:119], v[118:119], 0.5 op_sel_hi:[1,0]
	v_pk_mul_f32 v[112:113], v[112:113], 0.5 op_sel_hi:[1,0]
	v_pk_mul_f32 v[114:115], v[114:115], 0.5 op_sel_hi:[1,0]
	v_lshlrev_b32_e32 v212, 16, v239
	v_and_b32_e32 v213, 0xffff0000, v239
	v_and_b32_e32 v239, 0xffff0000, v238
	v_lshlrev_b32_e32 v238, 16, v238
	v_lshlrev_b32_e32 v214, 16, v241
	v_and_b32_e32 v215, 0xffff0000, v241
	v_and_b32_e32 v241, 0xffff0000, v240
	v_lshlrev_b32_e32 v240, 16, v240
	v_pk_add_f32 v[238:239], v[116:117], v[238:239]
	v_pk_add_f32 v[212:213], v[118:119], v[212:213]
	v_pk_add_f32 v[240:241], v[112:113], v[240:241]
	v_pk_add_f32 v[214:215], v[114:115], v[214:215]
	v_cvt_pk_bf16_f32 v116, v238, v239
	v_cvt_pk_bf16_f32 v117, v212, v213
	v_cvt_pk_bf16_f32 v118, v240, v241
	v_cvt_pk_bf16_f32 v119, v214, v215
	global_store_dwordx4 v169, v[116:119], s[42:43]
	v_mul_f32_e32 v112, v239, v239
	v_mul_f32_e32 v113, v213, v213
	v_mul_f32_e32 v114, v241, v241
	v_mul_f32_e32 v115, v215, v215
	v_fmac_f32_e32 v112, v238, v238
	v_fmac_f32_e32 v113, v212, v212
	v_fmac_f32_e32 v114, v240, v240
	v_fmac_f32_e32 v115, v214, v214
	v_add_f32_e32 v112, v112, v113
	v_add_f32_e32 v112, v114, v112
	v_add_f32_e32 v112, v115, v112
	s_nop 0
	v_pk_mul_f32 v[92:93], v[92:93], 0.5 op_sel_hi:[1,0]
	v_pk_mul_f32 v[94:95], v[94:95], 0.5 op_sel_hi:[1,0]
	v_pk_mul_f32 v[84:85], v[84:85], 0.5 op_sel_hi:[1,0]
	v_pk_mul_f32 v[86:87], v[86:87], 0.5 op_sel_hi:[1,0]
	v_lshlrev_b32_e32 v212, 16, v243
	v_and_b32_e32 v213, 0xffff0000, v243
	v_and_b32_e32 v243, 0xffff0000, v242
	v_lshlrev_b32_e32 v242, 16, v242
	v_lshlrev_b32_e32 v214, 16, v245
	v_and_b32_e32 v215, 0xffff0000, v245
	v_and_b32_e32 v245, 0xffff0000, v244
	v_lshlrev_b32_e32 v244, 16, v244
	v_pk_add_f32 v[242:243], v[92:93], v[242:243]
	v_pk_add_f32 v[212:213], v[94:95], v[212:213]
	v_pk_add_f32 v[244:245], v[84:85], v[244:245]
	v_pk_add_f32 v[214:215], v[86:87], v[214:215]
	v_cvt_pk_bf16_f32 v92, v242, v243
	v_cvt_pk_bf16_f32 v93, v212, v213
	v_cvt_pk_bf16_f32 v94, v244, v245
	v_cvt_pk_bf16_f32 v95, v214, v215
	global_store_dwordx4 v169, v[92:95], s[42:43] offset:256
	v_mul_f32_e32 v84, v243, v243
	v_mul_f32_e32 v85, v213, v213
	v_mul_f32_e32 v86, v245, v245
	v_mul_f32_e32 v87, v215, v215
	v_fmac_f32_e32 v84, v242, v242
	v_fmac_f32_e32 v85, v212, v212
	v_fmac_f32_e32 v86, v244, v244
	v_fmac_f32_e32 v87, v214, v214
	v_add_f32_e32 v84, v84, v85
	v_add_f32_e32 v84, v86, v84
	v_add_f32_e32 v84, v87, v84
	v_add_f32_e32 v112, v112, v84
	v_add_u32_e32 v169, 0x10000, v168
	s_nop 0
	v_pk_mul_f32 v[104:105], v[104:105], 0.5 op_sel_hi:[1,0]
	v_pk_mul_f32 v[106:107], v[106:107], 0.5 op_sel_hi:[1,0]
	v_pk_mul_f32 v[96:97], v[96:97], 0.5 op_sel_hi:[1,0]
	v_pk_mul_f32 v[98:99], v[98:99], 0.5 op_sel_hi:[1,0]
	v_lshlrev_b32_e32 v212, 16, v247
	v_and_b32_e32 v213, 0xffff0000, v247
;     __device__ __forceinline__ void operator()(AccRef acc, const pg8::Unit& u, int wr, int wc, int fr, int fq) const {
;     ...
;                 const int row = row0 + ai * 128 + m * 16; float ss = 0.f;
; #pragma unroll
;                 for (int bj = 0; bj < 2; ++bj) {
;                     bf16_t* xp = xb + (size_t)row * D + col0 + bj * 128;
;                     f32x4 a, b; unpack8(*(const u32x4*)xp, a, b);
;                     a += acc[ai][bj][m][0] * alpha; b += acc[ai][bj][m][1] * alpha;
;                     *(u32x4*)xp = pack8(a, b);
;                     ss += (a[0] * a[0] + a[1] * a[1]) + (a[2] * a[2] + a[3] * a[3]) + (b[0] * b[0] + b[1] * b[1]) + (b[2] * b[2] + b[3] * b[3]);
;                 }
	v_and_b32_e32 v247, 0xffff0000, v246
	v_lshlrev_b32_e32 v246, 16, v246
	v_lshlrev_b32_e32 v214, 16, v249
	v_and_b32_e32 v215, 0xffff0000, v249
	v_and_b32_e32 v249, 0xffff0000, v248
	v_lshlrev_b32_e32 v248, 16, v248
	v_pk_add_f32 v[246:247], v[104:105], v[246:247]
	v_pk_add_f32 v[212:213], v[106:107], v[212:213]
	v_pk_add_f32 v[248:249], v[96:97], v[248:249]
	v_pk_add_f32 v[214:215], v[98:99], v[214:215]
	v_cvt_pk_bf16_f32 v104, v246, v247
	v_cvt_pk_bf16_f32 v105, v212, v213
	v_cvt_pk_bf16_f32 v106, v248, v249
	v_cvt_pk_bf16_f32 v107, v214, v215
	global_store_dwordx4 v169, v[104:107], s[42:43]
	v_mul_f32_e32 v96, v247, v247
	v_mul_f32_e32 v97, v213, v213
	v_mul_f32_e32 v98, v249, v249
	v_mul_f32_e32 v99, v215, v215
	v_fmac_f32_e32 v96, v246, v246
	v_fmac_f32_e32 v97, v212, v212
	v_fmac_f32_e32 v98, v248, v248
	v_fmac_f32_e32 v99, v214, v214
	v_add_f32_e32 v96, v96, v97
	v_add_f32_e32 v96, v98, v96
	v_add_f32_e32 v96, v99, v96
	s_nop 0
	v_pk_mul_f32 v[76:77], v[76:77], 0.5 op_sel_hi:[1,0]
	v_pk_mul_f32 v[78:79], v[78:79], 0.5 op_sel_hi:[1,0]
	v_pk_mul_f32 v[72:73], v[72:73], 0.5 op_sel_hi:[1,0]
	v_pk_mul_f32 v[74:75], v[74:75], 0.5 op_sel_hi:[1,0]
	v_lshlrev_b32_e32 v212, 16, v251
	v_and_b32_e32 v213, 0xffff0000, v251
	v_and_b32_e32 v251, 0xffff0000, v250
	v_lshlrev_b32_e32 v250, 16, v250
	v_lshlrev_b32_e32 v214, 16, v253
	v_and_b32_e32 v215, 0xffff0000, v253
	v_and_b32_e32 v253, 0xffff0000, v252
	v_lshlrev_b32_e32 v252, 16, v252
	v_pk_add_f32 v[250:251], v[76:77], v[250:251]
	v_pk_add_f32 v[212:213], v[78:79], v[212:213]
	v_pk_add_f32 v[252:253], v[72:73], v[252:253]
	v_pk_add_f32 v[214:215], v[74:75], v[214:215]
	v_cvt_pk_bf16_f32 v76, v250, v251
	v_cvt_pk_bf16_f32 v77, v212, v213
	v_cvt_pk_bf16_f32 v78, v252, v253
	v_cvt_pk_bf16_f32 v79, v214, v215
	global_store_dwordx4 v169, v[76:79], s[42:43] offset:256
	v_mul_f32_e32 v72, v251, v251
	v_mul_f32_e32 v73, v213, v213
	v_mul_f32_e32 v74, v253, v253
	v_mul_f32_e32 v75, v215, v215
	v_fmac_f32_e32 v72, v250, v250
	v_fmac_f32_e32 v73, v212, v212
	v_fmac_f32_e32 v74, v252, v252
	v_fmac_f32_e32 v75, v214, v214
	v_add_f32_e32 v72, v72, v73
	v_add_f32_e32 v72, v74, v72
	v_add_f32_e32 v72, v75, v72
	v_add_f32_e32 v96, v96, v72
	v_add_u32_e32 v169, 0x18000, v168
	s_waitcnt vmcnt(15)
	v_pk_mul_f32 v[88:89], v[88:89], 0.5 op_sel_hi:[1,0]
	v_pk_mul_f32 v[90:91], v[90:91], 0.5 op_sel_hi:[1,0]
	v_pk_mul_f32 v[80:81], v[80:81], 0.5 op_sel_hi:[1,0]
	v_pk_mul_f32 v[82:83], v[82:83], 0.5 op_sel_hi:[1,0]
	v_lshlrev_b32_e32 v212, 16, v181
	v_and_b32_e32 v213, 0xffff0000, v181
	v_and_b32_e32 v181, 0xffff0000, v180
	v_lshlrev_b32_e32 v180, 16, v180
	v_lshlrev_b32_e32 v214, 16, v183
	v_and_b32_e32 v215, 0xffff0000, v183
	v_and_b32_e32 v183, 0xffff0000, v182
	v_lshlrev_b32_e32 v182, 16, v182
	v_pk_add_f32 v[180:181], v[88:89], v[180:181]
	v_pk_add_f32 v[212:213], v[90:91], v[212:213]
	v_pk_add_f32 v[182:183], v[80:81], v[182:183]
	v_pk_add_f32 v[214:215], v[82:83], v[214:215]
	v_cvt_pk_bf16_f32 v88, v180, v181
	v_cvt_pk_bf16_f32 v89, v212, v213
	v_cvt_pk_bf16_f32 v90, v182, v183
	v_cvt_pk_bf16_f32 v91, v214, v215
	global_store_dwordx4 v169, v[88:91], s[42:43]
	v_mul_f32_e32 v80, v181, v181
	v_mul_f32_e32 v81, v213, v213
	v_mul_f32_e32 v82, v183, v183
	v_mul_f32_e32 v83, v215, v215
	v_fmac_f32_e32 v80, v180, v180
	v_fmac_f32_e32 v81, v212, v212
	v_fmac_f32_e32 v82, v182, v182
	v_fmac_f32_e32 v83, v214, v214
	v_add_f32_e32 v80, v80, v81
	v_add_f32_e32 v80, v82, v80
	v_add_f32_e32 v80, v83, v80
	s_waitcnt vmcnt(15)
	v_pk_mul_f32 v[68:69], v[68:69], 0.5 op_sel_hi:[1,0]
	v_pk_mul_f32 v[70:71], v[70:71], 0.5 op_sel_hi:[1,0]
	v_pk_mul_f32 v[64:65], v[64:65], 0.5 op_sel_hi:[1,0]
	v_pk_mul_f32 v[66:67], v[66:67], 0.5 op_sel_hi:[1,0]
	v_lshlrev_b32_e32 v212, 16, v185
	v_and_b32_e32 v213, 0xffff0000, v185
	v_and_b32_e32 v185, 0xffff0000, v184
	v_lshlrev_b32_e32 v184, 16, v184
	v_lshlrev_b32_e32 v214, 16, v187
	v_and_b32_e32 v215, 0xffff0000, v187
	v_and_b32_e32 v187, 0xffff0000, v186
	v_lshlrev_b32_e32 v186, 16, v186
	v_pk_add_f32 v[184:185], v[68:69], v[184:185]
	v_pk_add_f32 v[212:213], v[70:71], v[212:213]
	v_pk_add_f32 v[186:187], v[64:65], v[186:187]
	v_pk_add_f32 v[214:215], v[66:67], v[214:215]
	v_cvt_pk_bf16_f32 v68, v184, v185
	v_cvt_pk_bf16_f32 v69, v212, v213
	v_cvt_pk_bf16_f32 v70, v186, v187
	v_cvt_pk_bf16_f32 v71, v214, v215
	global_store_dwordx4 v169, v[68:71], s[42:43] offset:256
	v_mul_f32_e32 v64, v185, v185
	v_mul_f32_e32 v65, v213, v213
	v_mul_f32_e32 v66, v187, v187
	v_mul_f32_e32 v67, v215, v215
	v_fmac_f32_e32 v64, v184, v184
	v_fmac_f32_e32 v65, v212, v212
	v_fmac_f32_e32 v66, v186, v186
	v_fmac_f32_e32 v67, v214, v214
	v_add_f32_e32 v64, v64, v65
	v_add_f32_e32 v64, v66, v64
	v_add_f32_e32 v64, v67, v64
	v_add_f32_e32 v80, v80, v64
	v_add_u32_e32 v169, 0x40000, v168
	s_waitcnt vmcnt(15)
	v_pk_mul_f32 v[60:61], v[60:61], 0.5 op_sel_hi:[1,0]
	v_pk_mul_f32 v[62:63], v[62:63], 0.5 op_sel_hi:[1,0]
	v_pk_mul_f32 v[56:57], v[56:57], 0.5 op_sel_hi:[1,0]
	v_pk_mul_f32 v[58:59], v[58:59], 0.5 op_sel_hi:[1,0]
	v_lshlrev_b32_e32 v212, 16, v189
	v_and_b32_e32 v213, 0xffff0000, v189
	v_and_b32_e32 v189, 0xffff0000, v188
	v_lshlrev_b32_e32 v188, 16, v188
	v_lshlrev_b32_e32 v214, 16, v191
	v_and_b32_e32 v215, 0xffff0000, v191
	v_and_b32_e32 v191, 0xffff0000, v190
	v_lshlrev_b32_e32 v190, 16, v190
	v_pk_add_f32 v[188:189], v[60:61], v[188:189]
	v_pk_add_f32 v[212:213], v[62:63], v[212:213]
	v_pk_add_f32 v[190:191], v[56:57], v[190:191]
	v_pk_add_f32 v[214:215], v[58:59], v[214:215]
	v_cvt_pk_bf16_f32 v60, v188, v189
	v_cvt_pk_bf16_f32 v61, v212, v213
	v_cvt_pk_bf16_f32 v62, v190, v191
	v_cvt_pk_bf16_f32 v63, v214, v215
	global_store_dwordx4 v169, v[60:63], s[42:43]
	v_mul_f32_e32 v56, v189, v189
	v_mul_f32_e32 v57, v213, v213
	v_mul_f32_e32 v58, v191, v191
	v_mul_f32_e32 v59, v215, v215
	v_fmac_f32_e32 v56, v188, v188
	v_fmac_f32_e32 v57, v212, v212
	v_fmac_f32_e32 v58, v190, v190
	v_fmac_f32_e32 v59, v214, v214
	v_add_f32_e32 v56, v56, v57
	v_add_f32_e32 v56, v58, v56
	v_add_f32_e32 v56, v59, v56
	s_waitcnt vmcnt(15)
;     __device__ __forceinline__ void operator()(AccRef acc, const pg8::Unit& u, int wr, int wc, int fr, int fq) const {
;     ...
;                 const int row = row0 + ai * 128 + m * 16; float ss = 0.f;
; #pragma unroll
;                 for (int bj = 0; bj < 2; ++bj) {
;                     bf16_t* xp = xb + (size_t)row * D + col0 + bj * 128;
;                     f32x4 a, b; unpack8(*(const u32x4*)xp, a, b);
;                     a += acc[ai][bj][m][0] * alpha; b += acc[ai][bj][m][1] * alpha;
;                     *(u32x4*)xp = pack8(a, b);
;                     ss += (a[0] * a[0] + a[1] * a[1]) + (a[2] * a[2] + a[3] * a[3]) + (b[0] * b[0] + b[1] * b[1]) + (b[2] * b[2] + b[3] * b[3]);
;                 }
	v_pk_mul_f32 v[44:45], v[44:45], 0.5 op_sel_hi:[1,0]
	v_pk_mul_f32 v[46:47], v[46:47], 0.5 op_sel_hi:[1,0]
	v_pk_mul_f32 v[36:37], v[36:37], 0.5 op_sel_hi:[1,0]
	v_pk_mul_f32 v[38:39], v[38:39], 0.5 op_sel_hi:[1,0]
	v_lshlrev_b32_e32 v212, 16, v193
	v_and_b32_e32 v213, 0xffff0000, v193
	v_and_b32_e32 v193, 0xffff0000, v192
	v_lshlrev_b32_e32 v192, 16, v192
	v_lshlrev_b32_e32 v214, 16, v195
	v_and_b32_e32 v215, 0xffff0000, v195
	v_and_b32_e32 v195, 0xffff0000, v194
	v_lshlrev_b32_e32 v194, 16, v194
	v_pk_add_f32 v[192:193], v[44:45], v[192:193]
	v_pk_add_f32 v[212:213], v[46:47], v[212:213]
	v_pk_add_f32 v[194:195], v[36:37], v[194:195]
	v_pk_add_f32 v[214:215], v[38:39], v[214:215]
	v_cvt_pk_bf16_f32 v44, v192, v193
	v_cvt_pk_bf16_f32 v45, v212, v213
	v_cvt_pk_bf16_f32 v46, v194, v195
	v_cvt_pk_bf16_f32 v47, v214, v215
	global_store_dwordx4 v169, v[44:47], s[42:43] offset:256
	v_mul_f32_e32 v36, v193, v193
	v_mul_f32_e32 v37, v213, v213
	v_mul_f32_e32 v38, v195, v195
	v_mul_f32_e32 v39, v215, v215
	v_fmac_f32_e32 v36, v192, v192
	v_fmac_f32_e32 v37, v212, v212
	v_fmac_f32_e32 v38, v194, v194
	v_fmac_f32_e32 v39, v214, v214
	v_add_f32_e32 v36, v36, v37
	v_add_f32_e32 v36, v38, v36
	v_add_f32_e32 v36, v39, v36
	v_add_f32_e32 v56, v56, v36
	v_add_u32_e32 v169, 0x48000, v168
	s_waitcnt vmcnt(15)
	v_pk_mul_f32 v[52:53], v[52:53], 0.5 op_sel_hi:[1,0]
	v_pk_mul_f32 v[54:55], v[54:55], 0.5 op_sel_hi:[1,0]
	v_pk_mul_f32 v[48:49], v[48:49], 0.5 op_sel_hi:[1,0]
	v_pk_mul_f32 v[50:51], v[50:51], 0.5 op_sel_hi:[1,0]
	v_lshlrev_b32_e32 v212, 16, v197
	v_and_b32_e32 v213, 0xffff0000, v197
	v_and_b32_e32 v197, 0xffff0000, v196
	v_lshlrev_b32_e32 v196, 16, v196
	v_lshlrev_b32_e32 v214, 16, v199
	v_and_b32_e32 v215, 0xffff0000, v199
	v_and_b32_e32 v199, 0xffff0000, v198
	v_lshlrev_b32_e32 v198, 16, v198
	v_pk_add_f32 v[196:197], v[52:53], v[196:197]
	v_pk_add_f32 v[212:213], v[54:55], v[212:213]
	v_pk_add_f32 v[198:199], v[48:49], v[198:199]
	v_pk_add_f32 v[214:215], v[50:51], v[214:215]
	v_cvt_pk_bf16_f32 v52, v196, v197
	v_cvt_pk_bf16_f32 v53, v212, v213
	v_cvt_pk_bf16_f32 v54, v198, v199
	v_cvt_pk_bf16_f32 v55, v214, v215
	global_store_dwordx4 v169, v[52:55], s[42:43]
	v_mul_f32_e32 v48, v197, v197
	v_mul_f32_e32 v49, v213, v213
	v_mul_f32_e32 v50, v199, v199
	v_mul_f32_e32 v51, v215, v215
	v_fmac_f32_e32 v48, v196, v196
	v_fmac_f32_e32 v49, v212, v212
	v_fmac_f32_e32 v50, v198, v198
	v_fmac_f32_e32 v51, v214, v214
	v_add_f32_e32 v48, v48, v49
	v_add_f32_e32 v48, v50, v48
	v_add_f32_e32 v48, v51, v48
	s_waitcnt vmcnt(15)
	v_pk_mul_f32 v[28:29], v[28:29], 0.5 op_sel_hi:[1,0]
	v_pk_mul_f32 v[30:31], v[30:31], 0.5 op_sel_hi:[1,0]
	v_pk_mul_f32 v[20:21], v[20:21], 0.5 op_sel_hi:[1,0]
	v_pk_mul_f32 v[22:23], v[22:23], 0.5 op_sel_hi:[1,0]
	v_lshlrev_b32_e32 v212, 16, v201
	v_and_b32_e32 v213, 0xffff0000, v201
	v_and_b32_e32 v201, 0xffff0000, v200
	v_lshlrev_b32_e32 v200, 16, v200
	v_lshlrev_b32_e32 v214, 16, v203
	v_and_b32_e32 v215, 0xffff0000, v203
	v_and_b32_e32 v203, 0xffff0000, v202
	v_lshlrev_b32_e32 v202, 16, v202
	v_pk_add_f32 v[200:201], v[28:29], v[200:201]
	v_pk_add_f32 v[212:213], v[30:31], v[212:213]
	v_pk_add_f32 v[202:203], v[20:21], v[202:203]
	v_pk_add_f32 v[214:215], v[22:23], v[214:215]
	v_cvt_pk_bf16_f32 v28, v200, v201
	v_cvt_pk_bf16_f32 v29, v212, v213
	v_cvt_pk_bf16_f32 v30, v202, v203
	v_cvt_pk_bf16_f32 v31, v214, v215
	global_store_dwordx4 v169, v[28:31], s[42:43] offset:256
	v_mul_f32_e32 v20, v201, v201
	v_mul_f32_e32 v21, v213, v213
	v_mul_f32_e32 v22, v203, v203
	v_mul_f32_e32 v23, v215, v215
	v_fmac_f32_e32 v20, v200, v200
	v_fmac_f32_e32 v21, v212, v212
	v_fmac_f32_e32 v22, v202, v202
	v_fmac_f32_e32 v23, v214, v214
	v_add_f32_e32 v20, v20, v21
	v_add_f32_e32 v20, v22, v20
	v_add_f32_e32 v20, v23, v20
	v_add_f32_e32 v48, v48, v20
	v_add_u32_e32 v169, 0x50000, v168
	s_waitcnt vmcnt(15)
	v_pk_mul_f32 v[40:41], v[40:41], 0.5 op_sel_hi:[1,0]
	v_pk_mul_f32 v[42:43], v[42:43], 0.5 op_sel_hi:[1,0]
	v_pk_mul_f32 v[32:33], v[32:33], 0.5 op_sel_hi:[1,0]
	v_pk_mul_f32 v[34:35], v[34:35], 0.5 op_sel_hi:[1,0]
	v_lshlrev_b32_e32 v212, 16, v205
	v_and_b32_e32 v213, 0xffff0000, v205
	v_and_b32_e32 v205, 0xffff0000, v204
	v_lshlrev_b32_e32 v204, 16, v204
	v_lshlrev_b32_e32 v214, 16, v207
	v_and_b32_e32 v215, 0xffff0000, v207
	v_and_b32_e32 v207, 0xffff0000, v206
	v_lshlrev_b32_e32 v206, 16, v206
	v_pk_add_f32 v[204:205], v[40:41], v[204:205]
	v_pk_add_f32 v[212:213], v[42:43], v[212:213]
	v_pk_add_f32 v[206:207], v[32:33], v[206:207]
	v_pk_add_f32 v[214:215], v[34:35], v[214:215]
	v_cvt_pk_bf16_f32 v40, v204, v205
	v_cvt_pk_bf16_f32 v41, v212, v213
	v_cvt_pk_bf16_f32 v42, v206, v207
	v_cvt_pk_bf16_f32 v43, v214, v215
	global_store_dwordx4 v169, v[40:43], s[42:43]
	v_mul_f32_e32 v32, v205, v205
	v_mul_f32_e32 v33, v213, v213
	v_mul_f32_e32 v34, v207, v207
	v_mul_f32_e32 v35, v215, v215
	v_fmac_f32_e32 v32, v204, v204
	v_fmac_f32_e32 v33, v212, v212
	v_fmac_f32_e32 v34, v206, v206
	v_fmac_f32_e32 v35, v214, v214
	v_add_f32_e32 v32, v32, v33
	v_add_f32_e32 v32, v34, v32
	v_add_f32_e32 v32, v35, v32
	s_waitcnt vmcnt(15)
;     __device__ __forceinline__ void operator()(AccRef acc, const pg8::Unit& u, int wr, int wc, int fr, int fq) const {
;     ...
;                 const int row = row0 + ai * 128 + m * 16; float ss = 0.f;
; #pragma unroll
;                 for (int bj = 0; bj < 2; ++bj) {
;                     bf16_t* xp = xb + (size_t)row * D + col0 + bj * 128;
;                     f32x4 a, b; unpack8(*(const u32x4*)xp, a, b);
;                     a += acc[ai][bj][m][0] * alpha; b += acc[ai][bj][m][1] * alpha;
;                     *(u32x4*)xp = pack8(a, b);
;                     ss += (a[0] * a[0] + a[1] * a[1]) + (a[2] * a[2] + a[3] * a[3]) + (b[0] * b[0] + b[1] * b[1]) + (b[2] * b[2] + b[3] * b[3]);
;                 }
;                 ss += __shfl_xor(ss, 16); ss += __shfl_xor(ss, 32);
;                 if (fq == 0) ssp[(size_t)row * 16 + u.pn * 4 + wc] = ss;
;             }
	v_pk_mul_f32 v[12:13], v[12:13], 0.5 op_sel_hi:[1,0]
	v_pk_mul_f32 v[14:15], v[14:15], 0.5 op_sel_hi:[1,0]
	v_pk_mul_f32 v[8:9], v[8:9], 0.5 op_sel_hi:[1,0]
	v_pk_mul_f32 v[10:11], v[10:11], 0.5 op_sel_hi:[1,0]
	v_lshlrev_b32_e32 v212, 16, v209
	v_and_b32_e32 v213, 0xffff0000, v209
	v_and_b32_e32 v209, 0xffff0000, v208
	v_lshlrev_b32_e32 v208, 16, v208
	v_lshlrev_b32_e32 v214, 16, v211
	v_and_b32_e32 v215, 0xffff0000, v211
	v_and_b32_e32 v211, 0xffff0000, v210
	v_lshlrev_b32_e32 v210, 16, v210
	v_pk_add_f32 v[208:209], v[12:13], v[208:209]
	v_pk_add_f32 v[212:213], v[14:15], v[212:213]
	v_pk_add_f32 v[210:211], v[8:9], v[210:211]
	v_pk_add_f32 v[214:215], v[10:11], v[214:215]
	v_cvt_pk_bf16_f32 v12, v208, v209
	v_cvt_pk_bf16_f32 v13, v212, v213
	v_cvt_pk_bf16_f32 v14, v210, v211
	v_cvt_pk_bf16_f32 v15, v214, v215
	global_store_dwordx4 v169, v[12:15], s[42:43] offset:256
	v_mul_f32_e32 v8, v209, v209
	v_mul_f32_e32 v9, v213, v213
	v_mul_f32_e32 v10, v211, v211
	v_mul_f32_e32 v11, v215, v215
	v_fmac_f32_e32 v8, v208, v208
	v_fmac_f32_e32 v9, v212, v212
	v_fmac_f32_e32 v10, v210, v210
	v_fmac_f32_e32 v11, v214, v214
	v_add_f32_e32 v8, v8, v9
	v_add_f32_e32 v8, v10, v8
	v_add_f32_e32 v8, v11, v8
	v_add_f32_e32 v32, v32, v8
	v_add_u32_e32 v169, 0x58000, v168
	s_waitcnt vmcnt(13)
	v_pk_mul_f32 v[24:25], v[24:25], 0.5 op_sel_hi:[1,0]
	v_pk_mul_f32 v[26:27], v[26:27], 0.5 op_sel_hi:[1,0]
	v_pk_mul_f32 v[16:17], v[16:17], 0.5 op_sel_hi:[1,0]
	v_pk_mul_f32 v[18:19], v[18:19], 0.5 op_sel_hi:[1,0]
	v_lshlrev_b32_e32 v212, 16, v231
	v_and_b32_e32 v213, 0xffff0000, v231
	v_and_b32_e32 v231, 0xffff0000, v230
	v_lshlrev_b32_e32 v230, 16, v230
	v_lshlrev_b32_e32 v214, 16, v233
	v_and_b32_e32 v215, 0xffff0000, v233
	v_and_b32_e32 v233, 0xffff0000, v232
	v_lshlrev_b32_e32 v232, 16, v232
	v_pk_add_f32 v[230:231], v[24:25], v[230:231]
	v_pk_add_f32 v[212:213], v[26:27], v[212:213]
	v_pk_add_f32 v[232:233], v[16:17], v[232:233]
	v_pk_add_f32 v[214:215], v[18:19], v[214:215]
	v_cvt_pk_bf16_f32 v24, v230, v231
	v_cvt_pk_bf16_f32 v25, v212, v213
	v_cvt_pk_bf16_f32 v26, v232, v233
	v_cvt_pk_bf16_f32 v27, v214, v215
	global_store_dwordx4 v169, v[24:27], s[42:43]
	v_mul_f32_e32 v16, v231, v231
	v_mul_f32_e32 v17, v213, v213
	v_mul_f32_e32 v18, v233, v233
	v_mul_f32_e32 v19, v215, v215
	v_fmac_f32_e32 v16, v230, v230
	v_fmac_f32_e32 v17, v212, v212
	v_fmac_f32_e32 v18, v232, v232
	v_fmac_f32_e32 v19, v214, v214
	v_add_f32_e32 v16, v16, v17
	v_add_f32_e32 v16, v18, v16
	v_add_f32_e32 v16, v19, v16
	s_waitcnt vmcnt(13)
	v_pk_mul_f32 v[4:5], v[4:5], 0.5 op_sel_hi:[1,0]
	v_pk_mul_f32 v[6:7], v[6:7], 0.5 op_sel_hi:[1,0]
	v_pk_mul_f32 v[0:1], v[0:1], 0.5 op_sel_hi:[1,0]
	v_pk_mul_f32 v[2:3], v[2:3], 0.5 op_sel_hi:[1,0]
	v_lshlrev_b32_e32 v212, 16, v235
	v_and_b32_e32 v213, 0xffff0000, v235
	v_and_b32_e32 v235, 0xffff0000, v234
	v_lshlrev_b32_e32 v234, 16, v234
	v_lshlrev_b32_e32 v214, 16, v237
	v_and_b32_e32 v215, 0xffff0000, v237
	v_and_b32_e32 v237, 0xffff0000, v236
	v_lshlrev_b32_e32 v236, 16, v236
	v_pk_add_f32 v[234:235], v[4:5], v[234:235]
	v_pk_add_f32 v[212:213], v[6:7], v[212:213]
	v_pk_add_f32 v[236:237], v[0:1], v[236:237]
	v_pk_add_f32 v[214:215], v[2:3], v[214:215]
	v_cvt_pk_bf16_f32 v4, v234, v235
	v_cvt_pk_bf16_f32 v5, v212, v213
	v_cvt_pk_bf16_f32 v6, v236, v237
	v_cvt_pk_bf16_f32 v7, v214, v215
	global_store_dwordx4 v169, v[4:7], s[42:43] offset:256
	v_mul_f32_e32 v0, v235, v235
	v_mul_f32_e32 v1, v213, v213
	v_mul_f32_e32 v2, v237, v237
	v_mul_f32_e32 v3, v215, v215
	v_fmac_f32_e32 v0, v234, v234
	v_fmac_f32_e32 v1, v212, v212
	v_fmac_f32_e32 v2, v236, v236
	v_fmac_f32_e32 v3, v214, v214
	v_add_f32_e32 v0, v0, v1
	v_add_f32_e32 v0, v2, v0
	v_add_f32_e32 v0, v3, v0
	v_add_f32_e32 v16, v16, v0
	ds_bpermute_b32 v121, v171, v120
	ds_bpermute_b32 v113, v171, v112
	ds_bpermute_b32 v97, v171, v96
	ds_bpermute_b32 v81, v171, v80
	ds_bpermute_b32 v57, v171, v56
	ds_bpermute_b32 v49, v171, v48
	ds_bpermute_b32 v33, v171, v32
	ds_bpermute_b32 v17, v171, v16
	s_waitcnt lgkmcnt(0)
	v_add_f32_e32 v120, v120, v121
	v_add_f32_e32 v112, v112, v113
	v_add_f32_e32 v96, v96, v97
	v_add_f32_e32 v80, v80, v81
	v_add_f32_e32 v56, v56, v57
	v_add_f32_e32 v48, v48, v49
	v_add_f32_e32 v32, v32, v33
	v_add_f32_e32 v16, v16, v17
	ds_bpermute_b32 v121, v172, v120
	ds_bpermute_b32 v113, v172, v112
	ds_bpermute_b32 v97, v172, v96
	ds_bpermute_b32 v81, v172, v80
	ds_bpermute_b32 v57, v172, v56
	ds_bpermute_b32 v49, v172, v48
	ds_bpermute_b32 v33, v172, v32
	ds_bpermute_b32 v17, v172, v16
	s_waitcnt lgkmcnt(0)
	v_add_f32_e32 v120, v120, v121
	v_add_f32_e32 v112, v112, v113
	v_add_f32_e32 v96, v96, v97
	v_add_f32_e32 v80, v80, v81
	v_add_f32_e32 v56, v56, v57
	v_add_f32_e32 v48, v48, v49
	v_add_f32_e32 v32, v32, v33
	v_add_f32_e32 v16, v16, v17
	s_and_saveexec_b64 s[34:35], s[2:3]
	global_store_dword v170, v120, s[46:47]
	global_store_dword v170, v112, s[46:47] offset:1024
	global_store_dword v170, v96, s[46:47] offset:2048
	global_store_dword v170, v80, s[46:47] offset:3072
	global_store_dword v173, v56, s[46:47]
	global_store_dword v173, v48, s[46:47] offset:1024
	global_store_dword v173, v32, s[46:47] offset:2048
	global_store_dword v173, v16, s[46:47] offset:3072
	s_or_b64 exec, exec, s[34:35]
	s_and_b64 vcc, exec, s[4:5]
	s_mov_b64 s[4:5], -1

; #define PG8_STAGE(bufoff, gbase, voff) do { _Pragma("unroll") for (int _i = 0; _i < 2; ++_i) \
;         __builtin_amdgcn_global_load_lds((const unsigned*)((const char*)(gbase) + (voff)[_i]), (PG8_LAS unsigned*)(lds + (bufoff) + ldsw + _i * 8192), 16, 0, 0); } while (0)
; #define PG8_LDA(dst, b, h) do { _Pragma("unroll") for (int m = 0; m < 4; ++m) _Pragma("unroll") for (int k = 0; k < 2; ++k) dst[m][k] = *(const PG8_LAS bf16x8*)(lds + PG8_SA(b, h) + aoff + m * 2048 + k * 1024); } while (0)
; #define PG8_LDB(dst, b, h) do { _Pragma("unroll") for (int n = 0; n < 2; ++n) _Pragma("unroll") for (int k = 0; k < 2; ++k) dst[n][k] = *(const PG8_LAS bf16x8*)(lds + PG8_SB(b, h) + boff + n * 2048 + k * 1024); } while (0)
; #define PG8_MMA(ai, bj, At, Bt) do { __builtin_amdgcn_s_setprio(1); _Pragma("unroll") for (int m = 0; m < 4; ++m) _Pragma("unroll") for (int n = 0; n < 2; ++n) _Pragma("unroll") for (int k = 0; k < 2; ++k) \
;         acc[ai][bj][m][n] = __builtin_amdgcn_mfma_f32_16x16x32_bf16(Bt[n][k], At[m][k], acc[ai][bj][m][n], 0, 0, 0); __builtin_amdgcn_s_setprio(0); } while (0)
; #define PG8_WAIT_V(n) asm volatile("s_waitcnt vmcnt(" #n ")" ::: "memory")
; #define PG8_WAIT_L(n) asm volatile("s_waitcnt lgkmcnt(" #n ")" ::: "memory")
; #define PG8_BAR __builtin_amdgcn_s_barrier()
; #define PG8_SCHED __builtin_amdgcn_sched_barrier(0)
; template <class Epi, class Sched, bool ALIGN_EPI = false, bool SP2 = false>
; __device__ __forceinline__ void gemm_phase(PG8_LAS unsigned char* lds, const Gemm g, const Sched& S, const Epi& E) {
;     ...
;             PG8_LDB(B0, 0, 0); PG8_LDB(B1, 0, 1); PG8_SCHED; PG8_LDA(At, 0, 0); PG8_STAGE(PG8_SA(1, 1), a1 + hstep, voffA);
;             PG8_WAIT_V(8); PG8_WAIT_L(0); PG8_BAR; PG8_MMA(0, 0, At, B0); PG8_MMA(0, 1, At, B1); PG8_BAR; PG8_SCHED;
;             PG8_LDA(At, 0, 1); PG8_STAGE(PG8_SB(0, 0), b2, voffB); PG8_STAGE(PG8_SB(0, 1), b2 + hstep, voffB); PG8_STAGE(PG8_SA(0, 0), a2, voffA);
;             PG8_WAIT_V(8); PG8_WAIT_L(0); PG8_BAR; PG8_MMA(1, 0, At, B0); PG8_MMA(1, 1, At, B1); PG8_BAR; PG8_SCHED;
.LBB0_1601:
	ds_read_b128 v[144:147], v159
	ds_read_b128 v[148:151], v159 offset:1024
	ds_read_b128 v[152:155], v159 offset:2048
	ds_read_b128 v[164:167], v159 offset:3072
	ds_read_b128 v[168:171], v160
	ds_read_b128 v[172:175], v160 offset:1024
	ds_read_b128 v[180:183], v160 offset:2048
	ds_read_b128 v[184:187], v160 offset:3072
	s_add_i32 s65, s34, 2
	s_add_u32 s66, s30, 0x80
	s_addc_u32 s35, s31, 0
	s_cmp_eq_u32 s41, s34
	s_cselect_b32 s34, s0, s66
	s_cselect_b32 s35, s1, s35
	s_cselect_b32 s67, s29, s64
	s_cselect_b32 s66, s28, s63
	v_lshl_add_u64 v[176:177], s[30:31], 0, v[136:137]
	s_add_i32 m0, s17, 0xc000
	ds_read_b128 v[188:191], v161
	ds_read_b128 v[192:195], v161 offset:1024
	ds_read_b128 v[196:199], v161 offset:2048
	ds_read_b128 v[200:203], v161 offset:3072
	ds_read_b128 v[204:207], v161 offset:4096
	ds_read_b128 v[208:211], v161 offset:5120
	ds_read_b128 v[212:215], v161 offset:6144
	ds_read_b128 v[216:219], v161 offset:7168
	global_load_lds_dwordx4 v[176:177], off
	v_lshl_add_u64 v[176:177], s[30:31], 0, v[138:139]
	s_add_i32 m0, s17, 0xe000
	s_nop 0
	global_load_lds_dwordx4 v[176:177], off
	s_waitcnt vmcnt(8)
	s_waitcnt lgkmcnt(0)
	s_barrier
	s_setprio 1
	s_waitcnt lgkmcnt(0)
	v_mfma_f32_16x16x32_bf16 v[124:127], v[144:147], v[188:191], v[124:127]
	v_mfma_f32_16x16x32_bf16 v[120:123], v[152:155], v[188:191], v[120:123]
	v_mfma_f32_16x16x32_bf16 v[116:119], v[144:147], v[196:199], v[116:119]
	v_mfma_f32_16x16x32_bf16 v[112:115], v[152:155], v[196:199], v[112:115]
	v_mfma_f32_16x16x32_bf16 v[104:107], v[144:147], v[204:207], v[104:107]
	v_mfma_f32_16x16x32_bf16 v[96:99], v[152:155], v[204:207], v[96:99]
	v_mfma_f32_16x16x32_bf16 v[88:91], v[144:147], v[212:215], v[88:91]
	v_mfma_f32_16x16x32_bf16 v[80:83], v[152:155], v[212:215], v[80:83]
	v_mfma_f32_16x16x32_bf16 v[124:127], v[148:151], v[192:195], v[124:127]
	v_mfma_f32_16x16x32_bf16 v[120:123], v[164:167], v[192:195], v[120:123]
	v_mfma_f32_16x16x32_bf16 v[116:119], v[148:151], v[200:203], v[116:119]
	v_mfma_f32_16x16x32_bf16 v[112:115], v[164:167], v[200:203], v[112:115]
	v_mfma_f32_16x16x32_bf16 v[104:107], v[148:151], v[208:211], v[104:107]
	v_mfma_f32_16x16x32_bf16 v[96:99], v[164:167], v[208:211], v[96:99]
	v_mfma_f32_16x16x32_bf16 v[88:91], v[148:151], v[216:219], v[88:91]
	v_mfma_f32_16x16x32_bf16 v[80:83], v[164:167], v[216:219], v[80:83]
	s_setprio 0
	s_setprio 1
	v_mfma_f32_16x16x32_bf16 v[108:111], v[168:171], v[188:191], v[108:111]
	v_mfma_f32_16x16x32_bf16 v[100:103], v[180:183], v[188:191], v[100:103]
	v_mfma_f32_16x16x32_bf16 v[92:95], v[168:171], v[196:199], v[92:95]
	v_mfma_f32_16x16x32_bf16 v[84:87], v[180:183], v[196:199], v[84:87]
	v_mfma_f32_16x16x32_bf16 v[76:79], v[168:171], v[204:207], v[76:79]
	v_mfma_f32_16x16x32_bf16 v[72:75], v[180:183], v[204:207], v[72:75]
	v_mfma_f32_16x16x32_bf16 v[68:71], v[168:171], v[212:215], v[68:71]
	v_mfma_f32_16x16x32_bf16 v[64:67], v[180:183], v[212:215], v[64:67]
	v_mfma_f32_16x16x32_bf16 v[108:111], v[172:175], v[192:195], v[108:111]
	v_mfma_f32_16x16x32_bf16 v[100:103], v[184:187], v[192:195], v[100:103]
	v_mfma_f32_16x16x32_bf16 v[92:95], v[172:175], v[200:203], v[92:95]
	v_mfma_f32_16x16x32_bf16 v[84:87], v[184:187], v[200:203], v[84:87]
	v_mfma_f32_16x16x32_bf16 v[76:79], v[172:175], v[208:211], v[76:79]
	v_mfma_f32_16x16x32_bf16 v[72:75], v[184:187], v[208:211], v[72:75]
	v_mfma_f32_16x16x32_bf16 v[68:71], v[172:175], v[216:219], v[68:71]
	v_mfma_f32_16x16x32_bf16 v[64:67], v[184:187], v[216:219], v[64:67]
	s_setprio 0
	s_barrier
	s_add_i32 s68, s57, s16
	v_lshl_add_u64 v[176:177], s[66:67], 0, v[130:131]
	s_mov_b32 m0, s68
	ds_read_b128 v[188:191], v161 offset:16384
	ds_read_b128 v[192:195], v161 offset:17408
	ds_read_b128 v[196:199], v161 offset:18432
	ds_read_b128 v[200:203], v161 offset:19456
	ds_read_b128 v[204:207], v161 offset:20480
	ds_read_b128 v[208:211], v161 offset:21504
	ds_read_b128 v[212:215], v161 offset:22528
	ds_read_b128 v[216:219], v161 offset:23552
	global_load_lds_dwordx4 v[176:177], off
	s_add_i32 m0, s68, 0x2000
	v_lshl_add_u64 v[178:179], s[66:67], 0, v[134:135]
	s_add_u32 s66, s66, s6
	s_addc_u32 s67, s67, s7
	s_add_i32 s68, s58, s16
	global_load_lds_dwordx4 v[178:179], off
	v_lshl_add_u64 v[220:221], s[66:67], 0, v[130:131]
	s_mov_b32 m0, s68
	v_lshl_add_u64 v[222:223], s[66:67], 0, v[134:135]
	global_load_lds_dwordx4 v[220:221], off
	s_add_i32 m0, s68, 0x2000
	v_lshl_add_u64 v[224:225], s[34:35], 0, v[128:129]
	global_load_lds_dwordx4 v[222:223], off
	s_mov_b32 m0, s17
	v_lshl_add_u64 v[226:227], s[34:35], 0, v[132:133]
	global_load_lds_dwordx4 v[224:225], off
	s_mov_b32 m0, s19
	s_nop 0
	global_load_lds_dwordx4 v[226:227], off
	s_waitcnt vmcnt(8)
	s_waitcnt lgkmcnt(0)
	s_barrier
; #define PG8_STAGE(bufoff, gbase, voff) do { _Pragma("unroll") for (int _i = 0; _i < 2; ++_i) \
;         __builtin_amdgcn_global_load_lds((const unsigned*)((const char*)(gbase) + (voff)[_i]), (PG8_LAS unsigned*)(lds + (bufoff) + ldsw + _i * 8192), 16, 0, 0); } while (0)
; #define PG8_LDA(dst, b, h) do { _Pragma("unroll") for (int m = 0; m < 4; ++m) _Pragma("unroll") for (int k = 0; k < 2; ++k) dst[m][k] = *(const PG8_LAS bf16x8*)(lds + PG8_SA(b, h) + aoff + m * 2048 + k * 1024); } while (0)
; #define PG8_LDB(dst, b, h) do { _Pragma("unroll") for (int n = 0; n < 2; ++n) _Pragma("unroll") for (int k = 0; k < 2; ++k) dst[n][k] = *(const PG8_LAS bf16x8*)(lds + PG8_SB(b, h) + boff + n * 2048 + k * 1024); } while (0)
; #define PG8_MMA(ai, bj, At, Bt) do { __builtin_amdgcn_s_setprio(1); _Pragma("unroll") for (int m = 0; m < 4; ++m) _Pragma("unroll") for (int n = 0; n < 2; ++n) _Pragma("unroll") for (int k = 0; k < 2; ++k) \
;         acc[ai][bj][m][n] = __builtin_amdgcn_mfma_f32_16x16x32_bf16(Bt[n][k], At[m][k], acc[ai][bj][m][n], 0, 0, 0); __builtin_amdgcn_s_setprio(0); } while (0)
; #define PG8_WAIT_V(n) asm volatile("s_waitcnt vmcnt(" #n ")" ::: "memory")
; #define PG8_WAIT_L(n) asm volatile("s_waitcnt lgkmcnt(" #n ")" ::: "memory")
; #define PG8_BAR __builtin_amdgcn_s_barrier()
; #define PG8_SCHED __builtin_amdgcn_sched_barrier(0)
; template <class Epi, class Sched, bool ALIGN_EPI = false, bool SP2 = false>
; __device__ __forceinline__ void gemm_phase(PG8_LAS unsigned char* lds, const Gemm g, const Sched& S, const Epi& E) {
;     ...
;             PG8_WAIT_V(8); PG8_WAIT_L(0); PG8_BAR; PG8_MMA(1, 0, At, B0); PG8_MMA(1, 1, At, B1); PG8_BAR; PG8_SCHED;
;             PG8_LDB(B0, 1, 0); PG8_LDB(B1, 1, 1); PG8_SCHED; PG8_LDA(At, 1, 0); PG8_STAGE(PG8_SA(0, 1), a2 + hstep, voffA);
;             PG8_WAIT_V(8); PG8_WAIT_L(0); PG8_BAR; PG8_MMA(0, 0, At, B0); PG8_MMA(0, 1, At, B1); PG8_BAR; PG8_SCHED;
	s_setprio 1
	s_waitcnt lgkmcnt(0)
	v_mfma_f32_16x16x32_bf16 v[60:63], v[144:147], v[188:191], v[60:63]
	v_mfma_f32_16x16x32_bf16 v[56:59], v[152:155], v[188:191], v[56:59]
	v_mfma_f32_16x16x32_bf16 v[52:55], v[144:147], v[196:199], v[52:55]
	v_mfma_f32_16x16x32_bf16 v[48:51], v[152:155], v[196:199], v[48:51]
	v_mfma_f32_16x16x32_bf16 v[40:43], v[144:147], v[204:207], v[40:43]
	v_mfma_f32_16x16x32_bf16 v[32:35], v[152:155], v[204:207], v[32:35]
	v_mfma_f32_16x16x32_bf16 v[24:27], v[144:147], v[212:215], v[24:27]
	v_mfma_f32_16x16x32_bf16 v[16:19], v[152:155], v[212:215], v[16:19]
	v_mfma_f32_16x16x32_bf16 v[60:63], v[148:151], v[192:195], v[60:63]
	v_mfma_f32_16x16x32_bf16 v[56:59], v[164:167], v[192:195], v[56:59]
	v_mfma_f32_16x16x32_bf16 v[52:55], v[148:151], v[200:203], v[52:55]
	v_mfma_f32_16x16x32_bf16 v[48:51], v[164:167], v[200:203], v[48:51]
	v_mfma_f32_16x16x32_bf16 v[40:43], v[148:151], v[208:211], v[40:43]
	v_mfma_f32_16x16x32_bf16 v[32:35], v[164:167], v[208:211], v[32:35]
	v_mfma_f32_16x16x32_bf16 v[24:27], v[148:151], v[216:219], v[24:27]
	v_mfma_f32_16x16x32_bf16 v[16:19], v[164:167], v[216:219], v[16:19]
	s_setprio 0
	s_setprio 1
	v_mfma_f32_16x16x32_bf16 v[44:47], v[168:171], v[188:191], v[44:47]
	v_mfma_f32_16x16x32_bf16 v[36:39], v[180:183], v[188:191], v[36:39]
	v_mfma_f32_16x16x32_bf16 v[28:31], v[168:171], v[196:199], v[28:31]
	v_mfma_f32_16x16x32_bf16 v[20:23], v[180:183], v[196:199], v[20:23]
	v_mfma_f32_16x16x32_bf16 v[12:15], v[168:171], v[204:207], v[12:15]
	v_mfma_f32_16x16x32_bf16 v[8:11], v[180:183], v[204:207], v[8:11]
	v_mfma_f32_16x16x32_bf16 v[4:7], v[168:171], v[212:215], v[4:7]
	v_mfma_f32_16x16x32_bf16 v[0:3], v[180:183], v[212:215], v[0:3]
	v_mfma_f32_16x16x32_bf16 v[44:47], v[172:175], v[192:195], v[44:47]
	v_mfma_f32_16x16x32_bf16 v[36:39], v[184:187], v[192:195], v[36:39]
	v_mfma_f32_16x16x32_bf16 v[28:31], v[172:175], v[200:203], v[28:31]
	v_mfma_f32_16x16x32_bf16 v[20:23], v[184:187], v[200:203], v[20:23]
	v_mfma_f32_16x16x32_bf16 v[12:15], v[172:175], v[208:211], v[12:15]
	v_mfma_f32_16x16x32_bf16 v[8:11], v[184:187], v[208:211], v[8:11]
	v_mfma_f32_16x16x32_bf16 v[4:7], v[172:175], v[216:219], v[4:7]
	v_mfma_f32_16x16x32_bf16 v[0:3], v[184:187], v[216:219], v[0:3]
	s_setprio 0
	s_barrier
	s_add_i32 s66, 0, 0x18000
	v_add_u32_e32 v163, s66, v157
	s_add_i32 s67, 0, 0x1c000
	ds_read_b128 v[144:147], v163
	ds_read_b128 v[148:151], v163 offset:1024
	ds_read_b128 v[152:155], v163 offset:2048
	ds_read_b128 v[164:167], v163 offset:3072
	v_add_u32_e32 v163, s67, v157
	ds_read_b128 v[168:171], v163
	ds_read_b128 v[172:175], v163 offset:1024
	ds_read_b128 v[180:183], v163 offset:2048
	ds_read_b128 v[184:187], v163 offset:3072
	s_add_u32 s34, s34, s6
	s_addc_u32 s35, s35, s7
	s_mov_b32 m0, s33
	v_lshl_add_u64 v[228:229], s[34:35], 0, v[128:129]
	ds_read_b128 v[188:191], v161 offset:32768
	ds_read_b128 v[192:195], v161 offset:33792
	ds_read_b128 v[196:199], v161 offset:34816
	ds_read_b128 v[200:203], v161 offset:35840
	ds_read_b128 v[204:207], v161 offset:36864
	ds_read_b128 v[208:211], v161 offset:37888
	ds_read_b128 v[212:215], v161 offset:38912
	ds_read_b128 v[216:219], v161 offset:39936
	global_load_lds_dwordx4 v[228:229], off
	v_lshl_add_u64 v[228:229], s[34:35], 0, v[132:133]
	s_mov_b32 m0, s36
	s_nop 0
	global_load_lds_dwordx4 v[228:229], off
	s_waitcnt vmcnt(8)
	s_waitcnt lgkmcnt(0)
	s_barrier
	s_setprio 1
	s_waitcnt lgkmcnt(0)
	v_mfma_f32_16x16x32_bf16 v[124:127], v[144:147], v[188:191], v[124:127]
	v_mfma_f32_16x16x32_bf16 v[120:123], v[152:155], v[188:191], v[120:123]
	v_mfma_f32_16x16x32_bf16 v[116:119], v[144:147], v[196:199], v[116:119]
	v_mfma_f32_16x16x32_bf16 v[112:115], v[152:155], v[196:199], v[112:115]
	v_mfma_f32_16x16x32_bf16 v[104:107], v[144:147], v[204:207], v[104:107]
	v_mfma_f32_16x16x32_bf16 v[96:99], v[152:155], v[204:207], v[96:99]
	v_mfma_f32_16x16x32_bf16 v[88:91], v[144:147], v[212:215], v[88:91]
	v_mfma_f32_16x16x32_bf16 v[80:83], v[152:155], v[212:215], v[80:83]
	v_mfma_f32_16x16x32_bf16 v[124:127], v[148:151], v[192:195], v[124:127]
	v_mfma_f32_16x16x32_bf16 v[120:123], v[164:167], v[192:195], v[120:123]
	v_mfma_f32_16x16x32_bf16 v[116:119], v[148:151], v[200:203], v[116:119]
	v_mfma_f32_16x16x32_bf16 v[112:115], v[164:167], v[200:203], v[112:115]
	v_mfma_f32_16x16x32_bf16 v[104:107], v[148:151], v[208:211], v[104:107]
	v_mfma_f32_16x16x32_bf16 v[96:99], v[164:167], v[208:211], v[96:99]
	v_mfma_f32_16x16x32_bf16 v[88:91], v[148:151], v[216:219], v[88:91]
	v_mfma_f32_16x16x32_bf16 v[80:83], v[164:167], v[216:219], v[80:83]
	s_setprio 0
	s_setprio 1
	v_mfma_f32_16x16x32_bf16 v[108:111], v[168:171], v[188:191], v[108:111]
	v_mfma_f32_16x16x32_bf16 v[100:103], v[180:183], v[188:191], v[100:103]
	v_mfma_f32_16x16x32_bf16 v[92:95], v[168:171], v[196:199], v[92:95]
	v_mfma_f32_16x16x32_bf16 v[84:87], v[180:183], v[196:199], v[84:87]
	v_mfma_f32_16x16x32_bf16 v[76:79], v[168:171], v[204:207], v[76:79]
	v_mfma_f32_16x16x32_bf16 v[72:75], v[180:183], v[204:207], v[72:75]
	v_mfma_f32_16x16x32_bf16 v[68:71], v[168:171], v[212:215], v[68:71]
	v_mfma_f32_16x16x32_bf16 v[64:67], v[180:183], v[212:215], v[64:67]
	v_mfma_f32_16x16x32_bf16 v[108:111], v[172:175], v[192:195], v[108:111]
	v_mfma_f32_16x16x32_bf16 v[100:103], v[184:187], v[192:195], v[100:103]
	v_mfma_f32_16x16x32_bf16 v[92:95], v[172:175], v[200:203], v[92:95]
	v_mfma_f32_16x16x32_bf16 v[84:87], v[184:187], v[200:203], v[84:87]
	v_mfma_f32_16x16x32_bf16 v[76:79], v[172:175], v[208:211], v[76:79]
	v_mfma_f32_16x16x32_bf16 v[72:75], v[184:187], v[208:211], v[72:75]
	v_mfma_f32_16x16x32_bf16 v[68:71], v[172:175], v[216:219], v[68:71]
	v_mfma_f32_16x16x32_bf16 v[64:67], v[184:187], v[216:219], v[64:67]
	s_setprio 0
	s_barrier
; #define PG8_STAGE(bufoff, gbase, voff) do { _Pragma("unroll") for (int _i = 0; _i < 2; ++_i) \
;         __builtin_amdgcn_global_load_lds((const unsigned*)((const char*)(gbase) + (voff)[_i]), (PG8_LAS unsigned*)(lds + (bufoff) + ldsw + _i * 8192), 16, 0, 0); } while (0)
; #define PG8_LDA(dst, b, h) do { _Pragma("unroll") for (int m = 0; m < 4; ++m) _Pragma("unroll") for (int k = 0; k < 2; ++k) dst[m][k] = *(const PG8_LAS bf16x8*)(lds + PG8_SA(b, h) + aoff + m * 2048 + k * 1024); } while (0)
; #define PG8_MMA(ai, bj, At, Bt) do { __builtin_amdgcn_s_setprio(1); _Pragma("unroll") for (int m = 0; m < 4; ++m) _Pragma("unroll") for (int n = 0; n < 2; ++n) _Pragma("unroll") for (int k = 0; k < 2; ++k) \
;         acc[ai][bj][m][n] = __builtin_amdgcn_mfma_f32_16x16x32_bf16(Bt[n][k], At[m][k], acc[ai][bj][m][n], 0, 0, 0); __builtin_amdgcn_s_setprio(0); } while (0)
; #define PG8_WAIT_V(n) asm volatile("s_waitcnt vmcnt(" #n ")" ::: "memory")
; #define PG8_WAIT_L(n) asm volatile("s_waitcnt lgkmcnt(" #n ")" ::: "memory")
; #define PG8_BAR __builtin_amdgcn_s_barrier()
; #define PG8_SCHED __builtin_amdgcn_sched_barrier(0)
; template <class Epi, class Sched, bool ALIGN_EPI = false, bool SP2 = false>
; __device__ __forceinline__ void gemm_phase(PG8_LAS unsigned char* lds, const Gemm g, const Sched& S, const Epi& E) {
;     ...
;             PG8_LDA(At, 1, 1); PG8_STAGE(PG8_SB(1, 0), b3, voffB); PG8_STAGE(PG8_SB(1, 1), b3 + hstep, voffB); PG8_STAGE(PG8_SA(1, 0), a3, voffA);
;             PG8_WAIT_V(8); PG8_WAIT_L(0); PG8_BAR; PG8_MMA(1, 0, At, B0); PG8_MMA(1, 1, At, B1); PG8_BAR; PG8_SCHED;
;     ...
;         if constexpr (ALIGN_EPI) { if (wr == 0) PG8_BAR; }
	s_add_i32 s34, s66, s16
	v_lshl_add_u64 v[176:177], v[176:177], 0, s[22:23]
	s_mov_b32 m0, s34
	ds_read_b128 v[188:191], v161 offset:49152
	ds_read_b128 v[192:195], v161 offset:50176
	ds_read_b128 v[196:199], v161 offset:51200
	ds_read_b128 v[200:203], v161 offset:52224
	ds_read_b128 v[204:207], v161 offset:53248
	ds_read_b128 v[208:211], v161 offset:54272
	ds_read_b128 v[212:215], v161 offset:55296
	ds_read_b128 v[216:219], v161 offset:56320
	global_load_lds_dwordx4 v[176:177], off
	v_lshl_add_u64 v[176:177], v[178:179], 0, s[22:23]
	s_add_i32 m0, s34, 0x2000
	s_add_i32 s34, s67, s16
	global_load_lds_dwordx4 v[176:177], off
	v_lshl_add_u64 v[176:177], v[220:221], 0, s[22:23]
	s_mov_b32 m0, s34
	s_nop 0
	global_load_lds_dwordx4 v[176:177], off
	v_lshl_add_u64 v[176:177], v[222:223], 0, s[22:23]
	s_add_i32 m0, s34, 0x2000
	s_nop 0
	global_load_lds_dwordx4 v[176:177], off
	v_lshl_add_u64 v[176:177], v[224:225], 0, s[22:23]
	s_mov_b32 m0, s37
	s_nop 0
	global_load_lds_dwordx4 v[176:177], off
	v_lshl_add_u64 v[176:177], v[226:227], 0, s[22:23]
	s_mov_b32 m0, s38
	s_nop 0
	global_load_lds_dwordx4 v[176:177], off
	s_waitcnt vmcnt(8)
	s_waitcnt lgkmcnt(0)
	s_barrier
	s_setprio 1
	s_waitcnt lgkmcnt(0)
	v_mfma_f32_16x16x32_bf16 v[60:63], v[144:147], v[188:191], v[60:63]
	v_mfma_f32_16x16x32_bf16 v[56:59], v[152:155], v[188:191], v[56:59]
	v_mfma_f32_16x16x32_bf16 v[52:55], v[144:147], v[196:199], v[52:55]
	v_mfma_f32_16x16x32_bf16 v[48:51], v[152:155], v[196:199], v[48:51]
	v_mfma_f32_16x16x32_bf16 v[40:43], v[144:147], v[204:207], v[40:43]
	v_mfma_f32_16x16x32_bf16 v[32:35], v[152:155], v[204:207], v[32:35]
	v_mfma_f32_16x16x32_bf16 v[24:27], v[144:147], v[212:215], v[24:27]
	v_mfma_f32_16x16x32_bf16 v[16:19], v[152:155], v[212:215], v[16:19]
	v_mfma_f32_16x16x32_bf16 v[60:63], v[148:151], v[192:195], v[60:63]
	v_mfma_f32_16x16x32_bf16 v[56:59], v[164:167], v[192:195], v[56:59]
	v_mfma_f32_16x16x32_bf16 v[52:55], v[148:151], v[200:203], v[52:55]
	v_mfma_f32_16x16x32_bf16 v[48:51], v[164:167], v[200:203], v[48:51]
	v_mfma_f32_16x16x32_bf16 v[40:43], v[148:151], v[208:211], v[40:43]
	v_mfma_f32_16x16x32_bf16 v[32:35], v[164:167], v[208:211], v[32:35]
	v_mfma_f32_16x16x32_bf16 v[24:27], v[148:151], v[216:219], v[24:27]
	v_mfma_f32_16x16x32_bf16 v[16:19], v[164:167], v[216:219], v[16:19]
	s_setprio 0
	s_setprio 1
	v_mfma_f32_16x16x32_bf16 v[44:47], v[168:171], v[188:191], v[44:47]
	v_mfma_f32_16x16x32_bf16 v[36:39], v[180:183], v[188:191], v[36:39]
	v_mfma_f32_16x16x32_bf16 v[28:31], v[168:171], v[196:199], v[28:31]
	v_mfma_f32_16x16x32_bf16 v[20:23], v[180:183], v[196:199], v[20:23]
	v_mfma_f32_16x16x32_bf16 v[12:15], v[168:171], v[204:207], v[12:15]
	v_mfma_f32_16x16x32_bf16 v[8:11], v[180:183], v[204:207], v[8:11]
	v_mfma_f32_16x16x32_bf16 v[4:7], v[168:171], v[212:215], v[4:7]
	v_mfma_f32_16x16x32_bf16 v[0:3], v[180:183], v[212:215], v[0:3]
	v_mfma_f32_16x16x32_bf16 v[44:47], v[172:175], v[192:195], v[44:47]
	v_mfma_f32_16x16x32_bf16 v[36:39], v[184:187], v[192:195], v[36:39]
	v_mfma_f32_16x16x32_bf16 v[28:31], v[172:175], v[200:203], v[28:31]
	v_mfma_f32_16x16x32_bf16 v[20:23], v[184:187], v[200:203], v[20:23]
	v_mfma_f32_16x16x32_bf16 v[12:15], v[172:175], v[208:211], v[12:15]
	v_mfma_f32_16x16x32_bf16 v[8:11], v[184:187], v[208:211], v[8:11]
	v_mfma_f32_16x16x32_bf16 v[4:7], v[172:175], v[216:219], v[4:7]
	v_mfma_f32_16x16x32_bf16 v[0:3], v[184:187], v[216:219], v[0:3]
	s_setprio 0
	s_barrier
	s_add_u32 s30, s30, 0x100
	s_addc_u32 s31, s31, 0
	s_add_u32 s63, s63, 0x100
	s_addc_u32 s64, s64, 0
	s_cmp_ge_i32 s65, s40
	s_mov_b32 s34, s65
	s_cbranch_scc0 .LBB0_1601
.LBB0_1603:
	s_and_b64 vcc, exec, s[26:27]
	s_cbranch_vccz .LBB0_1605
	s_barrier

;     __host__ __device__ bool next(int i, Unit& u) const {
;         const long L = (long)i * G + c; if (L >= nwg) return false;
;         int wgid = (int)L; { const int q = nwg / NXCD, r = nwg % NXCD, xcd = wgid % NXCD, off = wgid / NXCD; wgid = (xcd < r ? xcd * (q + 1) : r * (q + 1) + (xcd - r) * q) + off; }
;     __device__ __forceinline__ void operator()(AccRef acc, const pg8::Unit& u, int wr, int wc, int fr, int fq) const {
;     ...
;                     bf16_t* xp = xb + (size_t)row * D + col0 + bj * 128;
;                     f32x4 a, b; unpack8(*(const u32x4*)xp, a, b);
.LBB0_2374:
	v_lshl_add_u32 v252, s60, 8, v148
	v_lshl_or_b32 v253, s14, 8, v150
	v_lshlrev_b32_e32 v253, 1, v253
	v_lshl_add_u32 v252, v252, 11, v253
	global_load_dwordx4 v[230:233], v252, s[42:43]
	global_load_dwordx4 v[234:237], v252, s[42:43] offset:256
	v_add_u32_e32 v253, 0x8000, v252
	global_load_dwordx4 v[238:241], v253, s[42:43]
	global_load_dwordx4 v[242:245], v253, s[42:43] offset:256
	v_add_u32_e32 v253, 0x10000, v252
	global_load_dwordx4 v[246:249], v253, s[42:43]
	global_load_dwordx4 v[250:253], v253, s[42:43] offset:256
	s_add_i32 s57, s57, 1
	s_mul_i32 s0, s57, s44
	s_mul_hi_u32 s1, s57, s45
	s_add_i32 s1, s1, s0
	s_mul_i32 s0, s57, s45
	s_add_u32 s4, s0, s18
	s_addc_u32 s5, s1, s50
	v_cmp_gt_i64_e32 vcc, s[4:5], v[142:143]
	v_cmp_lt_i64_e64 s[0:1], s[4:5], v[140:141]
	s_cbranch_vccnz .LBB0_2380
	s_ashr_i32 s5, s4, 31
	s_lshr_b32 s5, s5, 29
	s_add_i32 s28, s4, s5
	s_and_b32 s5, s28, -8
	s_sub_i32 s29, s4, s5
	s_cmp_gt_i32 s29, -1
	s_mov_b64 s[4:5], -1
	s_cbranch_scc0 .LBB0_2377
	s_lshl_b32 s58, s29, 6
	s_mov_b64 s[4:5], 0

;     __device__ __forceinline__ void operator()(const f32x4 (&acc)[2], int srow, int cgp, int kq) const { one(acc[0], srow, 2 * cgp, kq); one(acc[1], srow, 2 * cgp + 1, kq); }
;     __device__ __forceinline__ void operator()(AccRef acc, const pg8::Unit& u, int wr, int wc, int fr, int fq) const {
;         const int row0 = u.pm * 256 + wr * 64 + fr, col0 = u.pn * 256 + wc * 32 + 8 * fq;
; #pragma unroll
;         for (int ai = 0; ai < 2; ++ai)
; #pragma unroll
;             for (int m = 0; m < 4; ++m) {
;                 const int row = row0 + ai * 128 + m * 16; float ss = 0.f;
; #pragma unroll
;                 for (int bj = 0; bj < 2; ++bj) {
;                     bf16_t* xp = xb + (size_t)row * D + col0 + bj * 128;
;                     f32x4 a, b; unpack8(*(const u32x4*)xp, a, b);
;                     a += acc[ai][bj][m][0] * alpha; b += acc[ai][bj][m][1] * alpha;
;                     *(u32x4*)xp = pack8(a, b);
;                     ss += (a[0] * a[0] + a[1] * a[1]) + (a[2] * a[2] + a[3] * a[3]) + (b[0] * b[0] + b[1] * b[1]) + (b[2] * b[2] + b[3] * b[3]);
;                 }
;                 ss += __shfl_xor(ss, 16); ss += __shfl_xor(ss, 32);
;                 if (fq == 0) ssp[(size_t)row * 16 + u.pn * 4 + wc] = ss;
;             }
;     }
.LBB0_2389:
.Lres_beg4:
	v_lshl_add_u32 v170, s60, 8, v148
	v_lshl_or_b32 v169, s14, 8, v150
	v_lshlrev_b32_e32 v169, 1, v169
	v_lshl_add_u32 v168, v170, 11, v169
	v_add_u32_e32 v169, 0x18000, v168
	global_load_dwordx4 v[180:183], v169, s[42:43]
	global_load_dwordx4 v[184:187], v169, s[42:43] offset:256
	v_add_u32_e32 v169, 0x40000, v168
	global_load_dwordx4 v[188:191], v169, s[42:43]
	global_load_dwordx4 v[192:195], v169, s[42:43] offset:256
	v_add_u32_e32 v169, 0x48000, v168
	global_load_dwordx4 v[196:199], v169, s[42:43]
	global_load_dwordx4 v[200:203], v169, s[42:43] offset:256
	v_add_u32_e32 v169, 0x50000, v168
	global_load_dwordx4 v[204:207], v169, s[42:43]
	global_load_dwordx4 v[208:211], v169, s[42:43] offset:256
	v_bfe_u32 v171, v150, 5, 2
	v_lshl_add_u32 v171, s14, 2, v171
	v_lshlrev_b32_e32 v171, 2, v171
	v_lshl_add_u32 v170, v170, 6, v171
	v_add_u32_e32 v173, 0x2000, v170
	v_mbcnt_lo_u32_b32 v172, -1, 0
	v_mbcnt_hi_u32_b32 v172, -1, v172
	v_xor_b32_e32 v171, 16, v172
	v_xor_b32_e32 v172, 32, v172
	v_lshlrev_b32_e32 v171, 2, v171
	v_lshlrev_b32_e32 v172, 2, v172
	v_mov_b32_e32 v169, v168
	s_waitcnt vmcnt(8)
	v_lshlrev_b32_e32 v212, 16, v231
	v_and_b32_e32 v213, 0xffff0000, v231
	v_and_b32_e32 v231, 0xffff0000, v230
	v_lshlrev_b32_e32 v230, 16, v230
	v_lshlrev_b32_e32 v214, 16, v233
	v_and_b32_e32 v215, 0xffff0000, v233
	v_and_b32_e32 v233, 0xffff0000, v232
	v_lshlrev_b32_e32 v232, 16, v232
	v_pk_add_f32 v[230:231], v[124:125], v[230:231]
	v_pk_add_f32 v[212:213], v[126:127], v[212:213]
	v_pk_add_f32 v[232:233], v[120:121], v[232:233]
	v_pk_add_f32 v[214:215], v[122:123], v[214:215]
	v_cvt_pk_bf16_f32 v124, v230, v231
	v_cvt_pk_bf16_f32 v125, v212, v213
	v_cvt_pk_bf16_f32 v126, v232, v233
	v_cvt_pk_bf16_f32 v127, v214, v215
	global_store_dwordx4 v169, v[124:127], s[42:43]
	v_mul_f32_e32 v120, v231, v231
	v_mul_f32_e32 v121, v213, v213
	v_mul_f32_e32 v122, v233, v233
	v_mul_f32_e32 v123, v215, v215
	v_fmac_f32_e32 v120, v230, v230
	v_fmac_f32_e32 v121, v212, v212
	v_fmac_f32_e32 v122, v232, v232
	v_fmac_f32_e32 v123, v214, v214
	v_add_f32_e32 v120, v120, v121
	v_add_f32_e32 v120, v122, v120
	v_add_f32_e32 v120, v123, v120
	s_nop 0
	v_lshlrev_b32_e32 v212, 16, v235
	v_and_b32_e32 v213, 0xffff0000, v235
	v_and_b32_e32 v235, 0xffff0000, v234
	v_lshlrev_b32_e32 v234, 16, v234
	v_lshlrev_b32_e32 v214, 16, v237
	v_and_b32_e32 v215, 0xffff0000, v237
	v_and_b32_e32 v237, 0xffff0000, v236
	v_lshlrev_b32_e32 v236, 16, v236
	v_pk_add_f32 v[234:235], v[116:117], v[234:235]
	v_pk_add_f32 v[212:213], v[118:119], v[212:213]
	v_pk_add_f32 v[236:237], v[112:113], v[236:237]
	v_pk_add_f32 v[214:215], v[114:115], v[214:215]
	v_cvt_pk_bf16_f32 v116, v234, v235
	v_cvt_pk_bf16_f32 v117, v212, v213
	v_cvt_pk_bf16_f32 v118, v236, v237
	v_cvt_pk_bf16_f32 v119, v214, v215
	global_store_dwordx4 v169, v[116:119], s[42:43] offset:256
	v_mul_f32_e32 v112, v235, v235
	v_mul_f32_e32 v113, v213, v213
	v_mul_f32_e32 v114, v237, v237
	v_mul_f32_e32 v115, v215, v215
	v_fmac_f32_e32 v112, v234, v234
	v_fmac_f32_e32 v113, v212, v212
	v_fmac_f32_e32 v114, v236, v236
	v_fmac_f32_e32 v115, v214, v214
	v_add_f32_e32 v112, v112, v113
	v_add_f32_e32 v112, v114, v112
	v_add_f32_e32 v112, v115, v112
	v_add_f32_e32 v120, v120, v112
	v_add_u32_e32 v169, 0x58000, v168
	global_load_dwordx4 v[230:233], v169, s[42:43]
	global_load_dwordx4 v[234:237], v169, s[42:43] offset:256
	v_add_u32_e32 v169, 0x8000, v168
	s_nop 0
	v_lshlrev_b32_e32 v212, 16, v239
	v_and_b32_e32 v213, 0xffff0000, v239
	v_and_b32_e32 v239, 0xffff0000, v238
	v_lshlrev_b32_e32 v238, 16, v238
	v_lshlrev_b32_e32 v214, 16, v241
	v_and_b32_e32 v215, 0xffff0000, v241
	v_and_b32_e32 v241, 0xffff0000, v240
	v_lshlrev_b32_e32 v240, 16, v240
	v_pk_add_f32 v[238:239], v[108:109], v[238:239]
	v_pk_add_f32 v[212:213], v[110:111], v[212:213]
	v_pk_add_f32 v[240:241], v[104:105], v[240:241]
	v_pk_add_f32 v[214:215], v[106:107], v[214:215]
	v_cvt_pk_bf16_f32 v108, v238, v239
	v_cvt_pk_bf16_f32 v109, v212, v213
	v_cvt_pk_bf16_f32 v110, v240, v241
	v_cvt_pk_bf16_f32 v111, v214, v215
	global_store_dwordx4 v169, v[108:111], s[42:43]
	v_mul_f32_e32 v104, v239, v239
	v_mul_f32_e32 v105, v213, v213
	v_mul_f32_e32 v106, v241, v241
	v_mul_f32_e32 v107, v215, v215
	v_fmac_f32_e32 v104, v238, v238
	v_fmac_f32_e32 v105, v212, v212
	v_fmac_f32_e32 v106, v240, v240
	v_fmac_f32_e32 v107, v214, v214
	v_add_f32_e32 v104, v104, v105
	v_add_f32_e32 v104, v106, v104
	v_add_f32_e32 v104, v107, v104
	s_nop 0
	v_lshlrev_b32_e32 v212, 16, v243
	v_and_b32_e32 v213, 0xffff0000, v243
	v_and_b32_e32 v243, 0xffff0000, v242
	v_lshlrev_b32_e32 v242, 16, v242
	v_lshlrev_b32_e32 v214, 16, v245
	v_and_b32_e32 v215, 0xffff0000, v245
	v_and_b32_e32 v245, 0xffff0000, v244
	v_lshlrev_b32_e32 v244, 16, v244
	v_pk_add_f32 v[242:243], v[100:101], v[242:243]
	v_pk_add_f32 v[212:213], v[102:103], v[212:213]
	v_pk_add_f32 v[244:245], v[96:97], v[244:245]
	v_pk_add_f32 v[214:215], v[98:99], v[214:215]
	v_cvt_pk_bf16_f32 v100, v242, v243
	v_cvt_pk_bf16_f32 v101, v212, v213
	v_cvt_pk_bf16_f32 v102, v244, v245
	v_cvt_pk_bf16_f32 v103, v214, v215
	global_store_dwordx4 v169, v[100:103], s[42:43] offset:256
	v_mul_f32_e32 v96, v243, v243
	v_mul_f32_e32 v97, v213, v213
	v_mul_f32_e32 v98, v245, v245
	v_mul_f32_e32 v99, v215, v215
	v_fmac_f32_e32 v96, v242, v242
	v_fmac_f32_e32 v97, v212, v212
	v_fmac_f32_e32 v98, v244, v244
	v_fmac_f32_e32 v99, v214, v214
	v_add_f32_e32 v96, v96, v97
	v_add_f32_e32 v96, v98, v96
	v_add_f32_e32 v96, v99, v96
	v_add_f32_e32 v104, v104, v96
	v_add_u32_e32 v169, 0x10000, v168
	s_nop 0
	v_lshlrev_b32_e32 v212, 16, v247
	v_and_b32_e32 v213, 0xffff0000, v247
;     __device__ __forceinline__ void operator()(const f32x4 (&acc)[2], int srow, int cgp, int kq) const { one(acc[0], srow, 2 * cgp, kq); one(acc[1], srow, 2 * cgp + 1, kq); }
;     __device__ __forceinline__ void operator()(AccRef acc, const pg8::Unit& u, int wr, int wc, int fr, int fq) const {
;         const int row0 = u.pm * 256 + wr * 64 + fr, col0 = u.pn * 256 + wc * 32 + 8 * fq;
; #pragma unroll
;         for (int ai = 0; ai < 2; ++ai)
; #pragma unroll
;             for (int m = 0; m < 4; ++m) {
;                 const int row = row0 + ai * 128 + m * 16; float ss = 0.f;
; #pragma unroll
;                 for (int bj = 0; bj < 2; ++bj) {
;                     bf16_t* xp = xb + (size_t)row * D + col0 + bj * 128;
;                     f32x4 a, b; unpack8(*(const u32x4*)xp, a, b);
;                     a += acc[ai][bj][m][0] * alpha; b += acc[ai][bj][m][1] * alpha;
;                     *(u32x4*)xp = pack8(a, b);
;                     ss += (a[0] * a[0] + a[1] * a[1]) + (a[2] * a[2] + a[3] * a[3]) + (b[0] * b[0] + b[1] * b[1]) + (b[2] * b[2] + b[3] * b[3]);
;                 }
;                 ss += __shfl_xor(ss, 16); ss += __shfl_xor(ss, 32);
;                 if (fq == 0) ssp[(size_t)row * 16 + u.pn * 4 + wc] = ss;
;             }
;     }
	v_and_b32_e32 v247, 0xffff0000, v246
	v_lshlrev_b32_e32 v246, 16, v246
	v_lshlrev_b32_e32 v214, 16, v249
	v_and_b32_e32 v215, 0xffff0000, v249
	v_and_b32_e32 v249, 0xffff0000, v248
	v_lshlrev_b32_e32 v248, 16, v248
	v_pk_add_f32 v[246:247], v[92:93], v[246:247]
	v_pk_add_f32 v[212:213], v[94:95], v[212:213]
	v_pk_add_f32 v[248:249], v[88:89], v[248:249]
	v_pk_add_f32 v[214:215], v[90:91], v[214:215]
	v_cvt_pk_bf16_f32 v92, v246, v247
	v_cvt_pk_bf16_f32 v93, v212, v213
	v_cvt_pk_bf16_f32 v94, v248, v249
	v_cvt_pk_bf16_f32 v95, v214, v215
	global_store_dwordx4 v169, v[92:95], s[42:43]
	v_mul_f32_e32 v88, v247, v247
	v_mul_f32_e32 v89, v213, v213
	v_mul_f32_e32 v90, v249, v249
	v_mul_f32_e32 v91, v215, v215
	v_fmac_f32_e32 v88, v246, v246
	v_fmac_f32_e32 v89, v212, v212
	v_fmac_f32_e32 v90, v248, v248
	v_fmac_f32_e32 v91, v214, v214
	v_add_f32_e32 v88, v88, v89
	v_add_f32_e32 v88, v90, v88
	v_add_f32_e32 v88, v91, v88
	s_nop 0
	v_lshlrev_b32_e32 v212, 16, v251
	v_and_b32_e32 v213, 0xffff0000, v251
	v_and_b32_e32 v251, 0xffff0000, v250
	v_lshlrev_b32_e32 v250, 16, v250
	v_lshlrev_b32_e32 v214, 16, v253
	v_and_b32_e32 v215, 0xffff0000, v253
	v_and_b32_e32 v253, 0xffff0000, v252
	v_lshlrev_b32_e32 v252, 16, v252
	v_pk_add_f32 v[250:251], v[84:85], v[250:251]
	v_pk_add_f32 v[212:213], v[86:87], v[212:213]
	v_pk_add_f32 v[252:253], v[80:81], v[252:253]
	v_pk_add_f32 v[214:215], v[82:83], v[214:215]
	v_cvt_pk_bf16_f32 v84, v250, v251
	v_cvt_pk_bf16_f32 v85, v212, v213
	v_cvt_pk_bf16_f32 v86, v252, v253
	v_cvt_pk_bf16_f32 v87, v214, v215
	global_store_dwordx4 v169, v[84:87], s[42:43] offset:256
	v_mul_f32_e32 v80, v251, v251
	v_mul_f32_e32 v81, v213, v213
	v_mul_f32_e32 v82, v253, v253
	v_mul_f32_e32 v83, v215, v215
	v_fmac_f32_e32 v80, v250, v250
	v_fmac_f32_e32 v81, v212, v212
	v_fmac_f32_e32 v82, v252, v252
	v_fmac_f32_e32 v83, v214, v214
	v_add_f32_e32 v80, v80, v81
	v_add_f32_e32 v80, v82, v80
	v_add_f32_e32 v80, v83, v80
	v_add_f32_e32 v88, v88, v80
	v_add_u32_e32 v169, 0x18000, v168
	s_waitcnt vmcnt(15)
	v_lshlrev_b32_e32 v212, 16, v181
	v_and_b32_e32 v213, 0xffff0000, v181
	v_and_b32_e32 v181, 0xffff0000, v180
	v_lshlrev_b32_e32 v180, 16, v180
	v_lshlrev_b32_e32 v214, 16, v183
	v_and_b32_e32 v215, 0xffff0000, v183
	v_and_b32_e32 v183, 0xffff0000, v182
	v_lshlrev_b32_e32 v182, 16, v182
	v_pk_add_f32 v[180:181], v[76:77], v[180:181]
	v_pk_add_f32 v[212:213], v[78:79], v[212:213]
	v_pk_add_f32 v[182:183], v[72:73], v[182:183]
	v_pk_add_f32 v[214:215], v[74:75], v[214:215]
	v_cvt_pk_bf16_f32 v76, v180, v181
	v_cvt_pk_bf16_f32 v77, v212, v213
	v_cvt_pk_bf16_f32 v78, v182, v183
	v_cvt_pk_bf16_f32 v79, v214, v215
	global_store_dwordx4 v169, v[76:79], s[42:43]
	v_mul_f32_e32 v72, v181, v181
	v_mul_f32_e32 v73, v213, v213
	v_mul_f32_e32 v74, v183, v183
	v_mul_f32_e32 v75, v215, v215
	v_fmac_f32_e32 v72, v180, v180
	v_fmac_f32_e32 v73, v212, v212
	v_fmac_f32_e32 v74, v182, v182
	v_fmac_f32_e32 v75, v214, v214
	v_add_f32_e32 v72, v72, v73
	v_add_f32_e32 v72, v74, v72
	v_add_f32_e32 v72, v75, v72
	s_waitcnt vmcnt(15)
	v_lshlrev_b32_e32 v212, 16, v185
	v_and_b32_e32 v213, 0xffff0000, v185
	v_and_b32_e32 v185, 0xffff0000, v184
	v_lshlrev_b32_e32 v184, 16, v184
	v_lshlrev_b32_e32 v214, 16, v187
	v_and_b32_e32 v215, 0xffff0000, v187
	v_and_b32_e32 v187, 0xffff0000, v186
	v_lshlrev_b32_e32 v186, 16, v186
	v_pk_add_f32 v[184:185], v[68:69], v[184:185]
	v_pk_add_f32 v[212:213], v[70:71], v[212:213]
	v_pk_add_f32 v[186:187], v[64:65], v[186:187]
	v_pk_add_f32 v[214:215], v[66:67], v[214:215]
	v_cvt_pk_bf16_f32 v68, v184, v185
	v_cvt_pk_bf16_f32 v69, v212, v213
	v_cvt_pk_bf16_f32 v70, v186, v187
	v_cvt_pk_bf16_f32 v71, v214, v215
	global_store_dwordx4 v169, v[68:71], s[42:43] offset:256
	v_mul_f32_e32 v64, v185, v185
	v_mul_f32_e32 v65, v213, v213
	v_mul_f32_e32 v66, v187, v187
	v_mul_f32_e32 v67, v215, v215
	v_fmac_f32_e32 v64, v184, v184
	v_fmac_f32_e32 v65, v212, v212
	v_fmac_f32_e32 v66, v186, v186
	v_fmac_f32_e32 v67, v214, v214
	v_add_f32_e32 v64, v64, v65
	v_add_f32_e32 v64, v66, v64
	v_add_f32_e32 v64, v67, v64
	v_add_f32_e32 v72, v72, v64
	v_add_u32_e32 v169, 0x40000, v168
	s_waitcnt vmcnt(15)
	v_lshlrev_b32_e32 v212, 16, v189
	v_and_b32_e32 v213, 0xffff0000, v189
	v_and_b32_e32 v189, 0xffff0000, v188
	v_lshlrev_b32_e32 v188, 16, v188
	v_lshlrev_b32_e32 v214, 16, v191
	v_and_b32_e32 v215, 0xffff0000, v191
	v_and_b32_e32 v191, 0xffff0000, v190
	v_lshlrev_b32_e32 v190, 16, v190
	v_pk_add_f32 v[188:189], v[60:61], v[188:189]
	v_pk_add_f32 v[212:213], v[62:63], v[212:213]
	v_pk_add_f32 v[190:191], v[56:57], v[190:191]
	v_pk_add_f32 v[214:215], v[58:59], v[214:215]
	v_cvt_pk_bf16_f32 v60, v188, v189
	v_cvt_pk_bf16_f32 v61, v212, v213
	v_cvt_pk_bf16_f32 v62, v190, v191
	v_cvt_pk_bf16_f32 v63, v214, v215
	global_store_dwordx4 v169, v[60:63], s[42:43]
	v_mul_f32_e32 v56, v189, v189
	v_mul_f32_e32 v57, v213, v213
	v_mul_f32_e32 v58, v191, v191
	v_mul_f32_e32 v59, v215, v215
	v_fmac_f32_e32 v56, v188, v188
	v_fmac_f32_e32 v57, v212, v212
	v_fmac_f32_e32 v58, v190, v190
	v_fmac_f32_e32 v59, v214, v214
	v_add_f32_e32 v56, v56, v57
	v_add_f32_e32 v56, v58, v56
	v_add_f32_e32 v56, v59, v56
	s_waitcnt vmcnt(15)
;     __device__ __forceinline__ void operator()(const f32x4 (&acc)[2], int srow, int cgp, int kq) const { one(acc[0], srow, 2 * cgp, kq); one(acc[1], srow, 2 * cgp + 1, kq); }
;     __device__ __forceinline__ void operator()(AccRef acc, const pg8::Unit& u, int wr, int wc, int fr, int fq) const {
;         const int row0 = u.pm * 256 + wr * 64 + fr, col0 = u.pn * 256 + wc * 32 + 8 * fq;
; #pragma unroll
;         for (int ai = 0; ai < 2; ++ai)
; #pragma unroll
;             for (int m = 0; m < 4; ++m) {
;                 const int row = row0 + ai * 128 + m * 16; float ss = 0.f;
; #pragma unroll
;                 for (int bj = 0; bj < 2; ++bj) {
;                     bf16_t* xp = xb + (size_t)row * D + col0 + bj * 128;
;                     f32x4 a, b; unpack8(*(const u32x4*)xp, a, b);
;                     a += acc[ai][bj][m][0] * alpha; b += acc[ai][bj][m][1] * alpha;
;                     *(u32x4*)xp = pack8(a, b);
;                     ss += (a[0] * a[0] + a[1] * a[1]) + (a[2] * a[2] + a[3] * a[3]) + (b[0] * b[0] + b[1] * b[1]) + (b[2] * b[2] + b[3] * b[3]);
;                 }
;                 ss += __shfl_xor(ss, 16); ss += __shfl_xor(ss, 32);
;                 if (fq == 0) ssp[(size_t)row * 16 + u.pn * 4 + wc] = ss;
;             }
;     }
	v_lshlrev_b32_e32 v212, 16, v193
	v_and_b32_e32 v213, 0xffff0000, v193
	v_and_b32_e32 v193, 0xffff0000, v192
	v_lshlrev_b32_e32 v192, 16, v192
	v_lshlrev_b32_e32 v214, 16, v195
	v_and_b32_e32 v215, 0xffff0000, v195
	v_and_b32_e32 v195, 0xffff0000, v194
	v_lshlrev_b32_e32 v194, 16, v194
	v_pk_add_f32 v[192:193], v[52:53], v[192:193]
	v_pk_add_f32 v[212:213], v[54:55], v[212:213]
	v_pk_add_f32 v[194:195], v[48:49], v[194:195]
	v_pk_add_f32 v[214:215], v[50:51], v[214:215]
	v_cvt_pk_bf16_f32 v52, v192, v193
	v_cvt_pk_bf16_f32 v53, v212, v213
	v_cvt_pk_bf16_f32 v54, v194, v195
	v_cvt_pk_bf16_f32 v55, v214, v215
	global_store_dwordx4 v169, v[52:55], s[42:43] offset:256
	v_mul_f32_e32 v48, v193, v193
	v_mul_f32_e32 v49, v213, v213
	v_mul_f32_e32 v50, v195, v195
	v_mul_f32_e32 v51, v215, v215
	v_fmac_f32_e32 v48, v192, v192
	v_fmac_f32_e32 v49, v212, v212
	v_fmac_f32_e32 v50, v194, v194
	v_fmac_f32_e32 v51, v214, v214
	v_add_f32_e32 v48, v48, v49
	v_add_f32_e32 v48, v50, v48
	v_add_f32_e32 v48, v51, v48
	v_add_f32_e32 v56, v56, v48
	v_add_u32_e32 v169, 0x48000, v168
	s_waitcnt vmcnt(15)
	v_lshlrev_b32_e32 v212, 16, v197
	v_and_b32_e32 v213, 0xffff0000, v197
	v_and_b32_e32 v197, 0xffff0000, v196
	v_lshlrev_b32_e32 v196, 16, v196
	v_lshlrev_b32_e32 v214, 16, v199
	v_and_b32_e32 v215, 0xffff0000, v199
	v_and_b32_e32 v199, 0xffff0000, v198
	v_lshlrev_b32_e32 v198, 16, v198
	v_pk_add_f32 v[196:197], v[44:45], v[196:197]
	v_pk_add_f32 v[212:213], v[46:47], v[212:213]
	v_pk_add_f32 v[198:199], v[40:41], v[198:199]
	v_pk_add_f32 v[214:215], v[42:43], v[214:215]
	v_cvt_pk_bf16_f32 v44, v196, v197
	v_cvt_pk_bf16_f32 v45, v212, v213
	v_cvt_pk_bf16_f32 v46, v198, v199
	v_cvt_pk_bf16_f32 v47, v214, v215
	global_store_dwordx4 v169, v[44:47], s[42:43]
	v_mul_f32_e32 v40, v197, v197
	v_mul_f32_e32 v41, v213, v213
	v_mul_f32_e32 v42, v199, v199
	v_mul_f32_e32 v43, v215, v215
	v_fmac_f32_e32 v40, v196, v196
	v_fmac_f32_e32 v41, v212, v212
	v_fmac_f32_e32 v42, v198, v198
	v_fmac_f32_e32 v43, v214, v214
	v_add_f32_e32 v40, v40, v41
	v_add_f32_e32 v40, v42, v40
	v_add_f32_e32 v40, v43, v40
	s_waitcnt vmcnt(15)
	v_lshlrev_b32_e32 v212, 16, v201
	v_and_b32_e32 v213, 0xffff0000, v201
	v_and_b32_e32 v201, 0xffff0000, v200
	v_lshlrev_b32_e32 v200, 16, v200
	v_lshlrev_b32_e32 v214, 16, v203
	v_and_b32_e32 v215, 0xffff0000, v203
	v_and_b32_e32 v203, 0xffff0000, v202
	v_lshlrev_b32_e32 v202, 16, v202
	v_pk_add_f32 v[200:201], v[36:37], v[200:201]
	v_pk_add_f32 v[212:213], v[38:39], v[212:213]
	v_pk_add_f32 v[202:203], v[32:33], v[202:203]
	v_pk_add_f32 v[214:215], v[34:35], v[214:215]
	v_cvt_pk_bf16_f32 v36, v200, v201
	v_cvt_pk_bf16_f32 v37, v212, v213
	v_cvt_pk_bf16_f32 v38, v202, v203
	v_cvt_pk_bf16_f32 v39, v214, v215
	global_store_dwordx4 v169, v[36:39], s[42:43] offset:256
	v_mul_f32_e32 v32, v201, v201
	v_mul_f32_e32 v33, v213, v213
	v_mul_f32_e32 v34, v203, v203
	v_mul_f32_e32 v35, v215, v215
	v_fmac_f32_e32 v32, v200, v200
	v_fmac_f32_e32 v33, v212, v212
	v_fmac_f32_e32 v34, v202, v202
	v_fmac_f32_e32 v35, v214, v214
	v_add_f32_e32 v32, v32, v33
	v_add_f32_e32 v32, v34, v32
	v_add_f32_e32 v32, v35, v32
	v_add_f32_e32 v40, v40, v32
	v_add_u32_e32 v169, 0x50000, v168
	s_waitcnt vmcnt(15)
	v_lshlrev_b32_e32 v212, 16, v205
	v_and_b32_e32 v213, 0xffff0000, v205
	v_and_b32_e32 v205, 0xffff0000, v204
	v_lshlrev_b32_e32 v204, 16, v204
	v_lshlrev_b32_e32 v214, 16, v207
	v_and_b32_e32 v215, 0xffff0000, v207
	v_and_b32_e32 v207, 0xffff0000, v206
	v_lshlrev_b32_e32 v206, 16, v206
	v_pk_add_f32 v[204:205], v[28:29], v[204:205]
	v_pk_add_f32 v[212:213], v[30:31], v[212:213]
	v_pk_add_f32 v[206:207], v[24:25], v[206:207]
	v_pk_add_f32 v[214:215], v[26:27], v[214:215]
	v_cvt_pk_bf16_f32 v28, v204, v205
	v_cvt_pk_bf16_f32 v29, v212, v213
	v_cvt_pk_bf16_f32 v30, v206, v207
	v_cvt_pk_bf16_f32 v31, v214, v215
	global_store_dwordx4 v169, v[28:31], s[42:43]
	v_mul_f32_e32 v24, v205, v205
	v_mul_f32_e32 v25, v213, v213
	v_mul_f32_e32 v26, v207, v207
	v_mul_f32_e32 v27, v215, v215
	v_fmac_f32_e32 v24, v204, v204
	v_fmac_f32_e32 v25, v212, v212
	v_fmac_f32_e32 v26, v206, v206
	v_fmac_f32_e32 v27, v214, v214
	v_add_f32_e32 v24, v24, v25
	v_add_f32_e32 v24, v26, v24
	v_add_f32_e32 v24, v27, v24
	s_waitcnt vmcnt(15)
;     __device__ __forceinline__ void operator()(AccRef acc, const pg8::Unit& u, int wr, int wc, int fr, int fq) const {
;     ...
;             for (int m = 0; m < 4; ++m) {
;                 const int row = row0 + ai * 128 + m * 16; float ss = 0.f;
; #pragma unroll
;                 for (int bj = 0; bj < 2; ++bj) {
;                     bf16_t* xp = xb + (size_t)row * D + col0 + bj * 128;
;                     f32x4 a, b; unpack8(*(const u32x4*)xp, a, b);
;                     a += acc[ai][bj][m][0] * alpha; b += acc[ai][bj][m][1] * alpha;
;                     *(u32x4*)xp = pack8(a, b);
;                     ss += (a[0] * a[0] + a[1] * a[1]) + (a[2] * a[2] + a[3] * a[3]) + (b[0] * b[0] + b[1] * b[1]) + (b[2] * b[2] + b[3] * b[3]);
;                 }
;                 ss += __shfl_xor(ss, 16); ss += __shfl_xor(ss, 32);
;                 if (fq == 0) ssp[(size_t)row * 16 + u.pn * 4 + wc] = ss;
;             }
;     }
	v_lshlrev_b32_e32 v212, 16, v209
	v_and_b32_e32 v213, 0xffff0000, v209
	v_and_b32_e32 v209, 0xffff0000, v208
	v_lshlrev_b32_e32 v208, 16, v208
	v_lshlrev_b32_e32 v214, 16, v211
	v_and_b32_e32 v215, 0xffff0000, v211
	v_and_b32_e32 v211, 0xffff0000, v210
	v_lshlrev_b32_e32 v210, 16, v210
	v_pk_add_f32 v[208:209], v[20:21], v[208:209]
	v_pk_add_f32 v[212:213], v[22:23], v[212:213]
	v_pk_add_f32 v[210:211], v[16:17], v[210:211]
	v_pk_add_f32 v[214:215], v[18:19], v[214:215]
	v_cvt_pk_bf16_f32 v20, v208, v209
	v_cvt_pk_bf16_f32 v21, v212, v213
	v_cvt_pk_bf16_f32 v22, v210, v211
	v_cvt_pk_bf16_f32 v23, v214, v215
	global_store_dwordx4 v169, v[20:23], s[42:43] offset:256
	v_mul_f32_e32 v16, v209, v209
	v_mul_f32_e32 v17, v213, v213
	v_mul_f32_e32 v18, v211, v211
	v_mul_f32_e32 v19, v215, v215
	v_fmac_f32_e32 v16, v208, v208
	v_fmac_f32_e32 v17, v212, v212
	v_fmac_f32_e32 v18, v210, v210
	v_fmac_f32_e32 v19, v214, v214
	v_add_f32_e32 v16, v16, v17
	v_add_f32_e32 v16, v18, v16
	v_add_f32_e32 v16, v19, v16
	v_add_f32_e32 v24, v24, v16
	v_add_u32_e32 v169, 0x58000, v168
	s_waitcnt vmcnt(13)
	v_lshlrev_b32_e32 v212, 16, v231
	v_and_b32_e32 v213, 0xffff0000, v231
	v_and_b32_e32 v231, 0xffff0000, v230
	v_lshlrev_b32_e32 v230, 16, v230
	v_lshlrev_b32_e32 v214, 16, v233
	v_and_b32_e32 v215, 0xffff0000, v233
	v_and_b32_e32 v233, 0xffff0000, v232
	v_lshlrev_b32_e32 v232, 16, v232
	v_pk_add_f32 v[230:231], v[12:13], v[230:231]
	v_pk_add_f32 v[212:213], v[14:15], v[212:213]
	v_pk_add_f32 v[232:233], v[8:9], v[232:233]
	v_pk_add_f32 v[214:215], v[10:11], v[214:215]
	v_cvt_pk_bf16_f32 v12, v230, v231
	v_cvt_pk_bf16_f32 v13, v212, v213
	v_cvt_pk_bf16_f32 v14, v232, v233
	v_cvt_pk_bf16_f32 v15, v214, v215
	global_store_dwordx4 v169, v[12:15], s[42:43]
	v_mul_f32_e32 v8, v231, v231
	v_mul_f32_e32 v9, v213, v213
	v_mul_f32_e32 v10, v233, v233
	v_mul_f32_e32 v11, v215, v215
	v_fmac_f32_e32 v8, v230, v230
	v_fmac_f32_e32 v9, v212, v212
	v_fmac_f32_e32 v10, v232, v232
	v_fmac_f32_e32 v11, v214, v214
	v_add_f32_e32 v8, v8, v9
	v_add_f32_e32 v8, v10, v8
	v_add_f32_e32 v8, v11, v8
	s_waitcnt vmcnt(13)
	v_lshlrev_b32_e32 v212, 16, v235
	v_and_b32_e32 v213, 0xffff0000, v235
	v_and_b32_e32 v235, 0xffff0000, v234
	v_lshlrev_b32_e32 v234, 16, v234
	v_lshlrev_b32_e32 v214, 16, v237
	v_and_b32_e32 v215, 0xffff0000, v237
	v_and_b32_e32 v237, 0xffff0000, v236
	v_lshlrev_b32_e32 v236, 16, v236
	v_pk_add_f32 v[234:235], v[4:5], v[234:235]
	v_pk_add_f32 v[212:213], v[6:7], v[212:213]
	v_pk_add_f32 v[236:237], v[0:1], v[236:237]
	v_pk_add_f32 v[214:215], v[2:3], v[214:215]
	v_cvt_pk_bf16_f32 v4, v234, v235
	v_cvt_pk_bf16_f32 v5, v212, v213
	v_cvt_pk_bf16_f32 v6, v236, v237
	v_cvt_pk_bf16_f32 v7, v214, v215
	global_store_dwordx4 v169, v[4:7], s[42:43] offset:256
	v_mul_f32_e32 v0, v235, v235
	v_mul_f32_e32 v1, v213, v213
	v_mul_f32_e32 v2, v237, v237
	v_mul_f32_e32 v3, v215, v215
	v_fmac_f32_e32 v0, v234, v234
	v_fmac_f32_e32 v1, v212, v212
	v_fmac_f32_e32 v2, v236, v236
	v_fmac_f32_e32 v3, v214, v214
	v_add_f32_e32 v0, v0, v1
	v_add_f32_e32 v0, v2, v0
	v_add_f32_e32 v0, v3, v0
	v_add_f32_e32 v8, v8, v0
	ds_bpermute_b32 v121, v171, v120
	ds_bpermute_b32 v105, v171, v104
	ds_bpermute_b32 v89, v171, v88
	ds_bpermute_b32 v73, v171, v72
	ds_bpermute_b32 v57, v171, v56
	ds_bpermute_b32 v41, v171, v40
	ds_bpermute_b32 v25, v171, v24
	ds_bpermute_b32 v9, v171, v8
	s_waitcnt lgkmcnt(0)
	v_add_f32_e32 v120, v120, v121
	v_add_f32_e32 v104, v104, v105
	v_add_f32_e32 v88, v88, v89
	v_add_f32_e32 v72, v72, v73
	v_add_f32_e32 v56, v56, v57
	v_add_f32_e32 v40, v40, v41
	v_add_f32_e32 v24, v24, v25
	v_add_f32_e32 v8, v8, v9
	ds_bpermute_b32 v121, v172, v120
	ds_bpermute_b32 v105, v172, v104
	ds_bpermute_b32 v89, v172, v88
	ds_bpermute_b32 v73, v172, v72
	ds_bpermute_b32 v57, v172, v56
	ds_bpermute_b32 v41, v172, v40
	ds_bpermute_b32 v25, v172, v24
	ds_bpermute_b32 v9, v172, v8
	s_waitcnt lgkmcnt(0)
	v_add_f32_e32 v120, v120, v121
	v_add_f32_e32 v104, v104, v105
	v_add_f32_e32 v88, v88, v89
	v_add_f32_e32 v72, v72, v73
	v_add_f32_e32 v56, v56, v57
	v_add_f32_e32 v40, v40, v41
	v_add_f32_e32 v24, v24, v25
	v_add_f32_e32 v8, v8, v9
	s_and_saveexec_b64 s[34:35], s[2:3]
	global_store_dword v170, v120, s[46:47]
	global_store_dword v170, v104, s[46:47] offset:1024
	global_store_dword v170, v88, s[46:47] offset:2048
	global_store_dword v170, v72, s[46:47] offset:3072
	global_store_dword v173, v56, s[46:47]
	global_store_dword v173, v40, s[46:47] offset:1024
	global_store_dword v173, v24, s[46:47] offset:2048
	global_store_dword v173, v8, s[46:47] offset:3072
	s_or_b64 exec, exec, s[34:35]
	s_and_b64 vcc, exec, s[4:5]
	s_mov_b64 s[4:5], -1

; template <class Epi, class Sched, bool ALIGN_EPI = false, bool SP2 = false>
; __device__ __forceinline__ void gemm_phase(PG8_LAS unsigned char* lds, const Gemm g, const Sched& S, const Epi& E) {
;     ...
;         const bool has_next = S.next(ui + 1, nxt);
;         const char* nA = has_next ? (const char*)g.A + (size_t)nxt.pm * tstep : cA; const char* nB = has_next ? (const char*)g.Bt + (size_t)nxt.pn * tstep : cB;
;     __device__ __forceinline__ void operator()(AccRef acc, const pg8::Unit& u, int wr, int wc, int fr, int fq) const {
;     ...
;                     bf16_t* xp = xb + (size_t)row * D + col0 + bj * 128;
;                     f32x4 a, b; unpack8(*(const u32x4*)xp, a, b);
.LBB0_2563:
	v_lshl_add_u32 v252, s60, 8, v156
	v_lshl_or_b32 v253, s14, 8, v158
	v_lshlrev_b32_e32 v253, 1, v253
	v_lshl_add_u32 v252, v252, 11, v253
	global_load_dwordx4 v[230:233], v252, s[42:43]
	global_load_dwordx4 v[234:237], v252, s[42:43] offset:256
	v_add_u32_e32 v253, 0x8000, v252
	global_load_dwordx4 v[238:241], v253, s[42:43]
	global_load_dwordx4 v[242:245], v253, s[42:43] offset:256
	v_add_u32_e32 v253, 0x10000, v252
	global_load_dwordx4 v[246:249], v253, s[42:43]
	global_load_dwordx4 v[250:253], v253, s[42:43] offset:256
	s_add_i32 s57, s57, 1
	s_mul_i32 s0, s57, s44
	s_mul_hi_u32 s1, s57, s45
	s_add_i32 s1, s1, s0
	s_mul_i32 s0, s57, s45
	s_add_u32 s4, s0, s18
	s_addc_u32 s5, s1, s50
	v_cmp_gt_i64_e32 vcc, s[4:5], v[142:143]
	v_cmp_lt_i64_e64 s[0:1], s[4:5], v[140:141]
	s_cbranch_vccnz .LBB0_2569
	s_ashr_i32 s5, s4, 31
	s_lshr_b32 s5, s5, 29
	s_add_i32 s28, s4, s5
	s_and_b32 s5, s28, -8
	s_sub_i32 s29, s4, s5
	s_cmp_gt_i32 s29, -1
	s_mov_b64 s[4:5], -1
	s_cbranch_scc0 .LBB0_2566
	s_lshl_b32 s58, s29, 6
	s_mov_b64 s[4:5], 0

; #define PG8_STAGE(bufoff, gbase, voff) do { _Pragma("unroll") for (int _i = 0; _i < 2; ++_i) \
;         __builtin_amdgcn_global_load_lds((const unsigned*)((const char*)(gbase) + (voff)[_i]), (PG8_LAS unsigned*)(lds + (bufoff) + ldsw + _i * 8192), 16, 0, 0); } while (0)
; #define PG8_LDA(dst, b, h) do { _Pragma("unroll") for (int m = 0; m < 4; ++m) _Pragma("unroll") for (int k = 0; k < 2; ++k) dst[m][k] = *(const PG8_LAS bf16x8*)(lds + PG8_SA(b, h) + aoff + m * 2048 + k * 1024); } while (0)
; #define PG8_LDB(dst, b, h) do { _Pragma("unroll") for (int n = 0; n < 2; ++n) _Pragma("unroll") for (int k = 0; k < 2; ++k) dst[n][k] = *(const PG8_LAS bf16x8*)(lds + PG8_SB(b, h) + boff + n * 2048 + k * 1024); } while (0)
; #define PG8_MMA(ai, bj, At, Bt) do { __builtin_amdgcn_s_setprio(1); _Pragma("unroll") for (int m = 0; m < 4; ++m) _Pragma("unroll") for (int n = 0; n < 2; ++n) _Pragma("unroll") for (int k = 0; k < 2; ++k) \
;         acc[ai][bj][m][n] = __builtin_amdgcn_mfma_f32_16x16x32_bf16(Bt[n][k], At[m][k], acc[ai][bj][m][n], 0, 0, 0); __builtin_amdgcn_s_setprio(0); } while (0)
; #define PG8_WAIT_V(n) asm volatile("s_waitcnt vmcnt(" #n ")" ::: "memory")
; #define PG8_WAIT_L(n) asm volatile("s_waitcnt lgkmcnt(" #n ")" ::: "memory")
; #define PG8_BAR __builtin_amdgcn_s_barrier()
; #define PG8_SCHED __builtin_amdgcn_sched_barrier(0)
; template <class Epi, class Sched, bool ALIGN_EPI = false, bool SP2 = false>
; __device__ __forceinline__ void gemm_phase(PG8_LAS unsigned char* lds, const Gemm g, const Sched& S, const Epi& E) {
;     ...
;             PG8_LDB(B0, 0, 0); PG8_LDB(B1, 0, 1); PG8_SCHED; PG8_LDA(At, 0, 0); PG8_STAGE(PG8_SA(1, 1), a1 + hstep, voffA);
;             PG8_WAIT_V(8); PG8_WAIT_L(0); PG8_BAR; PG8_MMA(0, 0, At, B0); PG8_MMA(0, 1, At, B1); PG8_BAR; PG8_SCHED;
;             PG8_LDA(At, 0, 1); PG8_STAGE(PG8_SB(0, 0), b2, voffB); PG8_STAGE(PG8_SB(0, 1), b2 + hstep, voffB); PG8_STAGE(PG8_SA(0, 0), a2, voffA);
;             PG8_WAIT_V(8); PG8_WAIT_L(0); PG8_BAR; PG8_MMA(1, 0, At, B0); PG8_MMA(1, 1, At, B1); PG8_BAR; PG8_SCHED;
.LBB0_2575:
	ds_read_b128 v[144:147], v159
	ds_read_b128 v[148:151], v159 offset:1024
	ds_read_b128 v[152:155], v159 offset:2048
	ds_read_b128 v[164:167], v159 offset:3072
	ds_read_b128 v[168:171], v160
	ds_read_b128 v[172:175], v160 offset:1024
	ds_read_b128 v[176:179], v160 offset:2048
	ds_read_b128 v[180:183], v160 offset:3072
	s_add_i32 s63, s34, 2
	s_add_u32 s64, s30, 0x80
	s_addc_u32 s35, s31, 0
	s_cmp_eq_u32 s41, s34
	s_cselect_b32 s34, s0, s64
	s_cselect_b32 s35, s1, s35
	s_cselect_b32 s65, s29, s62
	s_cselect_b32 s64, s28, s61
	v_lshl_add_u64 v[216:217], s[30:31], 0, v[136:137]
	s_add_i32 m0, s17, 0xc000
	ds_read_b128 v[184:187], v161
	ds_read_b128 v[188:191], v161 offset:1024
	ds_read_b128 v[192:195], v161 offset:2048
	ds_read_b128 v[196:199], v161 offset:3072
	ds_read_b128 v[200:203], v161 offset:4096
	ds_read_b128 v[204:207], v161 offset:5120
	ds_read_b128 v[208:211], v161 offset:6144
	ds_read_b128 v[212:215], v161 offset:7168
	global_load_lds_dwordx4 v[216:217], off
	v_lshl_add_u64 v[216:217], s[30:31], 0, v[138:139]
	s_add_i32 m0, s17, 0xe000
	s_nop 0
	global_load_lds_dwordx4 v[216:217], off
	s_waitcnt vmcnt(8)
	s_waitcnt lgkmcnt(0)
	s_barrier
	s_setprio 1
	s_waitcnt lgkmcnt(0)
	v_mfma_f32_16x16x32_bf16 v[124:127], v[144:147], v[184:187], v[124:127]
	v_mfma_f32_16x16x32_bf16 v[120:123], v[152:155], v[184:187], v[120:123]
	v_mfma_f32_16x16x32_bf16 v[116:119], v[144:147], v[192:195], v[116:119]
	v_mfma_f32_16x16x32_bf16 v[112:115], v[152:155], v[192:195], v[112:115]
	v_mfma_f32_16x16x32_bf16 v[104:107], v[144:147], v[200:203], v[104:107]
	v_mfma_f32_16x16x32_bf16 v[96:99], v[152:155], v[200:203], v[96:99]
	v_mfma_f32_16x16x32_bf16 v[88:91], v[144:147], v[208:211], v[88:91]
	v_mfma_f32_16x16x32_bf16 v[80:83], v[152:155], v[208:211], v[80:83]
	v_mfma_f32_16x16x32_bf16 v[124:127], v[148:151], v[188:191], v[124:127]
	v_mfma_f32_16x16x32_bf16 v[120:123], v[164:167], v[188:191], v[120:123]
	v_mfma_f32_16x16x32_bf16 v[116:119], v[148:151], v[196:199], v[116:119]
	v_mfma_f32_16x16x32_bf16 v[112:115], v[164:167], v[196:199], v[112:115]
	v_mfma_f32_16x16x32_bf16 v[104:107], v[148:151], v[204:207], v[104:107]
	v_mfma_f32_16x16x32_bf16 v[96:99], v[164:167], v[204:207], v[96:99]
	v_mfma_f32_16x16x32_bf16 v[88:91], v[148:151], v[212:215], v[88:91]
	v_mfma_f32_16x16x32_bf16 v[80:83], v[164:167], v[212:215], v[80:83]
	s_setprio 0
	s_setprio 1
	v_mfma_f32_16x16x32_bf16 v[108:111], v[168:171], v[184:187], v[108:111]
	v_mfma_f32_16x16x32_bf16 v[100:103], v[176:179], v[184:187], v[100:103]
	v_mfma_f32_16x16x32_bf16 v[92:95], v[168:171], v[192:195], v[92:95]
	v_mfma_f32_16x16x32_bf16 v[84:87], v[176:179], v[192:195], v[84:87]
	v_mfma_f32_16x16x32_bf16 v[76:79], v[168:171], v[200:203], v[76:79]
	v_mfma_f32_16x16x32_bf16 v[72:75], v[176:179], v[200:203], v[72:75]
	v_mfma_f32_16x16x32_bf16 v[68:71], v[168:171], v[208:211], v[68:71]
	v_mfma_f32_16x16x32_bf16 v[64:67], v[176:179], v[208:211], v[64:67]
	v_mfma_f32_16x16x32_bf16 v[108:111], v[172:175], v[188:191], v[108:111]
	v_mfma_f32_16x16x32_bf16 v[100:103], v[180:183], v[188:191], v[100:103]
	v_mfma_f32_16x16x32_bf16 v[92:95], v[172:175], v[196:199], v[92:95]
	v_mfma_f32_16x16x32_bf16 v[84:87], v[180:183], v[196:199], v[84:87]
	v_mfma_f32_16x16x32_bf16 v[76:79], v[172:175], v[204:207], v[76:79]
	v_mfma_f32_16x16x32_bf16 v[72:75], v[180:183], v[204:207], v[72:75]
	v_mfma_f32_16x16x32_bf16 v[68:71], v[172:175], v[212:215], v[68:71]
	v_mfma_f32_16x16x32_bf16 v[64:67], v[180:183], v[212:215], v[64:67]
	s_setprio 0
	s_barrier
	s_add_i32 s66, s51, s16
	v_lshl_add_u64 v[216:217], s[64:65], 0, v[130:131]
	s_mov_b32 m0, s66
	ds_read_b128 v[184:187], v161 offset:16384
	ds_read_b128 v[188:191], v161 offset:17408
	ds_read_b128 v[192:195], v161 offset:18432
	ds_read_b128 v[196:199], v161 offset:19456
	ds_read_b128 v[200:203], v161 offset:20480
	ds_read_b128 v[204:207], v161 offset:21504
	ds_read_b128 v[208:211], v161 offset:22528
	ds_read_b128 v[212:215], v161 offset:23552
	global_load_lds_dwordx4 v[216:217], off
	s_add_i32 m0, s66, 0x2000
	v_lshl_add_u64 v[218:219], s[64:65], 0, v[134:135]
	s_add_u32 s64, s64, s6
	s_addc_u32 s65, s65, s7
	s_add_i32 s66, s56, s16
	global_load_lds_dwordx4 v[218:219], off
	v_lshl_add_u64 v[220:221], s[64:65], 0, v[130:131]
	s_mov_b32 m0, s66
	v_lshl_add_u64 v[222:223], s[64:65], 0, v[134:135]
	global_load_lds_dwordx4 v[220:221], off
	s_add_i32 m0, s66, 0x2000
	v_lshl_add_u64 v[224:225], s[34:35], 0, v[128:129]
	global_load_lds_dwordx4 v[222:223], off
	s_mov_b32 m0, s17
	v_lshl_add_u64 v[226:227], s[34:35], 0, v[132:133]
	global_load_lds_dwordx4 v[224:225], off
	s_mov_b32 m0, s19
	s_nop 0
	global_load_lds_dwordx4 v[226:227], off
	s_waitcnt vmcnt(8)
	s_waitcnt lgkmcnt(0)
	s_barrier
; #define PG8_STAGE(bufoff, gbase, voff) do { _Pragma("unroll") for (int _i = 0; _i < 2; ++_i) \
;         __builtin_amdgcn_global_load_lds((const unsigned*)((const char*)(gbase) + (voff)[_i]), (PG8_LAS unsigned*)(lds + (bufoff) + ldsw + _i * 8192), 16, 0, 0); } while (0)
; #define PG8_LDA(dst, b, h) do { _Pragma("unroll") for (int m = 0; m < 4; ++m) _Pragma("unroll") for (int k = 0; k < 2; ++k) dst[m][k] = *(const PG8_LAS bf16x8*)(lds + PG8_SA(b, h) + aoff + m * 2048 + k * 1024); } while (0)
; #define PG8_LDB(dst, b, h) do { _Pragma("unroll") for (int n = 0; n < 2; ++n) _Pragma("unroll") for (int k = 0; k < 2; ++k) dst[n][k] = *(const PG8_LAS bf16x8*)(lds + PG8_SB(b, h) + boff + n * 2048 + k * 1024); } while (0)
; #define PG8_MMA(ai, bj, At, Bt) do { __builtin_amdgcn_s_setprio(1); _Pragma("unroll") for (int m = 0; m < 4; ++m) _Pragma("unroll") for (int n = 0; n < 2; ++n) _Pragma("unroll") for (int k = 0; k < 2; ++k) \
;         acc[ai][bj][m][n] = __builtin_amdgcn_mfma_f32_16x16x32_bf16(Bt[n][k], At[m][k], acc[ai][bj][m][n], 0, 0, 0); __builtin_amdgcn_s_setprio(0); } while (0)
; #define PG8_WAIT_V(n) asm volatile("s_waitcnt vmcnt(" #n ")" ::: "memory")
; #define PG8_WAIT_L(n) asm volatile("s_waitcnt lgkmcnt(" #n ")" ::: "memory")
; #define PG8_BAR __builtin_amdgcn_s_barrier()
; #define PG8_SCHED __builtin_amdgcn_sched_barrier(0)
; template <class Epi, class Sched, bool ALIGN_EPI = false, bool SP2 = false>
; __device__ __forceinline__ void gemm_phase(PG8_LAS unsigned char* lds, const Gemm g, const Sched& S, const Epi& E) {
;     ...
;             PG8_WAIT_V(8); PG8_WAIT_L(0); PG8_BAR; PG8_MMA(1, 0, At, B0); PG8_MMA(1, 1, At, B1); PG8_BAR; PG8_SCHED;
;             PG8_LDB(B0, 1, 0); PG8_LDB(B1, 1, 1); PG8_SCHED; PG8_LDA(At, 1, 0); PG8_STAGE(PG8_SA(0, 1), a2 + hstep, voffA);
;             PG8_WAIT_V(8); PG8_WAIT_L(0); PG8_BAR; PG8_MMA(0, 0, At, B0); PG8_MMA(0, 1, At, B1); PG8_BAR; PG8_SCHED;
	s_setprio 1
	s_waitcnt lgkmcnt(0)
	v_mfma_f32_16x16x32_bf16 v[60:63], v[144:147], v[184:187], v[60:63]
	v_mfma_f32_16x16x32_bf16 v[56:59], v[152:155], v[184:187], v[56:59]
	v_mfma_f32_16x16x32_bf16 v[52:55], v[144:147], v[192:195], v[52:55]
	v_mfma_f32_16x16x32_bf16 v[48:51], v[152:155], v[192:195], v[48:51]
	v_mfma_f32_16x16x32_bf16 v[40:43], v[144:147], v[200:203], v[40:43]
	v_mfma_f32_16x16x32_bf16 v[32:35], v[152:155], v[200:203], v[32:35]
	v_mfma_f32_16x16x32_bf16 v[24:27], v[144:147], v[208:211], v[24:27]
	v_mfma_f32_16x16x32_bf16 v[16:19], v[152:155], v[208:211], v[16:19]
	v_mfma_f32_16x16x32_bf16 v[60:63], v[148:151], v[188:191], v[60:63]
	v_mfma_f32_16x16x32_bf16 v[56:59], v[164:167], v[188:191], v[56:59]
	v_mfma_f32_16x16x32_bf16 v[52:55], v[148:151], v[196:199], v[52:55]
	v_mfma_f32_16x16x32_bf16 v[48:51], v[164:167], v[196:199], v[48:51]
	v_mfma_f32_16x16x32_bf16 v[40:43], v[148:151], v[204:207], v[40:43]
	v_mfma_f32_16x16x32_bf16 v[32:35], v[164:167], v[204:207], v[32:35]
	v_mfma_f32_16x16x32_bf16 v[24:27], v[148:151], v[212:215], v[24:27]
	v_mfma_f32_16x16x32_bf16 v[16:19], v[164:167], v[212:215], v[16:19]
	s_setprio 0
	s_setprio 1
	v_mfma_f32_16x16x32_bf16 v[44:47], v[168:171], v[184:187], v[44:47]
	v_mfma_f32_16x16x32_bf16 v[36:39], v[176:179], v[184:187], v[36:39]
	v_mfma_f32_16x16x32_bf16 v[28:31], v[168:171], v[192:195], v[28:31]
	v_mfma_f32_16x16x32_bf16 v[20:23], v[176:179], v[192:195], v[20:23]
	v_mfma_f32_16x16x32_bf16 v[12:15], v[168:171], v[200:203], v[12:15]
	v_mfma_f32_16x16x32_bf16 v[8:11], v[176:179], v[200:203], v[8:11]
	v_mfma_f32_16x16x32_bf16 v[4:7], v[168:171], v[208:211], v[4:7]
	v_mfma_f32_16x16x32_bf16 v[0:3], v[176:179], v[208:211], v[0:3]
	v_mfma_f32_16x16x32_bf16 v[44:47], v[172:175], v[188:191], v[44:47]
	v_mfma_f32_16x16x32_bf16 v[36:39], v[180:183], v[188:191], v[36:39]
	v_mfma_f32_16x16x32_bf16 v[28:31], v[172:175], v[196:199], v[28:31]
	v_mfma_f32_16x16x32_bf16 v[20:23], v[180:183], v[196:199], v[20:23]
	v_mfma_f32_16x16x32_bf16 v[12:15], v[172:175], v[204:207], v[12:15]
	v_mfma_f32_16x16x32_bf16 v[8:11], v[180:183], v[204:207], v[8:11]
	v_mfma_f32_16x16x32_bf16 v[4:7], v[172:175], v[212:215], v[4:7]
	v_mfma_f32_16x16x32_bf16 v[0:3], v[180:183], v[212:215], v[0:3]
	s_setprio 0
	s_barrier
	s_add_i32 s64, 0, 0x18000
	v_add_u32_e32 v163, s64, v157
	s_add_i32 s65, 0, 0x1c000
	ds_read_b128 v[144:147], v163
	ds_read_b128 v[148:151], v163 offset:1024
	ds_read_b128 v[152:155], v163 offset:2048
	ds_read_b128 v[164:167], v163 offset:3072
	v_add_u32_e32 v163, s65, v157
	ds_read_b128 v[168:171], v163
	ds_read_b128 v[172:175], v163 offset:1024
	ds_read_b128 v[176:179], v163 offset:2048
	ds_read_b128 v[180:183], v163 offset:3072
	s_add_u32 s34, s34, s6
	s_addc_u32 s35, s35, s7
	s_mov_b32 m0, s33
	v_lshl_add_u64 v[228:229], s[34:35], 0, v[128:129]
	ds_read_b128 v[184:187], v161 offset:32768
	ds_read_b128 v[188:191], v161 offset:33792
	ds_read_b128 v[192:195], v161 offset:34816
	ds_read_b128 v[196:199], v161 offset:35840
	ds_read_b128 v[200:203], v161 offset:36864
	ds_read_b128 v[204:207], v161 offset:37888
	ds_read_b128 v[208:211], v161 offset:38912
	ds_read_b128 v[212:215], v161 offset:39936
	global_load_lds_dwordx4 v[228:229], off
	v_lshl_add_u64 v[228:229], s[34:35], 0, v[132:133]
	s_mov_b32 m0, s36
	s_nop 0
	global_load_lds_dwordx4 v[228:229], off
	s_waitcnt vmcnt(8)
	s_waitcnt lgkmcnt(0)
	s_barrier
	s_setprio 1
	s_waitcnt lgkmcnt(0)
	v_mfma_f32_16x16x32_bf16 v[124:127], v[144:147], v[184:187], v[124:127]
	v_mfma_f32_16x16x32_bf16 v[120:123], v[152:155], v[184:187], v[120:123]
	v_mfma_f32_16x16x32_bf16 v[116:119], v[144:147], v[192:195], v[116:119]
	v_mfma_f32_16x16x32_bf16 v[112:115], v[152:155], v[192:195], v[112:115]
	v_mfma_f32_16x16x32_bf16 v[104:107], v[144:147], v[200:203], v[104:107]
	v_mfma_f32_16x16x32_bf16 v[96:99], v[152:155], v[200:203], v[96:99]
	v_mfma_f32_16x16x32_bf16 v[88:91], v[144:147], v[208:211], v[88:91]
	v_mfma_f32_16x16x32_bf16 v[80:83], v[152:155], v[208:211], v[80:83]
	v_mfma_f32_16x16x32_bf16 v[124:127], v[148:151], v[188:191], v[124:127]
	v_mfma_f32_16x16x32_bf16 v[120:123], v[164:167], v[188:191], v[120:123]
	v_mfma_f32_16x16x32_bf16 v[116:119], v[148:151], v[196:199], v[116:119]
	v_mfma_f32_16x16x32_bf16 v[112:115], v[164:167], v[196:199], v[112:115]
	v_mfma_f32_16x16x32_bf16 v[104:107], v[148:151], v[204:207], v[104:107]
	v_mfma_f32_16x16x32_bf16 v[96:99], v[164:167], v[204:207], v[96:99]
	v_mfma_f32_16x16x32_bf16 v[88:91], v[148:151], v[212:215], v[88:91]
	v_mfma_f32_16x16x32_bf16 v[80:83], v[164:167], v[212:215], v[80:83]
	s_setprio 0
	s_setprio 1
	v_mfma_f32_16x16x32_bf16 v[108:111], v[168:171], v[184:187], v[108:111]
	v_mfma_f32_16x16x32_bf16 v[100:103], v[176:179], v[184:187], v[100:103]
	v_mfma_f32_16x16x32_bf16 v[92:95], v[168:171], v[192:195], v[92:95]
	v_mfma_f32_16x16x32_bf16 v[84:87], v[176:179], v[192:195], v[84:87]
	v_mfma_f32_16x16x32_bf16 v[76:79], v[168:171], v[200:203], v[76:79]
	v_mfma_f32_16x16x32_bf16 v[72:75], v[176:179], v[200:203], v[72:75]
	v_mfma_f32_16x16x32_bf16 v[68:71], v[168:171], v[208:211], v[68:71]
	v_mfma_f32_16x16x32_bf16 v[64:67], v[176:179], v[208:211], v[64:67]
	v_mfma_f32_16x16x32_bf16 v[108:111], v[172:175], v[188:191], v[108:111]
	v_mfma_f32_16x16x32_bf16 v[100:103], v[180:183], v[188:191], v[100:103]
	v_mfma_f32_16x16x32_bf16 v[92:95], v[172:175], v[196:199], v[92:95]
	v_mfma_f32_16x16x32_bf16 v[84:87], v[180:183], v[196:199], v[84:87]
	v_mfma_f32_16x16x32_bf16 v[76:79], v[172:175], v[204:207], v[76:79]
	v_mfma_f32_16x16x32_bf16 v[72:75], v[180:183], v[204:207], v[72:75]
	v_mfma_f32_16x16x32_bf16 v[68:71], v[172:175], v[212:215], v[68:71]
	v_mfma_f32_16x16x32_bf16 v[64:67], v[180:183], v[212:215], v[64:67]
	s_setprio 0
	s_barrier
; #define PG8_STAGE(bufoff, gbase, voff) do { _Pragma("unroll") for (int _i = 0; _i < 2; ++_i) \
;         __builtin_amdgcn_global_load_lds((const unsigned*)((const char*)(gbase) + (voff)[_i]), (PG8_LAS unsigned*)(lds + (bufoff) + ldsw + _i * 8192), 16, 0, 0); } while (0)
; #define PG8_LDA(dst, b, h) do { _Pragma("unroll") for (int m = 0; m < 4; ++m) _Pragma("unroll") for (int k = 0; k < 2; ++k) dst[m][k] = *(const PG8_LAS bf16x8*)(lds + PG8_SA(b, h) + aoff + m * 2048 + k * 1024); } while (0)
; #define PG8_MMA(ai, bj, At, Bt) do { __builtin_amdgcn_s_setprio(1); _Pragma("unroll") for (int m = 0; m < 4; ++m) _Pragma("unroll") for (int n = 0; n < 2; ++n) _Pragma("unroll") for (int k = 0; k < 2; ++k) \
;         acc[ai][bj][m][n] = __builtin_amdgcn_mfma_f32_16x16x32_bf16(Bt[n][k], At[m][k], acc[ai][bj][m][n], 0, 0, 0); __builtin_amdgcn_s_setprio(0); } while (0)
; #define PG8_WAIT_V(n) asm volatile("s_waitcnt vmcnt(" #n ")" ::: "memory")
; #define PG8_WAIT_L(n) asm volatile("s_waitcnt lgkmcnt(" #n ")" ::: "memory")
; #define PG8_BAR __builtin_amdgcn_s_barrier()
; #define PG8_SCHED __builtin_amdgcn_sched_barrier(0)
;     __device__ __forceinline__ void operator()(const f32x4 (&acc)[2], int srow, int cgp, int kq) const { one(acc[0], srow, 2 * cgp, kq); one(acc[1], srow, 2 * cgp + 1, kq); }
; template <class Epi, class Sched, bool ALIGN_EPI = false, bool SP2 = false>
; __device__ __forceinline__ void gemm_phase(PG8_LAS unsigned char* lds, const Gemm g, const Sched& S, const Epi& E) {
;     ...
;             PG8_LDA(At, 1, 1); PG8_STAGE(PG8_SB(1, 0), b3, voffB); PG8_STAGE(PG8_SB(1, 1), b3 + hstep, voffB); PG8_STAGE(PG8_SA(1, 0), a3, voffA);
;             PG8_WAIT_V(8); PG8_WAIT_L(0); PG8_BAR; PG8_MMA(1, 0, At, B0); PG8_MMA(1, 1, At, B1); PG8_BAR; PG8_SCHED;
;     __device__ __forceinline__ void operator()(AccRef acc, const pg8::Unit& u, int wr, int wc, int fr, int fq) const {
;         const int row0 = u.pm * 256 + wr * 64 + fr, col0 = u.pn * 256 + wc * 32 + 8 * fq;
; #pragma unroll
;         for (int ai = 0; ai < 2; ++ai)
; #pragma unroll
;             for (int m = 0; m < 4; ++m) {
;                 const int row = row0 + ai * 128 + m * 16; float ss = 0.f;
; #pragma unroll
;                 for (int bj = 0; bj < 2; ++bj) {
;                     bf16_t* xp = xb + (size_t)row * D + col0 + bj * 128;
;                     f32x4 a, b; unpack8(*(const u32x4*)xp, a, b);
	s_add_i32 s34, s64, s16
	v_lshl_add_u64 v[216:217], v[216:217], 0, s[22:23]
	s_mov_b32 m0, s34
	ds_read_b128 v[184:187], v161 offset:49152
	ds_read_b128 v[188:191], v161 offset:50176
	ds_read_b128 v[192:195], v161 offset:51200
	ds_read_b128 v[196:199], v161 offset:52224
	ds_read_b128 v[200:203], v161 offset:53248
	ds_read_b128 v[204:207], v161 offset:54272
	ds_read_b128 v[208:211], v161 offset:55296
	ds_read_b128 v[212:215], v161 offset:56320
	global_load_lds_dwordx4 v[216:217], off
	v_lshl_add_u64 v[216:217], v[218:219], 0, s[22:23]
	s_add_i32 m0, s34, 0x2000
	s_add_i32 s34, s65, s16
	global_load_lds_dwordx4 v[216:217], off
	v_lshl_add_u64 v[216:217], v[220:221], 0, s[22:23]
	s_mov_b32 m0, s34
	s_nop 0
	global_load_lds_dwordx4 v[216:217], off
	v_lshl_add_u64 v[216:217], v[222:223], 0, s[22:23]
	s_add_i32 m0, s34, 0x2000
	s_nop 0
	global_load_lds_dwordx4 v[216:217], off
	v_lshl_add_u64 v[216:217], v[224:225], 0, s[22:23]
	s_mov_b32 m0, s37
	s_nop 0
	global_load_lds_dwordx4 v[216:217], off
	v_lshl_add_u64 v[216:217], v[226:227], 0, s[22:23]
	s_mov_b32 m0, s38
	s_nop 0
	global_load_lds_dwordx4 v[216:217], off
	s_waitcnt vmcnt(8)
	s_waitcnt lgkmcnt(0)
	s_barrier
	s_setprio 1
	s_waitcnt lgkmcnt(0)
	v_mfma_f32_16x16x32_bf16 v[60:63], v[144:147], v[184:187], v[60:63]
	v_mfma_f32_16x16x32_bf16 v[56:59], v[152:155], v[184:187], v[56:59]
	v_mfma_f32_16x16x32_bf16 v[52:55], v[144:147], v[192:195], v[52:55]
	v_mfma_f32_16x16x32_bf16 v[48:51], v[152:155], v[192:195], v[48:51]
	v_mfma_f32_16x16x32_bf16 v[40:43], v[144:147], v[200:203], v[40:43]
	v_mfma_f32_16x16x32_bf16 v[32:35], v[152:155], v[200:203], v[32:35]
	v_mfma_f32_16x16x32_bf16 v[24:27], v[144:147], v[208:211], v[24:27]
	v_mfma_f32_16x16x32_bf16 v[16:19], v[152:155], v[208:211], v[16:19]
	v_mfma_f32_16x16x32_bf16 v[60:63], v[148:151], v[188:191], v[60:63]
	v_mfma_f32_16x16x32_bf16 v[56:59], v[164:167], v[188:191], v[56:59]
	v_mfma_f32_16x16x32_bf16 v[52:55], v[148:151], v[196:199], v[52:55]
	v_mfma_f32_16x16x32_bf16 v[48:51], v[164:167], v[196:199], v[48:51]
	v_mfma_f32_16x16x32_bf16 v[40:43], v[148:151], v[204:207], v[40:43]
	v_mfma_f32_16x16x32_bf16 v[32:35], v[164:167], v[204:207], v[32:35]
	v_mfma_f32_16x16x32_bf16 v[24:27], v[148:151], v[212:215], v[24:27]
	v_mfma_f32_16x16x32_bf16 v[16:19], v[164:167], v[212:215], v[16:19]
	s_setprio 0
	s_setprio 1
	v_mfma_f32_16x16x32_bf16 v[44:47], v[168:171], v[184:187], v[44:47]
	v_mfma_f32_16x16x32_bf16 v[36:39], v[176:179], v[184:187], v[36:39]
	v_mfma_f32_16x16x32_bf16 v[28:31], v[168:171], v[192:195], v[28:31]
	v_mfma_f32_16x16x32_bf16 v[20:23], v[176:179], v[192:195], v[20:23]
	v_mfma_f32_16x16x32_bf16 v[12:15], v[168:171], v[200:203], v[12:15]
	v_mfma_f32_16x16x32_bf16 v[8:11], v[176:179], v[200:203], v[8:11]
	v_mfma_f32_16x16x32_bf16 v[4:7], v[168:171], v[208:211], v[4:7]
	v_mfma_f32_16x16x32_bf16 v[0:3], v[176:179], v[208:211], v[0:3]
	v_mfma_f32_16x16x32_bf16 v[44:47], v[172:175], v[188:191], v[44:47]
	v_mfma_f32_16x16x32_bf16 v[36:39], v[180:183], v[188:191], v[36:39]
	v_mfma_f32_16x16x32_bf16 v[28:31], v[172:175], v[196:199], v[28:31]
	v_mfma_f32_16x16x32_bf16 v[20:23], v[180:183], v[196:199], v[20:23]
	v_mfma_f32_16x16x32_bf16 v[12:15], v[172:175], v[204:207], v[12:15]
	v_mfma_f32_16x16x32_bf16 v[8:11], v[180:183], v[204:207], v[8:11]
	v_mfma_f32_16x16x32_bf16 v[4:7], v[172:175], v[212:215], v[4:7]
	v_mfma_f32_16x16x32_bf16 v[0:3], v[180:183], v[212:215], v[0:3]
	s_setprio 0
	s_barrier
	s_add_u32 s30, s30, 0x100
	s_addc_u32 s31, s31, 0
	s_add_u32 s61, s61, 0x100
	s_addc_u32 s62, s62, 0
	s_cmp_ge_i32 s63, s40
	s_mov_b32 s34, s63
	s_cbranch_scc0 .LBB0_2575
.LBB0_2577:
	s_and_b64 vcc, exec, s[26:27]
	s_cbranch_vccz .LBB0_2579
	s_barrier
.LBB0_2579:
.Lres_beg5:
	v_lshl_add_u32 v170, s60, 8, v156
	v_lshl_or_b32 v169, s14, 8, v158
	v_lshlrev_b32_e32 v169, 1, v169
	v_lshl_add_u32 v168, v170, 11, v169
	v_add_u32_e32 v169, 0x18000, v168
	global_load_dwordx4 v[180:183], v169, s[42:43]
	global_load_dwordx4 v[184:187], v169, s[42:43] offset:256
	v_add_u32_e32 v169, 0x40000, v168
	global_load_dwordx4 v[188:191], v169, s[42:43]
	global_load_dwordx4 v[192:195], v169, s[42:43] offset:256
	v_add_u32_e32 v169, 0x48000, v168
	global_load_dwordx4 v[196:199], v169, s[42:43]
	global_load_dwordx4 v[200:203], v169, s[42:43] offset:256
	v_add_u32_e32 v169, 0x50000, v168
	global_load_dwordx4 v[204:207], v169, s[42:43]
	global_load_dwordx4 v[208:211], v169, s[42:43] offset:256
	v_bfe_u32 v171, v158, 5, 2
	v_lshl_add_u32 v171, s14, 2, v171
	v_lshlrev_b32_e32 v171, 2, v171
	v_lshl_add_u32 v170, v170, 6, v171
	v_add_u32_e32 v173, 0x2000, v170
	v_mbcnt_lo_u32_b32 v172, -1, 0
	v_mbcnt_hi_u32_b32 v172, -1, v172
	v_xor_b32_e32 v171, 16, v172
	v_xor_b32_e32 v172, 32, v172
	v_lshlrev_b32_e32 v171, 2, v171
	v_lshlrev_b32_e32 v172, 2, v172
	v_mov_b32_e32 v169, v168
	s_waitcnt vmcnt(8)
;     __device__ __forceinline__ void operator()(const f32x4 (&acc)[2], int srow, int cgp, int kq) const { one(acc[0], srow, 2 * cgp, kq); one(acc[1], srow, 2 * cgp + 1, kq); }
;     __device__ __forceinline__ void operator()(AccRef acc, const pg8::Unit& u, int wr, int wc, int fr, int fq) const {
;         const int row0 = u.pm * 256 + wr * 64 + fr, col0 = u.pn * 256 + wc * 32 + 8 * fq;
; #pragma unroll
;         for (int ai = 0; ai < 2; ++ai)
; #pragma unroll
;             for (int m = 0; m < 4; ++m) {
;                 const int row = row0 + ai * 128 + m * 16; float ss = 0.f;
; #pragma unroll
;                 for (int bj = 0; bj < 2; ++bj) {
;                     bf16_t* xp = xb + (size_t)row * D + col0 + bj * 128;
;                     f32x4 a, b; unpack8(*(const u32x4*)xp, a, b);
;                     a += acc[ai][bj][m][0] * alpha; b += acc[ai][bj][m][1] * alpha;
;                     *(u32x4*)xp = pack8(a, b);
;                     ss += (a[0] * a[0] + a[1] * a[1]) + (a[2] * a[2] + a[3] * a[3]) + (b[0] * b[0] + b[1] * b[1]) + (b[2] * b[2] + b[3] * b[3]);
;                 }
	v_pk_mul_f32 v[124:125], v[124:125], 0.5 op_sel_hi:[1,0]
	v_pk_mul_f32 v[126:127], v[126:127], 0.5 op_sel_hi:[1,0]
	v_pk_mul_f32 v[120:121], v[120:121], 0.5 op_sel_hi:[1,0]
	v_pk_mul_f32 v[122:123], v[122:123], 0.5 op_sel_hi:[1,0]
	v_lshlrev_b32_e32 v212, 16, v231
	v_and_b32_e32 v213, 0xffff0000, v231
	v_and_b32_e32 v231, 0xffff0000, v230
	v_lshlrev_b32_e32 v230, 16, v230
	v_lshlrev_b32_e32 v214, 16, v233
	v_and_b32_e32 v215, 0xffff0000, v233
	v_and_b32_e32 v233, 0xffff0000, v232
	v_lshlrev_b32_e32 v232, 16, v232
	v_pk_add_f32 v[230:231], v[124:125], v[230:231]
	v_pk_add_f32 v[212:213], v[126:127], v[212:213]
	v_pk_add_f32 v[232:233], v[120:121], v[232:233]
	v_pk_add_f32 v[214:215], v[122:123], v[214:215]
	v_cvt_pk_bf16_f32 v124, v230, v231
	v_cvt_pk_bf16_f32 v125, v212, v213
	v_cvt_pk_bf16_f32 v126, v232, v233
	v_cvt_pk_bf16_f32 v127, v214, v215
	global_store_dwordx4 v169, v[124:127], s[42:43]
	v_mul_f32_e32 v120, v231, v231
	v_mul_f32_e32 v121, v213, v213
	v_mul_f32_e32 v122, v233, v233
	v_mul_f32_e32 v123, v215, v215
	v_fmac_f32_e32 v120, v230, v230
	v_fmac_f32_e32 v121, v212, v212
	v_fmac_f32_e32 v122, v232, v232
	v_fmac_f32_e32 v123, v214, v214
	v_add_f32_e32 v120, v120, v121
	v_add_f32_e32 v120, v122, v120
	v_add_f32_e32 v120, v123, v120
	s_nop 0
	v_pk_mul_f32 v[108:109], v[108:109], 0.5 op_sel_hi:[1,0]
	v_pk_mul_f32 v[110:111], v[110:111], 0.5 op_sel_hi:[1,0]
	v_pk_mul_f32 v[100:101], v[100:101], 0.5 op_sel_hi:[1,0]
	v_pk_mul_f32 v[102:103], v[102:103], 0.5 op_sel_hi:[1,0]
	v_lshlrev_b32_e32 v212, 16, v235
	v_and_b32_e32 v213, 0xffff0000, v235
	v_and_b32_e32 v235, 0xffff0000, v234
	v_lshlrev_b32_e32 v234, 16, v234
	v_lshlrev_b32_e32 v214, 16, v237
	v_and_b32_e32 v215, 0xffff0000, v237
	v_and_b32_e32 v237, 0xffff0000, v236
	v_lshlrev_b32_e32 v236, 16, v236
	v_pk_add_f32 v[234:235], v[108:109], v[234:235]
	v_pk_add_f32 v[212:213], v[110:111], v[212:213]
	v_pk_add_f32 v[236:237], v[100:101], v[236:237]
	v_pk_add_f32 v[214:215], v[102:103], v[214:215]
	v_cvt_pk_bf16_f32 v108, v234, v235
	v_cvt_pk_bf16_f32 v109, v212, v213
	v_cvt_pk_bf16_f32 v110, v236, v237
	v_cvt_pk_bf16_f32 v111, v214, v215
	global_store_dwordx4 v169, v[108:111], s[42:43] offset:256
	v_mul_f32_e32 v100, v235, v235
	v_mul_f32_e32 v101, v213, v213
	v_mul_f32_e32 v102, v237, v237
	v_mul_f32_e32 v103, v215, v215
	v_fmac_f32_e32 v100, v234, v234
	v_fmac_f32_e32 v101, v212, v212
	v_fmac_f32_e32 v102, v236, v236
	v_fmac_f32_e32 v103, v214, v214
	v_add_f32_e32 v100, v100, v101
	v_add_f32_e32 v100, v102, v100
	v_add_f32_e32 v100, v103, v100
	v_add_f32_e32 v120, v120, v100
	v_add_u32_e32 v169, 0x58000, v168
	global_load_dwordx4 v[230:233], v169, s[42:43]
	global_load_dwordx4 v[234:237], v169, s[42:43] offset:256
	v_add_u32_e32 v169, 0x8000, v168
	s_nop 0
	v_pk_mul_f32 v[116:117], v[116:117], 0.5 op_sel_hi:[1,0]
	v_pk_mul_f32 v[118:119], v[118:119], 0.5 op_sel_hi:[1,0]
	v_pk_mul_f32 v[112:113], v[112:113], 0.5 op_sel_hi:[1,0]
	v_pk_mul_f32 v[114:115], v[114:115], 0.5 op_sel_hi:[1,0]
	v_lshlrev_b32_e32 v212, 16, v239
	v_and_b32_e32 v213, 0xffff0000, v239
	v_and_b32_e32 v239, 0xffff0000, v238
	v_lshlrev_b32_e32 v238, 16, v238
	v_lshlrev_b32_e32 v214, 16, v241
	v_and_b32_e32 v215, 0xffff0000, v241
	v_and_b32_e32 v241, 0xffff0000, v240
	v_lshlrev_b32_e32 v240, 16, v240
	v_pk_add_f32 v[238:239], v[116:117], v[238:239]
	v_pk_add_f32 v[212:213], v[118:119], v[212:213]
	v_pk_add_f32 v[240:241], v[112:113], v[240:241]
	v_pk_add_f32 v[214:215], v[114:115], v[214:215]
	v_cvt_pk_bf16_f32 v116, v238, v239
	v_cvt_pk_bf16_f32 v117, v212, v213
	v_cvt_pk_bf16_f32 v118, v240, v241
	v_cvt_pk_bf16_f32 v119, v214, v215
	global_store_dwordx4 v169, v[116:119], s[42:43]
	v_mul_f32_e32 v112, v239, v239
	v_mul_f32_e32 v113, v213, v213
	v_mul_f32_e32 v114, v241, v241
	v_mul_f32_e32 v115, v215, v215
	v_fmac_f32_e32 v112, v238, v238
	v_fmac_f32_e32 v113, v212, v212
	v_fmac_f32_e32 v114, v240, v240
	v_fmac_f32_e32 v115, v214, v214
	v_add_f32_e32 v112, v112, v113
	v_add_f32_e32 v112, v114, v112
	v_add_f32_e32 v112, v115, v112
	s_nop 0
	v_pk_mul_f32 v[92:93], v[92:93], 0.5 op_sel_hi:[1,0]
	v_pk_mul_f32 v[94:95], v[94:95], 0.5 op_sel_hi:[1,0]
	v_pk_mul_f32 v[84:85], v[84:85], 0.5 op_sel_hi:[1,0]
	v_pk_mul_f32 v[86:87], v[86:87], 0.5 op_sel_hi:[1,0]
	v_lshlrev_b32_e32 v212, 16, v243
	v_and_b32_e32 v213, 0xffff0000, v243
	v_and_b32_e32 v243, 0xffff0000, v242
	v_lshlrev_b32_e32 v242, 16, v242
	v_lshlrev_b32_e32 v214, 16, v245
	v_and_b32_e32 v215, 0xffff0000, v245
	v_and_b32_e32 v245, 0xffff0000, v244
	v_lshlrev_b32_e32 v244, 16, v244
	v_pk_add_f32 v[242:243], v[92:93], v[242:243]
	v_pk_add_f32 v[212:213], v[94:95], v[212:213]
	v_pk_add_f32 v[244:245], v[84:85], v[244:245]
	v_pk_add_f32 v[214:215], v[86:87], v[214:215]
	v_cvt_pk_bf16_f32 v92, v242, v243
	v_cvt_pk_bf16_f32 v93, v212, v213
	v_cvt_pk_bf16_f32 v94, v244, v245
	v_cvt_pk_bf16_f32 v95, v214, v215
	global_store_dwordx4 v169, v[92:95], s[42:43] offset:256
	v_mul_f32_e32 v84, v243, v243
	v_mul_f32_e32 v85, v213, v213
	v_mul_f32_e32 v86, v245, v245
	v_mul_f32_e32 v87, v215, v215
	v_fmac_f32_e32 v84, v242, v242
	v_fmac_f32_e32 v85, v212, v212
	v_fmac_f32_e32 v86, v244, v244
	v_fmac_f32_e32 v87, v214, v214
	v_add_f32_e32 v84, v84, v85
	v_add_f32_e32 v84, v86, v84
	v_add_f32_e32 v84, v87, v84
	v_add_f32_e32 v112, v112, v84
	v_add_u32_e32 v169, 0x10000, v168
	s_nop 0
	v_pk_mul_f32 v[104:105], v[104:105], 0.5 op_sel_hi:[1,0]
	v_pk_mul_f32 v[106:107], v[106:107], 0.5 op_sel_hi:[1,0]
	v_pk_mul_f32 v[96:97], v[96:97], 0.5 op_sel_hi:[1,0]
	v_pk_mul_f32 v[98:99], v[98:99], 0.5 op_sel_hi:[1,0]
	v_lshlrev_b32_e32 v212, 16, v247
	v_and_b32_e32 v213, 0xffff0000, v247
;     __device__ __forceinline__ void operator()(const f32x4 (&acc)[2], int srow, int cgp, int kq) const { one(acc[0], srow, 2 * cgp, kq); one(acc[1], srow, 2 * cgp + 1, kq); }
;     __device__ __forceinline__ void operator()(AccRef acc, const pg8::Unit& u, int wr, int wc, int fr, int fq) const {
;         const int row0 = u.pm * 256 + wr * 64 + fr, col0 = u.pn * 256 + wc * 32 + 8 * fq;
; #pragma unroll
;         for (int ai = 0; ai < 2; ++ai)
; #pragma unroll
;             for (int m = 0; m < 4; ++m) {
;                 const int row = row0 + ai * 128 + m * 16; float ss = 0.f;
; #pragma unroll
;                 for (int bj = 0; bj < 2; ++bj) {
;                     bf16_t* xp = xb + (size_t)row * D + col0 + bj * 128;
;                     f32x4 a, b; unpack8(*(const u32x4*)xp, a, b);
;                     a += acc[ai][bj][m][0] * alpha; b += acc[ai][bj][m][1] * alpha;
;                     *(u32x4*)xp = pack8(a, b);
;                     ss += (a[0] * a[0] + a[1] * a[1]) + (a[2] * a[2] + a[3] * a[3]) + (b[0] * b[0] + b[1] * b[1]) + (b[2] * b[2] + b[3] * b[3]);
;                 }
	v_and_b32_e32 v247, 0xffff0000, v246
	v_lshlrev_b32_e32 v246, 16, v246
	v_lshlrev_b32_e32 v214, 16, v249
	v_and_b32_e32 v215, 0xffff0000, v249
	v_and_b32_e32 v249, 0xffff0000, v248
	v_lshlrev_b32_e32 v248, 16, v248
	v_pk_add_f32 v[246:247], v[104:105], v[246:247]
	v_pk_add_f32 v[212:213], v[106:107], v[212:213]
	v_pk_add_f32 v[248:249], v[96:97], v[248:249]
	v_pk_add_f32 v[214:215], v[98:99], v[214:215]
	v_cvt_pk_bf16_f32 v104, v246, v247
	v_cvt_pk_bf16_f32 v105, v212, v213
	v_cvt_pk_bf16_f32 v106, v248, v249
	v_cvt_pk_bf16_f32 v107, v214, v215
	global_store_dwordx4 v169, v[104:107], s[42:43]
	v_mul_f32_e32 v96, v247, v247
	v_mul_f32_e32 v97, v213, v213
	v_mul_f32_e32 v98, v249, v249
	v_mul_f32_e32 v99, v215, v215
	v_fmac_f32_e32 v96, v246, v246
	v_fmac_f32_e32 v97, v212, v212
	v_fmac_f32_e32 v98, v248, v248
	v_fmac_f32_e32 v99, v214, v214
	v_add_f32_e32 v96, v96, v97
	v_add_f32_e32 v96, v98, v96
	v_add_f32_e32 v96, v99, v96
	s_nop 0
	v_pk_mul_f32 v[76:77], v[76:77], 0.5 op_sel_hi:[1,0]
	v_pk_mul_f32 v[78:79], v[78:79], 0.5 op_sel_hi:[1,0]
	v_pk_mul_f32 v[72:73], v[72:73], 0.5 op_sel_hi:[1,0]
	v_pk_mul_f32 v[74:75], v[74:75], 0.5 op_sel_hi:[1,0]
	v_lshlrev_b32_e32 v212, 16, v251
	v_and_b32_e32 v213, 0xffff0000, v251
	v_and_b32_e32 v251, 0xffff0000, v250
	v_lshlrev_b32_e32 v250, 16, v250
	v_lshlrev_b32_e32 v214, 16, v253
	v_and_b32_e32 v215, 0xffff0000, v253
	v_and_b32_e32 v253, 0xffff0000, v252
	v_lshlrev_b32_e32 v252, 16, v252
	v_pk_add_f32 v[250:251], v[76:77], v[250:251]
	v_pk_add_f32 v[212:213], v[78:79], v[212:213]
	v_pk_add_f32 v[252:253], v[72:73], v[252:253]
	v_pk_add_f32 v[214:215], v[74:75], v[214:215]
	v_cvt_pk_bf16_f32 v76, v250, v251
	v_cvt_pk_bf16_f32 v77, v212, v213
	v_cvt_pk_bf16_f32 v78, v252, v253
	v_cvt_pk_bf16_f32 v79, v214, v215
	global_store_dwordx4 v169, v[76:79], s[42:43] offset:256
	v_mul_f32_e32 v72, v251, v251
	v_mul_f32_e32 v73, v213, v213
	v_mul_f32_e32 v74, v253, v253
	v_mul_f32_e32 v75, v215, v215
	v_fmac_f32_e32 v72, v250, v250
	v_fmac_f32_e32 v73, v212, v212
	v_fmac_f32_e32 v74, v252, v252
	v_fmac_f32_e32 v75, v214, v214
	v_add_f32_e32 v72, v72, v73
	v_add_f32_e32 v72, v74, v72
	v_add_f32_e32 v72, v75, v72
	v_add_f32_e32 v96, v96, v72
	v_add_u32_e32 v169, 0x18000, v168
	s_waitcnt vmcnt(15)
	v_pk_mul_f32 v[88:89], v[88:89], 0.5 op_sel_hi:[1,0]
	v_pk_mul_f32 v[90:91], v[90:91], 0.5 op_sel_hi:[1,0]
	v_pk_mul_f32 v[80:81], v[80:81], 0.5 op_sel_hi:[1,0]
	v_pk_mul_f32 v[82:83], v[82:83], 0.5 op_sel_hi:[1,0]
	v_lshlrev_b32_e32 v212, 16, v181
	v_and_b32_e32 v213, 0xffff0000, v181
	v_and_b32_e32 v181, 0xffff0000, v180
	v_lshlrev_b32_e32 v180, 16, v180
	v_lshlrev_b32_e32 v214, 16, v183
	v_and_b32_e32 v215, 0xffff0000, v183
	v_and_b32_e32 v183, 0xffff0000, v182
	v_lshlrev_b32_e32 v182, 16, v182
	v_pk_add_f32 v[180:181], v[88:89], v[180:181]
	v_pk_add_f32 v[212:213], v[90:91], v[212:213]
	v_pk_add_f32 v[182:183], v[80:81], v[182:183]
	v_pk_add_f32 v[214:215], v[82:83], v[214:215]
	v_cvt_pk_bf16_f32 v88, v180, v181
	v_cvt_pk_bf16_f32 v89, v212, v213
	v_cvt_pk_bf16_f32 v90, v182, v183
	v_cvt_pk_bf16_f32 v91, v214, v215
	global_store_dwordx4 v169, v[88:91], s[42:43]
	v_mul_f32_e32 v80, v181, v181
	v_mul_f32_e32 v81, v213, v213
	v_mul_f32_e32 v82, v183, v183
	v_mul_f32_e32 v83, v215, v215
	v_fmac_f32_e32 v80, v180, v180
	v_fmac_f32_e32 v81, v212, v212
	v_fmac_f32_e32 v82, v182, v182
	v_fmac_f32_e32 v83, v214, v214
	v_add_f32_e32 v80, v80, v81
	v_add_f32_e32 v80, v82, v80
	v_add_f32_e32 v80, v83, v80
	s_waitcnt vmcnt(15)
	v_pk_mul_f32 v[68:69], v[68:69], 0.5 op_sel_hi:[1,0]
	v_pk_mul_f32 v[70:71], v[70:71], 0.5 op_sel_hi:[1,0]
	v_pk_mul_f32 v[64:65], v[64:65], 0.5 op_sel_hi:[1,0]
	v_pk_mul_f32 v[66:67], v[66:67], 0.5 op_sel_hi:[1,0]
	v_lshlrev_b32_e32 v212, 16, v185
	v_and_b32_e32 v213, 0xffff0000, v185
	v_and_b32_e32 v185, 0xffff0000, v184
	v_lshlrev_b32_e32 v184, 16, v184
	v_lshlrev_b32_e32 v214, 16, v187
	v_and_b32_e32 v215, 0xffff0000, v187
	v_and_b32_e32 v187, 0xffff0000, v186
	v_lshlrev_b32_e32 v186, 16, v186
	v_pk_add_f32 v[184:185], v[68:69], v[184:185]
	v_pk_add_f32 v[212:213], v[70:71], v[212:213]
	v_pk_add_f32 v[186:187], v[64:65], v[186:187]
	v_pk_add_f32 v[214:215], v[66:67], v[214:215]
	v_cvt_pk_bf16_f32 v68, v184, v185
	v_cvt_pk_bf16_f32 v69, v212, v213
	v_cvt_pk_bf16_f32 v70, v186, v187
	v_cvt_pk_bf16_f32 v71, v214, v215
	global_store_dwordx4 v169, v[68:71], s[42:43] offset:256
	v_mul_f32_e32 v64, v185, v185
	v_mul_f32_e32 v65, v213, v213
	v_mul_f32_e32 v66, v187, v187
	v_mul_f32_e32 v67, v215, v215
	v_fmac_f32_e32 v64, v184, v184
	v_fmac_f32_e32 v65, v212, v212
	v_fmac_f32_e32 v66, v186, v186
	v_fmac_f32_e32 v67, v214, v214
	v_add_f32_e32 v64, v64, v65
	v_add_f32_e32 v64, v66, v64
	v_add_f32_e32 v64, v67, v64
	v_add_f32_e32 v80, v80, v64
	v_add_u32_e32 v169, 0x40000, v168
	s_waitcnt vmcnt(15)
	v_pk_mul_f32 v[60:61], v[60:61], 0.5 op_sel_hi:[1,0]
	v_pk_mul_f32 v[62:63], v[62:63], 0.5 op_sel_hi:[1,0]
	v_pk_mul_f32 v[56:57], v[56:57], 0.5 op_sel_hi:[1,0]
	v_pk_mul_f32 v[58:59], v[58:59], 0.5 op_sel_hi:[1,0]
	v_lshlrev_b32_e32 v212, 16, v189
	v_and_b32_e32 v213, 0xffff0000, v189
	v_and_b32_e32 v189, 0xffff0000, v188
	v_lshlrev_b32_e32 v188, 16, v188
	v_lshlrev_b32_e32 v214, 16, v191
	v_and_b32_e32 v215, 0xffff0000, v191
	v_and_b32_e32 v191, 0xffff0000, v190
	v_lshlrev_b32_e32 v190, 16, v190
	v_pk_add_f32 v[188:189], v[60:61], v[188:189]
	v_pk_add_f32 v[212:213], v[62:63], v[212:213]
	v_pk_add_f32 v[190:191], v[56:57], v[190:191]
	v_pk_add_f32 v[214:215], v[58:59], v[214:215]
	v_cvt_pk_bf16_f32 v60, v188, v189
	v_cvt_pk_bf16_f32 v61, v212, v213
	v_cvt_pk_bf16_f32 v62, v190, v191
	v_cvt_pk_bf16_f32 v63, v214, v215
	global_store_dwordx4 v169, v[60:63], s[42:43]
	v_mul_f32_e32 v56, v189, v189
	v_mul_f32_e32 v57, v213, v213
	v_mul_f32_e32 v58, v191, v191
	v_mul_f32_e32 v59, v215, v215
	v_fmac_f32_e32 v56, v188, v188
	v_fmac_f32_e32 v57, v212, v212
	v_fmac_f32_e32 v58, v190, v190
	v_fmac_f32_e32 v59, v214, v214
	v_add_f32_e32 v56, v56, v57
	v_add_f32_e32 v56, v58, v56
	v_add_f32_e32 v56, v59, v56
	s_waitcnt vmcnt(15)
;     __device__ __forceinline__ void operator()(const f32x4 (&acc)[2], int srow, int cgp, int kq) const { one(acc[0], srow, 2 * cgp, kq); one(acc[1], srow, 2 * cgp + 1, kq); }
;     __device__ __forceinline__ void operator()(AccRef acc, const pg8::Unit& u, int wr, int wc, int fr, int fq) const {
;         const int row0 = u.pm * 256 + wr * 64 + fr, col0 = u.pn * 256 + wc * 32 + 8 * fq;
; #pragma unroll
;         for (int ai = 0; ai < 2; ++ai)
; #pragma unroll
;             for (int m = 0; m < 4; ++m) {
;                 const int row = row0 + ai * 128 + m * 16; float ss = 0.f;
; #pragma unroll
;                 for (int bj = 0; bj < 2; ++bj) {
;                     bf16_t* xp = xb + (size_t)row * D + col0 + bj * 128;
;                     f32x4 a, b; unpack8(*(const u32x4*)xp, a, b);
;                     a += acc[ai][bj][m][0] * alpha; b += acc[ai][bj][m][1] * alpha;
;                     *(u32x4*)xp = pack8(a, b);
;                     ss += (a[0] * a[0] + a[1] * a[1]) + (a[2] * a[2] + a[3] * a[3]) + (b[0] * b[0] + b[1] * b[1]) + (b[2] * b[2] + b[3] * b[3]);
;                 }
	v_pk_mul_f32 v[44:45], v[44:45], 0.5 op_sel_hi:[1,0]
	v_pk_mul_f32 v[46:47], v[46:47], 0.5 op_sel_hi:[1,0]
	v_pk_mul_f32 v[36:37], v[36:37], 0.5 op_sel_hi:[1,0]
	v_pk_mul_f32 v[38:39], v[38:39], 0.5 op_sel_hi:[1,0]
	v_lshlrev_b32_e32 v212, 16, v193
	v_and_b32_e32 v213, 0xffff0000, v193
	v_and_b32_e32 v193, 0xffff0000, v192
	v_lshlrev_b32_e32 v192, 16, v192
	v_lshlrev_b32_e32 v214, 16, v195
	v_and_b32_e32 v215, 0xffff0000, v195
	v_and_b32_e32 v195, 0xffff0000, v194
	v_lshlrev_b32_e32 v194, 16, v194
	v_pk_add_f32 v[192:193], v[44:45], v[192:193]
	v_pk_add_f32 v[212:213], v[46:47], v[212:213]
	v_pk_add_f32 v[194:195], v[36:37], v[194:195]
	v_pk_add_f32 v[214:215], v[38:39], v[214:215]
	v_cvt_pk_bf16_f32 v44, v192, v193
	v_cvt_pk_bf16_f32 v45, v212, v213
	v_cvt_pk_bf16_f32 v46, v194, v195
	v_cvt_pk_bf16_f32 v47, v214, v215
	global_store_dwordx4 v169, v[44:47], s[42:43] offset:256
	v_mul_f32_e32 v36, v193, v193
	v_mul_f32_e32 v37, v213, v213
	v_mul_f32_e32 v38, v195, v195
	v_mul_f32_e32 v39, v215, v215
	v_fmac_f32_e32 v36, v192, v192
	v_fmac_f32_e32 v37, v212, v212
	v_fmac_f32_e32 v38, v194, v194
	v_fmac_f32_e32 v39, v214, v214
	v_add_f32_e32 v36, v36, v37
	v_add_f32_e32 v36, v38, v36
	v_add_f32_e32 v36, v39, v36
	v_add_f32_e32 v56, v56, v36
	v_add_u32_e32 v169, 0x48000, v168
	s_waitcnt vmcnt(15)
	v_pk_mul_f32 v[52:53], v[52:53], 0.5 op_sel_hi:[1,0]
	v_pk_mul_f32 v[54:55], v[54:55], 0.5 op_sel_hi:[1,0]
	v_pk_mul_f32 v[48:49], v[48:49], 0.5 op_sel_hi:[1,0]
	v_pk_mul_f32 v[50:51], v[50:51], 0.5 op_sel_hi:[1,0]
	v_lshlrev_b32_e32 v212, 16, v197
	v_and_b32_e32 v213, 0xffff0000, v197
	v_and_b32_e32 v197, 0xffff0000, v196
	v_lshlrev_b32_e32 v196, 16, v196
	v_lshlrev_b32_e32 v214, 16, v199
	v_and_b32_e32 v215, 0xffff0000, v199
	v_and_b32_e32 v199, 0xffff0000, v198
	v_lshlrev_b32_e32 v198, 16, v198
	v_pk_add_f32 v[196:197], v[52:53], v[196:197]
	v_pk_add_f32 v[212:213], v[54:55], v[212:213]
	v_pk_add_f32 v[198:199], v[48:49], v[198:199]
	v_pk_add_f32 v[214:215], v[50:51], v[214:215]
	v_cvt_pk_bf16_f32 v52, v196, v197
	v_cvt_pk_bf16_f32 v53, v212, v213
	v_cvt_pk_bf16_f32 v54, v198, v199
	v_cvt_pk_bf16_f32 v55, v214, v215
	global_store_dwordx4 v169, v[52:55], s[42:43]
	v_mul_f32_e32 v48, v197, v197
	v_mul_f32_e32 v49, v213, v213
	v_mul_f32_e32 v50, v199, v199
	v_mul_f32_e32 v51, v215, v215
	v_fmac_f32_e32 v48, v196, v196
	v_fmac_f32_e32 v49, v212, v212
	v_fmac_f32_e32 v50, v198, v198
	v_fmac_f32_e32 v51, v214, v214
	v_add_f32_e32 v48, v48, v49
	v_add_f32_e32 v48, v50, v48
	v_add_f32_e32 v48, v51, v48
	s_waitcnt vmcnt(15)
	v_pk_mul_f32 v[28:29], v[28:29], 0.5 op_sel_hi:[1,0]
	v_pk_mul_f32 v[30:31], v[30:31], 0.5 op_sel_hi:[1,0]
	v_pk_mul_f32 v[20:21], v[20:21], 0.5 op_sel_hi:[1,0]
	v_pk_mul_f32 v[22:23], v[22:23], 0.5 op_sel_hi:[1,0]
	v_lshlrev_b32_e32 v212, 16, v201
	v_and_b32_e32 v213, 0xffff0000, v201
	v_and_b32_e32 v201, 0xffff0000, v200
	v_lshlrev_b32_e32 v200, 16, v200
	v_lshlrev_b32_e32 v214, 16, v203
	v_and_b32_e32 v215, 0xffff0000, v203
	v_and_b32_e32 v203, 0xffff0000, v202
	v_lshlrev_b32_e32 v202, 16, v202
	v_pk_add_f32 v[200:201], v[28:29], v[200:201]
	v_pk_add_f32 v[212:213], v[30:31], v[212:213]
	v_pk_add_f32 v[202:203], v[20:21], v[202:203]
	v_pk_add_f32 v[214:215], v[22:23], v[214:215]
	v_cvt_pk_bf16_f32 v28, v200, v201
	v_cvt_pk_bf16_f32 v29, v212, v213
	v_cvt_pk_bf16_f32 v30, v202, v203
	v_cvt_pk_bf16_f32 v31, v214, v215
	global_store_dwordx4 v169, v[28:31], s[42:43] offset:256
	v_mul_f32_e32 v20, v201, v201
	v_mul_f32_e32 v21, v213, v213
	v_mul_f32_e32 v22, v203, v203
	v_mul_f32_e32 v23, v215, v215
	v_fmac_f32_e32 v20, v200, v200
	v_fmac_f32_e32 v21, v212, v212
	v_fmac_f32_e32 v22, v202, v202
	v_fmac_f32_e32 v23, v214, v214
	v_add_f32_e32 v20, v20, v21
	v_add_f32_e32 v20, v22, v20
	v_add_f32_e32 v20, v23, v20
	v_add_f32_e32 v48, v48, v20
	v_add_u32_e32 v169, 0x50000, v168
	s_waitcnt vmcnt(15)
	v_pk_mul_f32 v[40:41], v[40:41], 0.5 op_sel_hi:[1,0]
	v_pk_mul_f32 v[42:43], v[42:43], 0.5 op_sel_hi:[1,0]
	v_pk_mul_f32 v[32:33], v[32:33], 0.5 op_sel_hi:[1,0]
	v_pk_mul_f32 v[34:35], v[34:35], 0.5 op_sel_hi:[1,0]
	v_lshlrev_b32_e32 v212, 16, v205
	v_and_b32_e32 v213, 0xffff0000, v205
	v_and_b32_e32 v205, 0xffff0000, v204
	v_lshlrev_b32_e32 v204, 16, v204
	v_lshlrev_b32_e32 v214, 16, v207
	v_and_b32_e32 v215, 0xffff0000, v207
	v_and_b32_e32 v207, 0xffff0000, v206
	v_lshlrev_b32_e32 v206, 16, v206
	v_pk_add_f32 v[204:205], v[40:41], v[204:205]
	v_pk_add_f32 v[212:213], v[42:43], v[212:213]
	v_pk_add_f32 v[206:207], v[32:33], v[206:207]
	v_pk_add_f32 v[214:215], v[34:35], v[214:215]
	v_cvt_pk_bf16_f32 v40, v204, v205
	v_cvt_pk_bf16_f32 v41, v212, v213
	v_cvt_pk_bf16_f32 v42, v206, v207
	v_cvt_pk_bf16_f32 v43, v214, v215
	global_store_dwordx4 v169, v[40:43], s[42:43]
	v_mul_f32_e32 v32, v205, v205
	v_mul_f32_e32 v33, v213, v213
	v_mul_f32_e32 v34, v207, v207
	v_mul_f32_e32 v35, v215, v215
	v_fmac_f32_e32 v32, v204, v204
	v_fmac_f32_e32 v33, v212, v212
	v_fmac_f32_e32 v34, v206, v206
	v_fmac_f32_e32 v35, v214, v214
	v_add_f32_e32 v32, v32, v33
	v_add_f32_e32 v32, v34, v32
	v_add_f32_e32 v32, v35, v32
	s_waitcnt vmcnt(15)
;     __device__ __forceinline__ void operator()(AccRef acc, const pg8::Unit& u, int wr, int wc, int fr, int fq) const {
;     ...
;             for (int m = 0; m < 4; ++m) {
;                 const int row = row0 + ai * 128 + m * 16; float ss = 0.f;
; #pragma unroll
;                 for (int bj = 0; bj < 2; ++bj) {
;                     bf16_t* xp = xb + (size_t)row * D + col0 + bj * 128;
;                     f32x4 a, b; unpack8(*(const u32x4*)xp, a, b);
;                     a += acc[ai][bj][m][0] * alpha; b += acc[ai][bj][m][1] * alpha;
;                     *(u32x4*)xp = pack8(a, b);
;                     ss += (a[0] * a[0] + a[1] * a[1]) + (a[2] * a[2] + a[3] * a[3]) + (b[0] * b[0] + b[1] * b[1]) + (b[2] * b[2] + b[3] * b[3]);
;                 }
;                 ss += __shfl_xor(ss, 16); ss += __shfl_xor(ss, 32);
;                 if (fq == 0) ssp[(size_t)row * 16 + u.pn * 4 + wc] = ss;
;             }
	v_pk_mul_f32 v[12:13], v[12:13], 0.5 op_sel_hi:[1,0]
	v_pk_mul_f32 v[14:15], v[14:15], 0.5 op_sel_hi:[1,0]
	v_pk_mul_f32 v[8:9], v[8:9], 0.5 op_sel_hi:[1,0]
	v_pk_mul_f32 v[10:11], v[10:11], 0.5 op_sel_hi:[1,0]
	v_lshlrev_b32_e32 v212, 16, v209
	v_and_b32_e32 v213, 0xffff0000, v209
	v_and_b32_e32 v209, 0xffff0000, v208
	v_lshlrev_b32_e32 v208, 16, v208
	v_lshlrev_b32_e32 v214, 16, v211
	v_and_b32_e32 v215, 0xffff0000, v211
	v_and_b32_e32 v211, 0xffff0000, v210
	v_lshlrev_b32_e32 v210, 16, v210
	v_pk_add_f32 v[208:209], v[12:13], v[208:209]
	v_pk_add_f32 v[212:213], v[14:15], v[212:213]
	v_pk_add_f32 v[210:211], v[8:9], v[210:211]
	v_pk_add_f32 v[214:215], v[10:11], v[214:215]
	v_cvt_pk_bf16_f32 v12, v208, v209
	v_cvt_pk_bf16_f32 v13, v212, v213
	v_cvt_pk_bf16_f32 v14, v210, v211
	v_cvt_pk_bf16_f32 v15, v214, v215
	global_store_dwordx4 v169, v[12:15], s[42:43] offset:256
	v_mul_f32_e32 v8, v209, v209
	v_mul_f32_e32 v9, v213, v213
	v_mul_f32_e32 v10, v211, v211
	v_mul_f32_e32 v11, v215, v215
	v_fmac_f32_e32 v8, v208, v208
	v_fmac_f32_e32 v9, v212, v212
	v_fmac_f32_e32 v10, v210, v210
	v_fmac_f32_e32 v11, v214, v214
	v_add_f32_e32 v8, v8, v9
	v_add_f32_e32 v8, v10, v8
	v_add_f32_e32 v8, v11, v8
	v_add_f32_e32 v32, v32, v8
	v_add_u32_e32 v169, 0x58000, v168
	s_waitcnt vmcnt(13)
	v_pk_mul_f32 v[24:25], v[24:25], 0.5 op_sel_hi:[1,0]
	v_pk_mul_f32 v[26:27], v[26:27], 0.5 op_sel_hi:[1,0]
	v_pk_mul_f32 v[16:17], v[16:17], 0.5 op_sel_hi:[1,0]
	v_pk_mul_f32 v[18:19], v[18:19], 0.5 op_sel_hi:[1,0]
	v_lshlrev_b32_e32 v212, 16, v231
	v_and_b32_e32 v213, 0xffff0000, v231
	v_and_b32_e32 v231, 0xffff0000, v230
	v_lshlrev_b32_e32 v230, 16, v230
	v_lshlrev_b32_e32 v214, 16, v233
	v_and_b32_e32 v215, 0xffff0000, v233
	v_and_b32_e32 v233, 0xffff0000, v232
	v_lshlrev_b32_e32 v232, 16, v232
	v_pk_add_f32 v[230:231], v[24:25], v[230:231]
	v_pk_add_f32 v[212:213], v[26:27], v[212:213]
	v_pk_add_f32 v[232:233], v[16:17], v[232:233]
	v_pk_add_f32 v[214:215], v[18:19], v[214:215]
	v_cvt_pk_bf16_f32 v24, v230, v231
	v_cvt_pk_bf16_f32 v25, v212, v213
	v_cvt_pk_bf16_f32 v26, v232, v233
	v_cvt_pk_bf16_f32 v27, v214, v215
	global_store_dwordx4 v169, v[24:27], s[42:43]
	v_mul_f32_e32 v16, v231, v231
	v_mul_f32_e32 v17, v213, v213
	v_mul_f32_e32 v18, v233, v233
	v_mul_f32_e32 v19, v215, v215
	v_fmac_f32_e32 v16, v230, v230
	v_fmac_f32_e32 v17, v212, v212
	v_fmac_f32_e32 v18, v232, v232
	v_fmac_f32_e32 v19, v214, v214
	v_add_f32_e32 v16, v16, v17
	v_add_f32_e32 v16, v18, v16
	v_add_f32_e32 v16, v19, v16
	s_waitcnt vmcnt(13)
	v_pk_mul_f32 v[4:5], v[4:5], 0.5 op_sel_hi:[1,0]
	v_pk_mul_f32 v[6:7], v[6:7], 0.5 op_sel_hi:[1,0]
	v_pk_mul_f32 v[0:1], v[0:1], 0.5 op_sel_hi:[1,0]
	v_pk_mul_f32 v[2:3], v[2:3], 0.5 op_sel_hi:[1,0]
	v_lshlrev_b32_e32 v212, 16, v235
	v_and_b32_e32 v213, 0xffff0000, v235
	v_and_b32_e32 v235, 0xffff0000, v234
	v_lshlrev_b32_e32 v234, 16, v234
	v_lshlrev_b32_e32 v214, 16, v237
	v_and_b32_e32 v215, 0xffff0000, v237
	v_and_b32_e32 v237, 0xffff0000, v236
	v_lshlrev_b32_e32 v236, 16, v236
	v_pk_add_f32 v[234:235], v[4:5], v[234:235]
	v_pk_add_f32 v[212:213], v[6:7], v[212:213]
	v_pk_add_f32 v[236:237], v[0:1], v[236:237]
	v_pk_add_f32 v[214:215], v[2:3], v[214:215]
	v_cvt_pk_bf16_f32 v4, v234, v235
	v_cvt_pk_bf16_f32 v5, v212, v213
	v_cvt_pk_bf16_f32 v6, v236, v237
	v_cvt_pk_bf16_f32 v7, v214, v215
	global_store_dwordx4 v169, v[4:7], s[42:43] offset:256
	v_mul_f32_e32 v0, v235, v235
	v_mul_f32_e32 v1, v213, v213
	v_mul_f32_e32 v2, v237, v237
	v_mul_f32_e32 v3, v215, v215
	v_fmac_f32_e32 v0, v234, v234
	v_fmac_f32_e32 v1, v212, v212
	v_fmac_f32_e32 v2, v236, v236
	v_fmac_f32_e32 v3, v214, v214
	v_add_f32_e32 v0, v0, v1
	v_add_f32_e32 v0, v2, v0
	v_add_f32_e32 v0, v3, v0
	v_add_f32_e32 v16, v16, v0
	ds_bpermute_b32 v121, v171, v120
	ds_bpermute_b32 v113, v171, v112
	ds_bpermute_b32 v97, v171, v96
	ds_bpermute_b32 v81, v171, v80
	ds_bpermute_b32 v57, v171, v56
	ds_bpermute_b32 v49, v171, v48
	ds_bpermute_b32 v33, v171, v32
	ds_bpermute_b32 v17, v171, v16
	s_waitcnt lgkmcnt(0)
	v_add_f32_e32 v120, v120, v121
	v_add_f32_e32 v112, v112, v113
	v_add_f32_e32 v96, v96, v97
	v_add_f32_e32 v80, v80, v81
	v_add_f32_e32 v56, v56, v57
	v_add_f32_e32 v48, v48, v49
	v_add_f32_e32 v32, v32, v33
	v_add_f32_e32 v16, v16, v17
	ds_bpermute_b32 v121, v172, v120
	ds_bpermute_b32 v113, v172, v112
	ds_bpermute_b32 v97, v172, v96
	ds_bpermute_b32 v81, v172, v80
	ds_bpermute_b32 v57, v172, v56
	ds_bpermute_b32 v49, v172, v48
	ds_bpermute_b32 v33, v172, v32
	ds_bpermute_b32 v17, v172, v16
	s_waitcnt lgkmcnt(0)
	v_add_f32_e32 v120, v120, v121
	v_add_f32_e32 v112, v112, v113
	v_add_f32_e32 v96, v96, v97
	v_add_f32_e32 v80, v80, v81
	v_add_f32_e32 v56, v56, v57
	v_add_f32_e32 v48, v48, v49
	v_add_f32_e32 v32, v32, v33
	v_add_f32_e32 v16, v16, v17
	s_and_saveexec_b64 s[34:35], s[2:3]
	global_store_dword v170, v120, s[46:47]
	global_store_dword v170, v112, s[46:47] offset:1024
	global_store_dword v170, v96, s[46:47] offset:2048
	global_store_dword v170, v80, s[46:47] offset:3072
	global_store_dword v173, v56, s[46:47]
	global_store_dword v173, v48, s[46:47] offset:1024
	global_store_dword v173, v32, s[46:47] offset:2048
	global_store_dword v173, v16, s[46:47] offset:3072
	s_or_b64 exec, exec, s[34:35]
	s_and_b64 vcc, exec, s[4:5]
	s_mov_b64 s[4:5], -1
